# combo32 with inverted K-loop wave priorities: staging half at priority 1, MFMA half at priority 0, mid-segment flip removed
# speedup vs baseline: 1.0147x; 1.0029x over previous
; #define PG8_STAGE(bufoff, gbase, voff) do { _Pragma("unroll") for (int _i = 0; _i < 2; ++_i) \
;         __builtin_amdgcn_global_load_lds((const unsigned*)((const char*)(gbase) + (voff)[_i]), (PG8_LAS unsigned*)(lds + (bufoff) + ldsw + _i * 8192), 16, 0, 0); } while (0)
; #define PG8_LDA(dst, b, h) do { _Pragma("unroll") for (int m = 0; m < 4; ++m) _Pragma("unroll") for (int k = 0; k < 2; ++k) dst[m][k] = *(const PG8_LAS bf16x8*)(lds + PG8_SA(b, h) + aoff + m * 2048 + k * 1024); } while (0)
; #define PG8_LDB(dst, b, h) do { _Pragma("unroll") for (int n = 0; n < 2; ++n) _Pragma("unroll") for (int k = 0; k < 2; ++k) dst[n][k] = *(const PG8_LAS bf16x8*)(lds + PG8_SB(b, h) + boff + n * 2048 + k * 1024); } while (0)
; #define PG8_MMA(ai, bj, At, Bt) do { __builtin_amdgcn_s_setprio(1); _Pragma("unroll") for (int m = 0; m < 4; ++m) _Pragma("unroll") for (int n = 0; n < 2; ++n) _Pragma("unroll") for (int k = 0; k < 2; ++k) \
;         acc[ai][bj][m][n] = __builtin_amdgcn_mfma_f32_16x16x32_bf16(Bt[n][k], At[m][k], acc[ai][bj][m][n], 0, 0, 0); __builtin_amdgcn_s_setprio(0); } while (0)
; #define PG8_WAIT_V(n) asm volatile("s_waitcnt vmcnt(" #n ")" ::: "memory")
; #define PG8_WAIT_L(n) asm volatile("s_waitcnt lgkmcnt(" #n ")" ::: "memory")
; #define PG8_BAR __builtin_amdgcn_s_barrier()
; #define PG8_SCHED __builtin_amdgcn_sched_barrier(0)
; template <class Epi, class Sched, bool ALIGN_EPI = false, bool SP2 = false>
; __device__ __forceinline__ void gemm_phase(PG8_LAS unsigned char* lds, const Gemm g, const Sched& S, const Epi& E, const int tid_arg) {
;     ...
;             PG8_LDB(B0, 0, 0); PG8_LDB(B1, 0, 1); PG8_SCHED; PG8_LDA(At, 0, 0); PG8_STAGE(PG8_SA(1, 1), a1 + hstep, voffA);
;             PG8_WAIT_V(8); PG8_WAIT_L(0); PG8_BAR; PG8_MMA(0, 0, At, B0); PG8_MMA(0, 1, At, B1); PG8_BAR; PG8_SCHED;
;             PG8_LDA(At, 0, 1); PG8_STAGE(PG8_SB(0, 0), b2, voffB); PG8_STAGE(PG8_SB(0, 1), b2 + hstep, voffB); PG8_STAGE(PG8_SA(0, 0), a2, voffA);
;             PG8_WAIT_V(8); PG8_WAIT_L(0); PG8_BAR; PG8_MMA(1, 0, At, B0); PG8_MMA(1, 1, At, B1); PG8_BAR; PG8_SCHED;
.LBB0_253:
	ds_read_b128 v[144:147], v166
	ds_read_b128 v[148:151], v167
	ds_read_b128 v[152:155], v168
	ds_read_b128 v[156:159], v169
	ds_read_b128 v[184:187], v170
	ds_read_b128 v[188:191], v171
	ds_read_b128 v[192:195], v172
	ds_read_b128 v[196:199], v173
	s_add_u32 s0, s8, 0xfffc0080
	s_addc_u32 s1, s9, -1
	s_cmp_eq_u32 s70, 12
	s_cselect_b32 s35, s23, s1
	s_cselect_b32 s34, s36, s0
	s_cselect_b32 s1, s21, s69
	s_cselect_b32 s0, s37, s68
	s_mov_b32 m0, s57
	v_lshl_add_u64 v[160:161], s[8:9], 0, v[138:139]
	ds_read_b128 v[200:203], v165
	ds_read_b128 v[204:207], v165 offset:1024
	ds_read_b128 v[208:211], v165 offset:2048
	ds_read_b128 v[212:215], v165 offset:3072
	ds_read_b128 v[216:219], v165 offset:4096
	ds_read_b128 v[220:223], v165 offset:5120
	ds_read_b128 v[224:227], v165 offset:6144
	ds_read_b128 v[228:231], v165 offset:7168
	global_load_lds_dwordx4 v[160:161], off
	v_lshl_add_u64 v[160:161], s[8:9], 0, v[136:137]
	s_mov_b32 m0, s58
	s_nop 0
	global_load_lds_dwordx4 v[160:161], off
	s_waitcnt vmcnt(8)
	s_waitcnt lgkmcnt(0)
	s_setprio 0
	s_barrier
	v_mfma_f32_16x16x32_bf16 v[124:127], v[144:147], v[200:203], v[124:127]
	v_mfma_f32_16x16x32_bf16 v[120:123], v[152:155], v[200:203], v[120:123]
	v_mfma_f32_16x16x32_bf16 v[108:111], v[144:147], v[208:211], v[108:111]
	v_mfma_f32_16x16x32_bf16 v[104:107], v[152:155], v[208:211], v[104:107]
	v_mfma_f32_16x16x32_bf16 v[92:95], v[144:147], v[216:219], v[92:95]
	v_mfma_f32_16x16x32_bf16 v[88:91], v[152:155], v[216:219], v[88:91]
	v_mfma_f32_16x16x32_bf16 v[76:79], v[144:147], v[224:227], v[76:79]
	v_mfma_f32_16x16x32_bf16 v[72:75], v[152:155], v[224:227], v[72:75]
	v_mfma_f32_16x16x32_bf16 v[124:127], v[148:151], v[204:207], v[124:127]
	v_mfma_f32_16x16x32_bf16 v[120:123], v[156:159], v[204:207], v[120:123]
	v_mfma_f32_16x16x32_bf16 v[108:111], v[148:151], v[212:215], v[108:111]
	v_mfma_f32_16x16x32_bf16 v[104:107], v[156:159], v[212:215], v[104:107]
	v_mfma_f32_16x16x32_bf16 v[92:95], v[148:151], v[220:223], v[92:95]
	v_mfma_f32_16x16x32_bf16 v[88:91], v[156:159], v[220:223], v[88:91]
	v_mfma_f32_16x16x32_bf16 v[76:79], v[148:151], v[228:231], v[76:79]
	v_mfma_f32_16x16x32_bf16 v[72:75], v[156:159], v[228:231], v[72:75]
	v_mfma_f32_16x16x32_bf16 v[116:119], v[184:187], v[200:203], v[116:119]
	v_mfma_f32_16x16x32_bf16 v[112:115], v[192:195], v[200:203], v[112:115]
	v_mfma_f32_16x16x32_bf16 v[100:103], v[184:187], v[208:211], v[100:103]
	v_mfma_f32_16x16x32_bf16 v[96:99], v[192:195], v[208:211], v[96:99]
	v_mfma_f32_16x16x32_bf16 v[84:87], v[184:187], v[216:219], v[84:87]
	v_mfma_f32_16x16x32_bf16 v[80:83], v[192:195], v[216:219], v[80:83]
	v_mfma_f32_16x16x32_bf16 v[68:71], v[184:187], v[224:227], v[68:71]
	v_mfma_f32_16x16x32_bf16 v[64:67], v[192:195], v[224:227], v[64:67]
	v_mfma_f32_16x16x32_bf16 v[116:119], v[188:191], v[204:207], v[116:119]
	v_mfma_f32_16x16x32_bf16 v[112:115], v[196:199], v[204:207], v[112:115]
	v_mfma_f32_16x16x32_bf16 v[100:103], v[188:191], v[212:215], v[100:103]
	v_mfma_f32_16x16x32_bf16 v[96:99], v[196:199], v[212:215], v[96:99]
	v_mfma_f32_16x16x32_bf16 v[84:87], v[188:191], v[220:223], v[84:87]
	v_mfma_f32_16x16x32_bf16 v[80:83], v[196:199], v[220:223], v[80:83]
	v_mfma_f32_16x16x32_bf16 v[68:71], v[188:191], v[228:231], v[68:71]
	v_mfma_f32_16x16x32_bf16 v[64:67], v[196:199], v[228:231], v[64:67]
	s_barrier
	s_setprio 1
	s_mov_b32 m0, s29
	v_lshl_add_u64 v[160:161], s[0:1], 0, v[130:131]
	s_add_u32 s72, s0, 0x40000
	ds_read_b128 v[200:203], v165 offset:16384
	ds_read_b128 v[204:207], v165 offset:17408
	ds_read_b128 v[208:211], v165 offset:18432
	ds_read_b128 v[212:215], v165 offset:19456
	ds_read_b128 v[216:219], v165 offset:20480
	ds_read_b128 v[220:223], v165 offset:21504
	ds_read_b128 v[224:227], v165 offset:22528
	ds_read_b128 v[228:231], v165 offset:23552
	global_load_lds_dwordx4 v[160:161], off
	v_lshl_add_u64 v[232:233], s[0:1], 0, v[134:135]
	s_mov_b32 m0, s31
	s_addc_u32 s73, s1, 0
	global_load_lds_dwordx4 v[232:233], off
	v_lshl_add_u64 v[234:235], s[72:73], 0, v[130:131]
	s_mov_b32 m0, s40
	v_lshl_add_u64 v[236:237], s[34:35], 0, v[132:133]
	global_load_lds_dwordx4 v[234:235], off
	v_lshl_add_u64 v[234:235], s[72:73], 0, v[134:135]
	s_mov_b32 m0, s41
	s_nop 0
	global_load_lds_dwordx4 v[234:235], off
	v_lshl_add_u64 v[234:235], s[34:35], 0, v[128:129]
	s_mov_b32 m0, s39
	s_nop 0
	global_load_lds_dwordx4 v[234:235], off
	s_mov_b32 m0, s42
	s_nop 0
	global_load_lds_dwordx4 v[236:237], off
	s_waitcnt vmcnt(8)
	s_waitcnt lgkmcnt(0)
	s_setprio 0
	s_barrier
	v_mfma_f32_16x16x32_bf16 v[60:63], v[144:147], v[200:203], v[60:63]
	v_mfma_f32_16x16x32_bf16 v[56:59], v[152:155], v[200:203], v[56:59]
	v_mfma_f32_16x16x32_bf16 v[44:47], v[144:147], v[208:211], v[44:47]
	v_mfma_f32_16x16x32_bf16 v[40:43], v[152:155], v[208:211], v[40:43]
	v_mfma_f32_16x16x32_bf16 v[28:31], v[144:147], v[216:219], v[28:31]
	v_mfma_f32_16x16x32_bf16 v[24:27], v[152:155], v[216:219], v[24:27]
	v_mfma_f32_16x16x32_bf16 v[12:15], v[144:147], v[224:227], v[12:15]
	v_mfma_f32_16x16x32_bf16 v[8:11], v[152:155], v[224:227], v[8:11]
	v_mfma_f32_16x16x32_bf16 v[60:63], v[148:151], v[204:207], v[60:63]
	v_mfma_f32_16x16x32_bf16 v[56:59], v[156:159], v[204:207], v[56:59]
	v_mfma_f32_16x16x32_bf16 v[44:47], v[148:151], v[212:215], v[44:47]
	v_mfma_f32_16x16x32_bf16 v[40:43], v[156:159], v[212:215], v[40:43]
	v_mfma_f32_16x16x32_bf16 v[28:31], v[148:151], v[220:223], v[28:31]
	v_mfma_f32_16x16x32_bf16 v[24:27], v[156:159], v[220:223], v[24:27]
	v_mfma_f32_16x16x32_bf16 v[12:15], v[148:151], v[228:231], v[12:15]
	v_mfma_f32_16x16x32_bf16 v[8:11], v[156:159], v[228:231], v[8:11]
	v_mfma_f32_16x16x32_bf16 v[52:55], v[184:187], v[200:203], v[52:55]
	v_mfma_f32_16x16x32_bf16 v[48:51], v[192:195], v[200:203], v[48:51]
	v_mfma_f32_16x16x32_bf16 v[36:39], v[184:187], v[208:211], v[36:39]
	v_mfma_f32_16x16x32_bf16 v[32:35], v[192:195], v[208:211], v[32:35]
	v_mfma_f32_16x16x32_bf16 v[20:23], v[184:187], v[216:219], v[20:23]
	v_mfma_f32_16x16x32_bf16 v[16:19], v[192:195], v[216:219], v[16:19]
	v_mfma_f32_16x16x32_bf16 v[4:7], v[184:187], v[224:227], v[4:7]
	v_mfma_f32_16x16x32_bf16 v[0:3], v[192:195], v[224:227], v[0:3]
	v_mfma_f32_16x16x32_bf16 v[52:55], v[188:191], v[204:207], v[52:55]
	v_mfma_f32_16x16x32_bf16 v[48:51], v[196:199], v[204:207], v[48:51]
	v_mfma_f32_16x16x32_bf16 v[36:39], v[188:191], v[212:215], v[36:39]
	v_mfma_f32_16x16x32_bf16 v[32:35], v[196:199], v[212:215], v[32:35]
	v_mfma_f32_16x16x32_bf16 v[20:23], v[188:191], v[220:223], v[20:23]
	v_mfma_f32_16x16x32_bf16 v[16:19], v[196:199], v[220:223], v[16:19]
	v_mfma_f32_16x16x32_bf16 v[4:7], v[188:191], v[228:231], v[4:7]
	v_mfma_f32_16x16x32_bf16 v[0:3], v[196:199], v[228:231], v[0:3]
	s_barrier
; #define PG8_STAGE(bufoff, gbase, voff) do { _Pragma("unroll") for (int _i = 0; _i < 2; ++_i) \
;         __builtin_amdgcn_global_load_lds((const unsigned*)((const char*)(gbase) + (voff)[_i]), (PG8_LAS unsigned*)(lds + (bufoff) + ldsw + _i * 8192), 16, 0, 0); } while (0)
; #define PG8_LDA(dst, b, h) do { _Pragma("unroll") for (int m = 0; m < 4; ++m) _Pragma("unroll") for (int k = 0; k < 2; ++k) dst[m][k] = *(const PG8_LAS bf16x8*)(lds + PG8_SA(b, h) + aoff + m * 2048 + k * 1024); } while (0)
; #define PG8_LDB(dst, b, h) do { _Pragma("unroll") for (int n = 0; n < 2; ++n) _Pragma("unroll") for (int k = 0; k < 2; ++k) dst[n][k] = *(const PG8_LAS bf16x8*)(lds + PG8_SB(b, h) + boff + n * 2048 + k * 1024); } while (0)
; #define PG8_MMA(ai, bj, At, Bt) do { __builtin_amdgcn_s_setprio(1); _Pragma("unroll") for (int m = 0; m < 4; ++m) _Pragma("unroll") for (int n = 0; n < 2; ++n) _Pragma("unroll") for (int k = 0; k < 2; ++k) \
;         acc[ai][bj][m][n] = __builtin_amdgcn_mfma_f32_16x16x32_bf16(Bt[n][k], At[m][k], acc[ai][bj][m][n], 0, 0, 0); __builtin_amdgcn_s_setprio(0); } while (0)
; #define PG8_WAIT_V(n) asm volatile("s_waitcnt vmcnt(" #n ")" ::: "memory")
; #define PG8_WAIT_L(n) asm volatile("s_waitcnt lgkmcnt(" #n ")" ::: "memory")
; #define PG8_BAR __builtin_amdgcn_s_barrier()
; #define PG8_SCHED __builtin_amdgcn_sched_barrier(0)
; template <class Epi, class Sched, bool ALIGN_EPI = false, bool SP2 = false>
; __device__ __forceinline__ void gemm_phase(PG8_LAS unsigned char* lds, const Gemm g, const Sched& S, const Epi& E, const int tid_arg) {
;     ...
;             PG8_LDB(B0, 1, 0); PG8_LDB(B1, 1, 1); PG8_SCHED; PG8_LDA(At, 1, 0); PG8_STAGE(PG8_SA(0, 1), a2 + hstep, voffA);
;             PG8_WAIT_V(8); PG8_WAIT_L(0); PG8_BAR; PG8_MMA(0, 0, At, B0); PG8_MMA(0, 1, At, B1); PG8_BAR; PG8_SCHED;
;             PG8_LDA(At, 1, 1); PG8_STAGE(PG8_SB(1, 0), b3, voffB); PG8_STAGE(PG8_SB(1, 1), b3 + hstep, voffB); PG8_STAGE(PG8_SA(1, 0), a3, voffA);
;             PG8_WAIT_V(8); PG8_WAIT_L(0); PG8_BAR; PG8_MMA(1, 0, At, B0); PG8_MMA(1, 1, At, B1); PG8_BAR; PG8_SCHED;
	s_setprio 1
	ds_read_b128 v[144:147], v174
	ds_read_b128 v[148:151], v175
	ds_read_b128 v[152:155], v176
	ds_read_b128 v[156:159], v177
	ds_read_b128 v[184:187], v178
	ds_read_b128 v[188:191], v179
	ds_read_b128 v[192:195], v180
	ds_read_b128 v[196:199], v181
	s_add_u32 s34, s34, 0x40000
	s_addc_u32 s35, s35, 0
	s_mov_b32 m0, s43
	v_lshl_add_u64 v[238:239], s[34:35], 0, v[128:129]
	ds_read_b128 v[200:203], v165 offset:32768
	ds_read_b128 v[204:207], v165 offset:33792
	ds_read_b128 v[208:211], v165 offset:34816
	ds_read_b128 v[212:215], v165 offset:35840
	ds_read_b128 v[216:219], v165 offset:36864
	ds_read_b128 v[220:223], v165 offset:37888
	ds_read_b128 v[224:227], v165 offset:38912
	ds_read_b128 v[228:231], v165 offset:39936
	global_load_lds_dwordx4 v[238:239], off
	v_lshl_add_u64 v[238:239], s[34:35], 0, v[132:133]
	s_mov_b32 m0, s44
	s_nop 0
	global_load_lds_dwordx4 v[238:239], off
	s_waitcnt vmcnt(8)
	s_waitcnt lgkmcnt(0)
	s_setprio 0
	s_barrier
	v_mfma_f32_16x16x32_bf16 v[124:127], v[144:147], v[200:203], v[124:127]
	v_mfma_f32_16x16x32_bf16 v[120:123], v[152:155], v[200:203], v[120:123]
	v_mfma_f32_16x16x32_bf16 v[108:111], v[144:147], v[208:211], v[108:111]
	v_mfma_f32_16x16x32_bf16 v[104:107], v[152:155], v[208:211], v[104:107]
	v_mfma_f32_16x16x32_bf16 v[92:95], v[144:147], v[216:219], v[92:95]
	v_mfma_f32_16x16x32_bf16 v[88:91], v[152:155], v[216:219], v[88:91]
	v_mfma_f32_16x16x32_bf16 v[76:79], v[144:147], v[224:227], v[76:79]
	v_mfma_f32_16x16x32_bf16 v[72:75], v[152:155], v[224:227], v[72:75]
	v_mfma_f32_16x16x32_bf16 v[124:127], v[148:151], v[204:207], v[124:127]
	v_mfma_f32_16x16x32_bf16 v[120:123], v[156:159], v[204:207], v[120:123]
	v_mfma_f32_16x16x32_bf16 v[108:111], v[148:151], v[212:215], v[108:111]
	v_mfma_f32_16x16x32_bf16 v[104:107], v[156:159], v[212:215], v[104:107]
	v_mfma_f32_16x16x32_bf16 v[92:95], v[148:151], v[220:223], v[92:95]
	v_mfma_f32_16x16x32_bf16 v[88:91], v[156:159], v[220:223], v[88:91]
	v_mfma_f32_16x16x32_bf16 v[76:79], v[148:151], v[228:231], v[76:79]
	v_mfma_f32_16x16x32_bf16 v[72:75], v[156:159], v[228:231], v[72:75]
	v_mfma_f32_16x16x32_bf16 v[116:119], v[184:187], v[200:203], v[116:119]
	v_mfma_f32_16x16x32_bf16 v[112:115], v[192:195], v[200:203], v[112:115]
	v_mfma_f32_16x16x32_bf16 v[100:103], v[184:187], v[208:211], v[100:103]
	v_mfma_f32_16x16x32_bf16 v[96:99], v[192:195], v[208:211], v[96:99]
	v_mfma_f32_16x16x32_bf16 v[84:87], v[184:187], v[216:219], v[84:87]
	v_mfma_f32_16x16x32_bf16 v[80:83], v[192:195], v[216:219], v[80:83]
	v_mfma_f32_16x16x32_bf16 v[68:71], v[184:187], v[224:227], v[68:71]
	v_mfma_f32_16x16x32_bf16 v[64:67], v[192:195], v[224:227], v[64:67]
	v_mfma_f32_16x16x32_bf16 v[116:119], v[188:191], v[204:207], v[116:119]
	v_mfma_f32_16x16x32_bf16 v[112:115], v[196:199], v[204:207], v[112:115]
	v_mfma_f32_16x16x32_bf16 v[100:103], v[188:191], v[212:215], v[100:103]
	v_mfma_f32_16x16x32_bf16 v[96:99], v[196:199], v[212:215], v[96:99]
	v_mfma_f32_16x16x32_bf16 v[84:87], v[188:191], v[220:223], v[84:87]
	v_mfma_f32_16x16x32_bf16 v[80:83], v[196:199], v[220:223], v[80:83]
	v_mfma_f32_16x16x32_bf16 v[68:71], v[188:191], v[228:231], v[68:71]
	v_mfma_f32_16x16x32_bf16 v[64:67], v[196:199], v[228:231], v[64:67]
	s_barrier
	s_setprio 1
	s_mov_b32 m0, s47
	v_lshl_add_u64 v[160:161], v[160:161], 0, s[14:15]
	s_add_u32 s0, s0, 0x40080
	ds_read_b128 v[200:203], v165 offset:49152
	ds_read_b128 v[204:207], v165 offset:50176
	ds_read_b128 v[208:211], v165 offset:51200
	ds_read_b128 v[212:215], v165 offset:52224
	ds_read_b128 v[216:219], v165 offset:53248
	ds_read_b128 v[220:223], v165 offset:54272
	ds_read_b128 v[224:227], v165 offset:55296
	ds_read_b128 v[228:231], v165 offset:56320
	global_load_lds_dwordx4 v[160:161], off
	v_lshl_add_u64 v[160:161], v[232:233], 0, s[14:15]
	s_mov_b32 m0, s48
	s_addc_u32 s1, s1, 0
	global_load_lds_dwordx4 v[160:161], off
	v_lshl_add_u64 v[160:161], s[0:1], 0, v[130:131]
	s_mov_b32 m0, s51
	s_nop 0
	global_load_lds_dwordx4 v[160:161], off
	v_lshl_add_u64 v[160:161], s[0:1], 0, v[134:135]
	s_mov_b32 m0, s52
	s_nop 0
	global_load_lds_dwordx4 v[160:161], off
	v_lshl_add_u64 v[160:161], v[234:235], 0, s[14:15]
	s_mov_b32 m0, s49
	s_nop 0
	global_load_lds_dwordx4 v[160:161], off
	v_lshl_add_u64 v[160:161], v[236:237], 0, s[14:15]
	s_mov_b32 m0, s50
	s_nop 0
	global_load_lds_dwordx4 v[160:161], off
	s_waitcnt vmcnt(8)
	s_waitcnt lgkmcnt(0)
	s_setprio 0
	s_barrier
	v_mfma_f32_16x16x32_bf16 v[60:63], v[144:147], v[200:203], v[60:63]
	v_mfma_f32_16x16x32_bf16 v[56:59], v[152:155], v[200:203], v[56:59]
	v_mfma_f32_16x16x32_bf16 v[44:47], v[144:147], v[208:211], v[44:47]
	v_mfma_f32_16x16x32_bf16 v[40:43], v[152:155], v[208:211], v[40:43]
	v_mfma_f32_16x16x32_bf16 v[28:31], v[144:147], v[216:219], v[28:31]
	v_mfma_f32_16x16x32_bf16 v[24:27], v[152:155], v[216:219], v[24:27]
	v_mfma_f32_16x16x32_bf16 v[12:15], v[144:147], v[224:227], v[12:15]
	v_mfma_f32_16x16x32_bf16 v[8:11], v[152:155], v[224:227], v[8:11]
	v_mfma_f32_16x16x32_bf16 v[60:63], v[148:151], v[204:207], v[60:63]
	v_mfma_f32_16x16x32_bf16 v[56:59], v[156:159], v[204:207], v[56:59]
	v_mfma_f32_16x16x32_bf16 v[44:47], v[148:151], v[212:215], v[44:47]
	v_mfma_f32_16x16x32_bf16 v[40:43], v[156:159], v[212:215], v[40:43]
	v_mfma_f32_16x16x32_bf16 v[28:31], v[148:151], v[220:223], v[28:31]
	v_mfma_f32_16x16x32_bf16 v[24:27], v[156:159], v[220:223], v[24:27]
	v_mfma_f32_16x16x32_bf16 v[12:15], v[148:151], v[228:231], v[12:15]
	v_mfma_f32_16x16x32_bf16 v[8:11], v[156:159], v[228:231], v[8:11]
	v_mfma_f32_16x16x32_bf16 v[52:55], v[184:187], v[200:203], v[52:55]
	v_mfma_f32_16x16x32_bf16 v[48:51], v[192:195], v[200:203], v[48:51]
	v_mfma_f32_16x16x32_bf16 v[36:39], v[184:187], v[208:211], v[36:39]
	v_mfma_f32_16x16x32_bf16 v[32:35], v[192:195], v[208:211], v[32:35]
	v_mfma_f32_16x16x32_bf16 v[20:23], v[184:187], v[216:219], v[20:23]
	v_mfma_f32_16x16x32_bf16 v[16:19], v[192:195], v[216:219], v[16:19]
	v_mfma_f32_16x16x32_bf16 v[4:7], v[184:187], v[224:227], v[4:7]
	v_mfma_f32_16x16x32_bf16 v[0:3], v[192:195], v[224:227], v[0:3]
	v_mfma_f32_16x16x32_bf16 v[52:55], v[188:191], v[204:207], v[52:55]
	v_mfma_f32_16x16x32_bf16 v[48:51], v[196:199], v[204:207], v[48:51]
	v_mfma_f32_16x16x32_bf16 v[36:39], v[188:191], v[212:215], v[36:39]
	v_mfma_f32_16x16x32_bf16 v[32:35], v[196:199], v[212:215], v[32:35]
	v_mfma_f32_16x16x32_bf16 v[20:23], v[188:191], v[220:223], v[20:23]
	v_mfma_f32_16x16x32_bf16 v[16:19], v[196:199], v[220:223], v[16:19]
	v_mfma_f32_16x16x32_bf16 v[4:7], v[188:191], v[228:231], v[4:7]
	v_mfma_f32_16x16x32_bf16 v[0:3], v[196:199], v[228:231], v[0:3]
	s_barrier
	s_setprio 1
	s_add_i32 s70, s70, 2
	s_add_u32 s68, s68, 0x100
	s_addc_u32 s69, s69, 0
	s_add_u32 s8, s8, 0x100
	s_addc_u32 s9, s9, 0
	s_cmp_gt_u32 s70, 13
	s_cbranch_scc0 .LBB0_253
	s_setprio 0
	s_and_b64 vcc, exec, s[16:17]
	s_cbranch_vccz .LBB0_256
	s_barrier

; #define PG8_STAGE(bufoff, gbase, voff) do { _Pragma("unroll") for (int _i = 0; _i < 2; ++_i) \
;         __builtin_amdgcn_global_load_lds((const unsigned*)((const char*)(gbase) + (voff)[_i]), (PG8_LAS unsigned*)(lds + (bufoff) + ldsw + _i * 8192), 16, 0, 0); } while (0)
; #define PG8_LDA(dst, b, h) do { _Pragma("unroll") for (int m = 0; m < 4; ++m) _Pragma("unroll") for (int k = 0; k < 2; ++k) dst[m][k] = *(const PG8_LAS bf16x8*)(lds + PG8_SA(b, h) + aoff + m * 2048 + k * 1024); } while (0)
; #define PG8_LDB(dst, b, h) do { _Pragma("unroll") for (int n = 0; n < 2; ++n) _Pragma("unroll") for (int k = 0; k < 2; ++k) dst[n][k] = *(const PG8_LAS bf16x8*)(lds + PG8_SB(b, h) + boff + n * 2048 + k * 1024); } while (0)
; #define PG8_MMA(ai, bj, At, Bt) do { __builtin_amdgcn_s_setprio(1); _Pragma("unroll") for (int m = 0; m < 4; ++m) _Pragma("unroll") for (int n = 0; n < 2; ++n) _Pragma("unroll") for (int k = 0; k < 2; ++k) \
;         acc[ai][bj][m][n] = __builtin_amdgcn_mfma_f32_16x16x32_bf16(Bt[n][k], At[m][k], acc[ai][bj][m][n], 0, 0, 0); __builtin_amdgcn_s_setprio(0); } while (0)
; #define PG8_WAIT_V(n) asm volatile("s_waitcnt vmcnt(" #n ")" ::: "memory")
; #define PG8_WAIT_L(n) asm volatile("s_waitcnt lgkmcnt(" #n ")" ::: "memory")
; #define PG8_BAR __builtin_amdgcn_s_barrier()
; #define PG8_SCHED __builtin_amdgcn_sched_barrier(0)
; template <class Epi, class Sched, bool ALIGN_EPI = false, bool SP2 = false>
; __device__ __forceinline__ void gemm_phase(PG8_LAS unsigned char* lds, const Gemm g, const Sched& S, const Epi& E, const int tid_arg) {
;     ...
;             PG8_LDB(B0, 0, 0); PG8_LDB(B1, 0, 1); PG8_SCHED; PG8_LDA(At, 0, 0); PG8_STAGE(PG8_SA(1, 1), a1 + hstep, voffA);
;             PG8_WAIT_V(8); PG8_WAIT_L(0); PG8_BAR; PG8_MMA(0, 0, At, B0); PG8_MMA(0, 1, At, B1); PG8_BAR; PG8_SCHED;
;             PG8_LDA(At, 0, 1); PG8_STAGE(PG8_SB(0, 0), b2, voffB); PG8_STAGE(PG8_SB(0, 1), b2 + hstep, voffB); PG8_STAGE(PG8_SA(0, 0), a2, voffA);
;             PG8_WAIT_V(8); PG8_WAIT_L(0); PG8_BAR; PG8_MMA(1, 0, At, B0); PG8_MMA(1, 1, At, B1); PG8_BAR; PG8_SCHED;
.LBB0_533:
	ds_read_b128 v[128:131], v165
	ds_read_b128 v[132:135], v166
	ds_read_b128 v[152:155], v167
	ds_read_b128 v[156:159], v168
	ds_read_b128 v[182:185], v169
	ds_read_b128 v[186:189], v170
	ds_read_b128 v[190:193], v171
	ds_read_b128 v[194:197], v172
	s_add_u32 s0, s12, 0xfffc0080
	s_addc_u32 s1, s13, -1
	s_cmp_eq_u32 s65, 12
	s_cselect_b32 s37, s11, s1
	s_cselect_b32 s36, s29, s0
	s_cselect_b32 s1, s27, s64
	s_cselect_b32 s0, s62, s63
	s_mov_b32 m0, s59
	v_lshl_add_u64 v[160:161], s[12:13], 0, v[146:147]
	ds_read_b128 v[198:201], v164
	ds_read_b128 v[202:205], v164 offset:1024
	ds_read_b128 v[206:209], v164 offset:2048
	ds_read_b128 v[210:213], v164 offset:3072
	ds_read_b128 v[214:217], v164 offset:4096
	ds_read_b128 v[218:221], v164 offset:5120
	ds_read_b128 v[222:225], v164 offset:6144
	ds_read_b128 v[226:229], v164 offset:7168
	global_load_lds_dwordx4 v[160:161], off
	v_lshl_add_u64 v[160:161], s[12:13], 0, v[144:145]
	s_mov_b32 m0, s60
	s_nop 0
	global_load_lds_dwordx4 v[160:161], off
	s_waitcnt vmcnt(8)
	s_waitcnt lgkmcnt(0)
	s_setprio 0
	s_barrier
	v_mfma_f32_16x16x32_bf16 v[124:127], v[128:131], v[198:201], v[124:127]
	v_mfma_f32_16x16x32_bf16 v[120:123], v[152:155], v[198:201], v[120:123]
	v_mfma_f32_16x16x32_bf16 v[108:111], v[128:131], v[206:209], v[108:111]
	v_mfma_f32_16x16x32_bf16 v[104:107], v[152:155], v[206:209], v[104:107]
	v_mfma_f32_16x16x32_bf16 v[92:95], v[128:131], v[214:217], v[92:95]
	v_mfma_f32_16x16x32_bf16 v[88:91], v[152:155], v[214:217], v[88:91]
	v_mfma_f32_16x16x32_bf16 v[76:79], v[128:131], v[222:225], v[76:79]
	v_mfma_f32_16x16x32_bf16 v[72:75], v[152:155], v[222:225], v[72:75]
	v_mfma_f32_16x16x32_bf16 v[124:127], v[132:135], v[202:205], v[124:127]
	v_mfma_f32_16x16x32_bf16 v[120:123], v[156:159], v[202:205], v[120:123]
	v_mfma_f32_16x16x32_bf16 v[108:111], v[132:135], v[210:213], v[108:111]
	v_mfma_f32_16x16x32_bf16 v[104:107], v[156:159], v[210:213], v[104:107]
	v_mfma_f32_16x16x32_bf16 v[92:95], v[132:135], v[218:221], v[92:95]
	v_mfma_f32_16x16x32_bf16 v[88:91], v[156:159], v[218:221], v[88:91]
	v_mfma_f32_16x16x32_bf16 v[76:79], v[132:135], v[226:229], v[76:79]
	v_mfma_f32_16x16x32_bf16 v[72:75], v[156:159], v[226:229], v[72:75]
	v_mfma_f32_16x16x32_bf16 v[116:119], v[182:185], v[198:201], v[116:119]
	v_mfma_f32_16x16x32_bf16 v[112:115], v[190:193], v[198:201], v[112:115]
	v_mfma_f32_16x16x32_bf16 v[100:103], v[182:185], v[206:209], v[100:103]
	v_mfma_f32_16x16x32_bf16 v[96:99], v[190:193], v[206:209], v[96:99]
	v_mfma_f32_16x16x32_bf16 v[84:87], v[182:185], v[214:217], v[84:87]
	v_mfma_f32_16x16x32_bf16 v[80:83], v[190:193], v[214:217], v[80:83]
	v_mfma_f32_16x16x32_bf16 v[68:71], v[182:185], v[222:225], v[68:71]
	v_mfma_f32_16x16x32_bf16 v[64:67], v[190:193], v[222:225], v[64:67]
	v_mfma_f32_16x16x32_bf16 v[116:119], v[186:189], v[202:205], v[116:119]
	v_mfma_f32_16x16x32_bf16 v[112:115], v[194:197], v[202:205], v[112:115]
	v_mfma_f32_16x16x32_bf16 v[100:103], v[186:189], v[210:213], v[100:103]
	v_mfma_f32_16x16x32_bf16 v[96:99], v[194:197], v[210:213], v[96:99]
	v_mfma_f32_16x16x32_bf16 v[84:87], v[186:189], v[218:221], v[84:87]
	v_mfma_f32_16x16x32_bf16 v[80:83], v[194:197], v[218:221], v[80:83]
	v_mfma_f32_16x16x32_bf16 v[68:71], v[186:189], v[226:229], v[68:71]
	v_mfma_f32_16x16x32_bf16 v[64:67], v[194:197], v[226:229], v[64:67]
	s_barrier
	s_setprio 1
	s_mov_b32 m0, s5
	v_lshl_add_u64 v[160:161], s[0:1], 0, v[138:139]
	s_add_u32 s66, s0, 0x40000
	ds_read_b128 v[198:201], v164 offset:16384
	ds_read_b128 v[202:205], v164 offset:17408
	ds_read_b128 v[206:209], v164 offset:18432
	ds_read_b128 v[210:213], v164 offset:19456
	ds_read_b128 v[214:217], v164 offset:20480
	ds_read_b128 v[218:221], v164 offset:21504
	ds_read_b128 v[222:225], v164 offset:22528
	ds_read_b128 v[226:229], v164 offset:23552
	global_load_lds_dwordx4 v[160:161], off
	v_lshl_add_u64 v[230:231], s[0:1], 0, v[142:143]
	s_mov_b32 m0, s40
	s_addc_u32 s67, s1, 0
	global_load_lds_dwordx4 v[230:231], off
	v_lshl_add_u64 v[232:233], s[66:67], 0, v[138:139]
	s_mov_b32 m0, s41
	v_lshl_add_u64 v[234:235], s[36:37], 0, v[140:141]
	global_load_lds_dwordx4 v[232:233], off
	v_lshl_add_u64 v[232:233], s[66:67], 0, v[142:143]
	s_mov_b32 m0, s42
	s_nop 0
	global_load_lds_dwordx4 v[232:233], off
	v_lshl_add_u64 v[232:233], s[36:37], 0, v[136:137]
	s_mov_b32 m0, s39
	s_nop 0
	global_load_lds_dwordx4 v[232:233], off
	s_mov_b32 m0, s43
	s_nop 0
	global_load_lds_dwordx4 v[234:235], off
	s_waitcnt vmcnt(8)
	s_waitcnt lgkmcnt(0)
	s_setprio 0
	s_barrier
	v_mfma_f32_16x16x32_bf16 v[60:63], v[128:131], v[198:201], v[60:63]
	v_mfma_f32_16x16x32_bf16 v[56:59], v[152:155], v[198:201], v[56:59]
	v_mfma_f32_16x16x32_bf16 v[44:47], v[128:131], v[206:209], v[44:47]
	v_mfma_f32_16x16x32_bf16 v[40:43], v[152:155], v[206:209], v[40:43]
	v_mfma_f32_16x16x32_bf16 v[28:31], v[128:131], v[214:217], v[28:31]
	v_mfma_f32_16x16x32_bf16 v[24:27], v[152:155], v[214:217], v[24:27]
	v_mfma_f32_16x16x32_bf16 v[12:15], v[128:131], v[222:225], v[12:15]
	v_mfma_f32_16x16x32_bf16 v[8:11], v[152:155], v[222:225], v[8:11]
	v_mfma_f32_16x16x32_bf16 v[60:63], v[132:135], v[202:205], v[60:63]
	v_mfma_f32_16x16x32_bf16 v[56:59], v[156:159], v[202:205], v[56:59]
	v_mfma_f32_16x16x32_bf16 v[44:47], v[132:135], v[210:213], v[44:47]
	v_mfma_f32_16x16x32_bf16 v[40:43], v[156:159], v[210:213], v[40:43]
	v_mfma_f32_16x16x32_bf16 v[28:31], v[132:135], v[218:221], v[28:31]
	v_mfma_f32_16x16x32_bf16 v[24:27], v[156:159], v[218:221], v[24:27]
	v_mfma_f32_16x16x32_bf16 v[12:15], v[132:135], v[226:229], v[12:15]
	v_mfma_f32_16x16x32_bf16 v[8:11], v[156:159], v[226:229], v[8:11]
	v_mfma_f32_16x16x32_bf16 v[52:55], v[182:185], v[198:201], v[52:55]
	v_mfma_f32_16x16x32_bf16 v[48:51], v[190:193], v[198:201], v[48:51]
	v_mfma_f32_16x16x32_bf16 v[36:39], v[182:185], v[206:209], v[36:39]
	v_mfma_f32_16x16x32_bf16 v[32:35], v[190:193], v[206:209], v[32:35]
	v_mfma_f32_16x16x32_bf16 v[20:23], v[182:185], v[214:217], v[20:23]
	v_mfma_f32_16x16x32_bf16 v[16:19], v[190:193], v[214:217], v[16:19]
	v_mfma_f32_16x16x32_bf16 v[4:7], v[182:185], v[222:225], v[4:7]
	v_mfma_f32_16x16x32_bf16 v[0:3], v[190:193], v[222:225], v[0:3]
	v_mfma_f32_16x16x32_bf16 v[52:55], v[186:189], v[202:205], v[52:55]
	v_mfma_f32_16x16x32_bf16 v[48:51], v[194:197], v[202:205], v[48:51]
	v_mfma_f32_16x16x32_bf16 v[36:39], v[186:189], v[210:213], v[36:39]
	v_mfma_f32_16x16x32_bf16 v[32:35], v[194:197], v[210:213], v[32:35]
	v_mfma_f32_16x16x32_bf16 v[20:23], v[186:189], v[218:221], v[20:23]
	v_mfma_f32_16x16x32_bf16 v[16:19], v[194:197], v[218:221], v[16:19]
	v_mfma_f32_16x16x32_bf16 v[4:7], v[186:189], v[226:229], v[4:7]
	v_mfma_f32_16x16x32_bf16 v[0:3], v[194:197], v[226:229], v[0:3]
	s_barrier
; #define PG8_STAGE(bufoff, gbase, voff) do { _Pragma("unroll") for (int _i = 0; _i < 2; ++_i) \
;         __builtin_amdgcn_global_load_lds((const unsigned*)((const char*)(gbase) + (voff)[_i]), (PG8_LAS unsigned*)(lds + (bufoff) + ldsw + _i * 8192), 16, 0, 0); } while (0)
; #define PG8_LDA(dst, b, h) do { _Pragma("unroll") for (int m = 0; m < 4; ++m) _Pragma("unroll") for (int k = 0; k < 2; ++k) dst[m][k] = *(const PG8_LAS bf16x8*)(lds + PG8_SA(b, h) + aoff + m * 2048 + k * 1024); } while (0)
; #define PG8_LDB(dst, b, h) do { _Pragma("unroll") for (int n = 0; n < 2; ++n) _Pragma("unroll") for (int k = 0; k < 2; ++k) dst[n][k] = *(const PG8_LAS bf16x8*)(lds + PG8_SB(b, h) + boff + n * 2048 + k * 1024); } while (0)
; #define PG8_MMA(ai, bj, At, Bt) do { __builtin_amdgcn_s_setprio(1); _Pragma("unroll") for (int m = 0; m < 4; ++m) _Pragma("unroll") for (int n = 0; n < 2; ++n) _Pragma("unroll") for (int k = 0; k < 2; ++k) \
;         acc[ai][bj][m][n] = __builtin_amdgcn_mfma_f32_16x16x32_bf16(Bt[n][k], At[m][k], acc[ai][bj][m][n], 0, 0, 0); __builtin_amdgcn_s_setprio(0); } while (0)
; #define PG8_WAIT_V(n) asm volatile("s_waitcnt vmcnt(" #n ")" ::: "memory")
; #define PG8_WAIT_L(n) asm volatile("s_waitcnt lgkmcnt(" #n ")" ::: "memory")
; #define PG8_BAR __builtin_amdgcn_s_barrier()
; #define PG8_SCHED __builtin_amdgcn_sched_barrier(0)
; template <class Epi, class Sched, bool ALIGN_EPI = false, bool SP2 = false>
; __device__ __forceinline__ void gemm_phase(PG8_LAS unsigned char* lds, const Gemm g, const Sched& S, const Epi& E, const int tid_arg) {
;     ...
;             PG8_LDB(B0, 1, 0); PG8_LDB(B1, 1, 1); PG8_SCHED; PG8_LDA(At, 1, 0); PG8_STAGE(PG8_SA(0, 1), a2 + hstep, voffA);
;             PG8_WAIT_V(8); PG8_WAIT_L(0); PG8_BAR; PG8_MMA(0, 0, At, B0); PG8_MMA(0, 1, At, B1); PG8_BAR; PG8_SCHED;
;             PG8_LDA(At, 1, 1); PG8_STAGE(PG8_SB(1, 0), b3, voffB); PG8_STAGE(PG8_SB(1, 1), b3 + hstep, voffB); PG8_STAGE(PG8_SA(1, 0), a3, voffA);
;             PG8_WAIT_V(8); PG8_WAIT_L(0); PG8_BAR; PG8_MMA(1, 0, At, B0); PG8_MMA(1, 1, At, B1); PG8_BAR; PG8_SCHED;
	s_setprio 1
	ds_read_b128 v[128:131], v173
	ds_read_b128 v[132:135], v174
	ds_read_b128 v[152:155], v175
	ds_read_b128 v[156:159], v176
	ds_read_b128 v[182:185], v177
	ds_read_b128 v[186:189], v178
	ds_read_b128 v[190:193], v179
	ds_read_b128 v[194:197], v180
	s_add_u32 s36, s36, 0x40000
	s_addc_u32 s37, s37, 0
	s_mov_b32 m0, s44
	v_lshl_add_u64 v[236:237], s[36:37], 0, v[136:137]
	ds_read_b128 v[198:201], v164 offset:32768
	ds_read_b128 v[202:205], v164 offset:33792
	ds_read_b128 v[206:209], v164 offset:34816
	ds_read_b128 v[210:213], v164 offset:35840
	ds_read_b128 v[214:217], v164 offset:36864
	ds_read_b128 v[218:221], v164 offset:37888
	ds_read_b128 v[222:225], v164 offset:38912
	ds_read_b128 v[226:229], v164 offset:39936
	global_load_lds_dwordx4 v[236:237], off
	v_lshl_add_u64 v[236:237], s[36:37], 0, v[140:141]
	s_mov_b32 m0, s45
	s_nop 0
	global_load_lds_dwordx4 v[236:237], off
	s_waitcnt vmcnt(8)
	s_waitcnt lgkmcnt(0)
	s_setprio 0
	s_barrier
	v_mfma_f32_16x16x32_bf16 v[124:127], v[128:131], v[198:201], v[124:127]
	v_mfma_f32_16x16x32_bf16 v[120:123], v[152:155], v[198:201], v[120:123]
	v_mfma_f32_16x16x32_bf16 v[108:111], v[128:131], v[206:209], v[108:111]
	v_mfma_f32_16x16x32_bf16 v[104:107], v[152:155], v[206:209], v[104:107]
	v_mfma_f32_16x16x32_bf16 v[92:95], v[128:131], v[214:217], v[92:95]
	v_mfma_f32_16x16x32_bf16 v[88:91], v[152:155], v[214:217], v[88:91]
	v_mfma_f32_16x16x32_bf16 v[76:79], v[128:131], v[222:225], v[76:79]
	v_mfma_f32_16x16x32_bf16 v[72:75], v[152:155], v[222:225], v[72:75]
	v_mfma_f32_16x16x32_bf16 v[124:127], v[132:135], v[202:205], v[124:127]
	v_mfma_f32_16x16x32_bf16 v[120:123], v[156:159], v[202:205], v[120:123]
	v_mfma_f32_16x16x32_bf16 v[108:111], v[132:135], v[210:213], v[108:111]
	v_mfma_f32_16x16x32_bf16 v[104:107], v[156:159], v[210:213], v[104:107]
	v_mfma_f32_16x16x32_bf16 v[92:95], v[132:135], v[218:221], v[92:95]
	v_mfma_f32_16x16x32_bf16 v[88:91], v[156:159], v[218:221], v[88:91]
	v_mfma_f32_16x16x32_bf16 v[76:79], v[132:135], v[226:229], v[76:79]
	v_mfma_f32_16x16x32_bf16 v[72:75], v[156:159], v[226:229], v[72:75]
	v_mfma_f32_16x16x32_bf16 v[116:119], v[182:185], v[198:201], v[116:119]
	v_mfma_f32_16x16x32_bf16 v[112:115], v[190:193], v[198:201], v[112:115]
	v_mfma_f32_16x16x32_bf16 v[100:103], v[182:185], v[206:209], v[100:103]
	v_mfma_f32_16x16x32_bf16 v[96:99], v[190:193], v[206:209], v[96:99]
	v_mfma_f32_16x16x32_bf16 v[84:87], v[182:185], v[214:217], v[84:87]
	v_mfma_f32_16x16x32_bf16 v[80:83], v[190:193], v[214:217], v[80:83]
	v_mfma_f32_16x16x32_bf16 v[68:71], v[182:185], v[222:225], v[68:71]
	v_mfma_f32_16x16x32_bf16 v[64:67], v[190:193], v[222:225], v[64:67]
	v_mfma_f32_16x16x32_bf16 v[116:119], v[186:189], v[202:205], v[116:119]
	v_mfma_f32_16x16x32_bf16 v[112:115], v[194:197], v[202:205], v[112:115]
	v_mfma_f32_16x16x32_bf16 v[100:103], v[186:189], v[210:213], v[100:103]
	v_mfma_f32_16x16x32_bf16 v[96:99], v[194:197], v[210:213], v[96:99]
	v_mfma_f32_16x16x32_bf16 v[84:87], v[186:189], v[218:221], v[84:87]
	v_mfma_f32_16x16x32_bf16 v[80:83], v[194:197], v[218:221], v[80:83]
	v_mfma_f32_16x16x32_bf16 v[68:71], v[186:189], v[226:229], v[68:71]
	v_mfma_f32_16x16x32_bf16 v[64:67], v[194:197], v[226:229], v[64:67]
	s_barrier
	s_setprio 1
	s_mov_b32 m0, s49
	v_lshl_add_u64 v[160:161], v[160:161], 0, s[20:21]
	s_add_u32 s0, s0, 0x40080
	ds_read_b128 v[198:201], v164 offset:49152
	ds_read_b128 v[202:205], v164 offset:50176
	ds_read_b128 v[206:209], v164 offset:51200
	ds_read_b128 v[210:213], v164 offset:52224
	ds_read_b128 v[214:217], v164 offset:53248
	ds_read_b128 v[218:221], v164 offset:54272
	ds_read_b128 v[222:225], v164 offset:55296
	ds_read_b128 v[226:229], v164 offset:56320
	global_load_lds_dwordx4 v[160:161], off
	v_lshl_add_u64 v[160:161], v[230:231], 0, s[20:21]
	s_mov_b32 m0, s50
	s_addc_u32 s1, s1, 0
	global_load_lds_dwordx4 v[160:161], off
	v_lshl_add_u64 v[160:161], s[0:1], 0, v[138:139]
	s_mov_b32 m0, s53
	s_nop 0
	global_load_lds_dwordx4 v[160:161], off
	v_lshl_add_u64 v[160:161], s[0:1], 0, v[142:143]
	s_mov_b32 m0, s54
	s_nop 0
	global_load_lds_dwordx4 v[160:161], off
	v_lshl_add_u64 v[160:161], v[232:233], 0, s[20:21]
	s_mov_b32 m0, s51
	s_nop 0
	global_load_lds_dwordx4 v[160:161], off
	v_lshl_add_u64 v[160:161], v[234:235], 0, s[20:21]
	s_mov_b32 m0, s52
	s_nop 0
	global_load_lds_dwordx4 v[160:161], off
	s_waitcnt vmcnt(8)
	s_waitcnt lgkmcnt(0)
	s_setprio 0
	s_barrier
	v_mfma_f32_16x16x32_bf16 v[60:63], v[128:131], v[198:201], v[60:63]
	v_mfma_f32_16x16x32_bf16 v[56:59], v[152:155], v[198:201], v[56:59]
	v_mfma_f32_16x16x32_bf16 v[44:47], v[128:131], v[206:209], v[44:47]
	v_mfma_f32_16x16x32_bf16 v[40:43], v[152:155], v[206:209], v[40:43]
	v_mfma_f32_16x16x32_bf16 v[28:31], v[128:131], v[214:217], v[28:31]
	v_mfma_f32_16x16x32_bf16 v[24:27], v[152:155], v[214:217], v[24:27]
	v_mfma_f32_16x16x32_bf16 v[12:15], v[128:131], v[222:225], v[12:15]
	v_mfma_f32_16x16x32_bf16 v[8:11], v[152:155], v[222:225], v[8:11]
	v_mfma_f32_16x16x32_bf16 v[60:63], v[132:135], v[202:205], v[60:63]
	v_mfma_f32_16x16x32_bf16 v[56:59], v[156:159], v[202:205], v[56:59]
	v_mfma_f32_16x16x32_bf16 v[44:47], v[132:135], v[210:213], v[44:47]
	v_mfma_f32_16x16x32_bf16 v[40:43], v[156:159], v[210:213], v[40:43]
	v_mfma_f32_16x16x32_bf16 v[28:31], v[132:135], v[218:221], v[28:31]
	v_mfma_f32_16x16x32_bf16 v[24:27], v[156:159], v[218:221], v[24:27]
	v_mfma_f32_16x16x32_bf16 v[12:15], v[132:135], v[226:229], v[12:15]
	v_mfma_f32_16x16x32_bf16 v[8:11], v[156:159], v[226:229], v[8:11]
	v_mfma_f32_16x16x32_bf16 v[52:55], v[182:185], v[198:201], v[52:55]
	v_mfma_f32_16x16x32_bf16 v[48:51], v[190:193], v[198:201], v[48:51]
	v_mfma_f32_16x16x32_bf16 v[36:39], v[182:185], v[206:209], v[36:39]
	v_mfma_f32_16x16x32_bf16 v[32:35], v[190:193], v[206:209], v[32:35]
	v_mfma_f32_16x16x32_bf16 v[20:23], v[182:185], v[214:217], v[20:23]
	v_mfma_f32_16x16x32_bf16 v[16:19], v[190:193], v[214:217], v[16:19]
	v_mfma_f32_16x16x32_bf16 v[4:7], v[182:185], v[222:225], v[4:7]
	v_mfma_f32_16x16x32_bf16 v[0:3], v[190:193], v[222:225], v[0:3]
	v_mfma_f32_16x16x32_bf16 v[52:55], v[186:189], v[202:205], v[52:55]
	v_mfma_f32_16x16x32_bf16 v[48:51], v[194:197], v[202:205], v[48:51]
	v_mfma_f32_16x16x32_bf16 v[36:39], v[186:189], v[210:213], v[36:39]
	v_mfma_f32_16x16x32_bf16 v[32:35], v[194:197], v[210:213], v[32:35]
	v_mfma_f32_16x16x32_bf16 v[20:23], v[186:189], v[218:221], v[20:23]
	v_mfma_f32_16x16x32_bf16 v[16:19], v[194:197], v[218:221], v[16:19]
	v_mfma_f32_16x16x32_bf16 v[4:7], v[186:189], v[226:229], v[4:7]
	v_mfma_f32_16x16x32_bf16 v[0:3], v[194:197], v[226:229], v[0:3]
	s_barrier
	s_setprio 1
	s_add_i32 s65, s65, 2
	s_add_u32 s63, s63, 0x100
	s_addc_u32 s64, s64, 0
	s_add_u32 s12, s12, 0x100
	s_addc_u32 s13, s13, 0
	s_cmp_gt_u32 s65, 13
	s_cbranch_scc0 .LBB0_533
	s_setprio 0
	s_and_b64 vcc, exec, s[22:23]
	s_cbranch_vccz .LBB0_536
	s_barrier

; #define PG8_STAGE(bufoff, gbase, voff) do { _Pragma("unroll") for (int _i = 0; _i < 2; ++_i) \
;         __builtin_amdgcn_global_load_lds((const unsigned*)((const char*)(gbase) + (voff)[_i]), (PG8_LAS unsigned*)(lds + (bufoff) + ldsw + _i * 8192), 16, 0, 0); } while (0)
; #define PG8_LDA(dst, b, h) do { _Pragma("unroll") for (int m = 0; m < 4; ++m) _Pragma("unroll") for (int k = 0; k < 2; ++k) dst[m][k] = *(const PG8_LAS bf16x8*)(lds + PG8_SA(b, h) + aoff + m * 2048 + k * 1024); } while (0)
; #define PG8_LDB(dst, b, h) do { _Pragma("unroll") for (int n = 0; n < 2; ++n) _Pragma("unroll") for (int k = 0; k < 2; ++k) dst[n][k] = *(const PG8_LAS bf16x8*)(lds + PG8_SB(b, h) + boff + n * 2048 + k * 1024); } while (0)
; #define PG8_MMA(ai, bj, At, Bt) do { __builtin_amdgcn_s_setprio(1); _Pragma("unroll") for (int m = 0; m < 4; ++m) _Pragma("unroll") for (int n = 0; n < 2; ++n) _Pragma("unroll") for (int k = 0; k < 2; ++k) \
;         acc[ai][bj][m][n] = __builtin_amdgcn_mfma_f32_16x16x32_bf16(Bt[n][k], At[m][k], acc[ai][bj][m][n], 0, 0, 0); __builtin_amdgcn_s_setprio(0); } while (0)
; #define PG8_WAIT_V(n) asm volatile("s_waitcnt vmcnt(" #n ")" ::: "memory")
; #define PG8_WAIT_L(n) asm volatile("s_waitcnt lgkmcnt(" #n ")" ::: "memory")
; #define PG8_BAR __builtin_amdgcn_s_barrier()
; #define PG8_SCHED __builtin_amdgcn_sched_barrier(0)
; template <class Epi, class Sched, bool ALIGN_EPI = false, bool SP2 = false>
; __device__ __forceinline__ void gemm_phase(PG8_LAS unsigned char* lds, const Gemm g, const Sched& S, const Epi& E, const int tid_arg) {
;     ...
;             PG8_LDB(B0, 0, 0); PG8_LDB(B1, 0, 1); PG8_SCHED; PG8_LDA(At, 0, 0); PG8_STAGE(PG8_SA(1, 1), a1 + hstep, voffA);
;             PG8_WAIT_V(8); PG8_WAIT_L(0); PG8_BAR; PG8_MMA(0, 0, At, B0); PG8_MMA(0, 1, At, B1); PG8_BAR; PG8_SCHED;
;             PG8_LDA(At, 0, 1); PG8_STAGE(PG8_SB(0, 0), b2, voffB); PG8_STAGE(PG8_SB(0, 1), b2 + hstep, voffB); PG8_STAGE(PG8_SA(0, 0), a2, voffA);
;             PG8_WAIT_V(8); PG8_WAIT_L(0); PG8_BAR; PG8_MMA(1, 0, At, B0); PG8_MMA(1, 1, At, B1); PG8_BAR; PG8_SCHED;
.LBB0_685:
	ds_read_b128 v[72:75], v207
	ds_read_b128 v[100:103], v208
	ds_read_b128 v[136:139], v209
	ds_read_b128 v[140:143], v210
	ds_read_b128 v[144:147], v211
	ds_read_b128 v[148:151], v212
	ds_read_b128 v[152:155], v213
	ds_read_b128 v[156:159], v214
	s_add_u32 s10, s4, 0x100
	s_addc_u32 s11, s5, 0
	s_cmp_eq_u32 s79, 12
	s_cselect_b32 s15, s17, s11
	s_cselect_b32 s14, s37, s10
	s_cselect_b32 s1, s35, s78
	s_cselect_b32 s0, s46, s47
	s_mov_b32 m0, s72
	v_lshl_add_u64 v[184:185], s[4:5], 0, v[196:197]
	ds_read_b128 v[160:163], v206
	ds_read_b128 v[164:167], v206 offset:1024
	ds_read_b128 v[168:171], v206 offset:2048
	ds_read_b128 v[172:175], v206 offset:3072
	ds_read_b128 v[176:179], v206 offset:4096
	ds_read_b128 v[180:183], v206 offset:5120
	ds_read_b128 v[226:229], v206 offset:6144
	ds_read_b128 v[230:233], v206 offset:7168
	global_load_lds_dwordx4 v[184:185], off
	v_lshl_add_u64 v[184:185], s[4:5], 0, v[194:195]
	s_mov_b32 m0, s73
	s_nop 0
	global_load_lds_dwordx4 v[184:185], off
	s_waitcnt vmcnt(8)
	s_waitcnt lgkmcnt(0)
	s_setprio 0
	s_barrier
	v_mfma_f32_16x16x32_bf16 v[132:135], v[72:75], v[160:163], v[132:135]
	v_mfma_f32_16x16x32_bf16 v[60:63], v[136:139], v[160:163], v[60:63]
	v_mfma_f32_16x16x32_bf16 v[124:127], v[72:75], v[168:171], v[124:127]
	v_mfma_f32_16x16x32_bf16 v[52:55], v[136:139], v[168:171], v[52:55]
	v_mfma_f32_16x16x32_bf16 v[116:119], v[72:75], v[176:179], v[116:119]
	v_mfma_f32_16x16x32_bf16 v[44:47], v[136:139], v[176:179], v[44:47]
	v_mfma_f32_16x16x32_bf16 v[108:111], v[72:75], v[226:229], v[108:111]
	v_mfma_f32_16x16x32_bf16 v[36:39], v[136:139], v[226:229], v[36:39]
	v_mfma_f32_16x16x32_bf16 v[132:135], v[100:103], v[164:167], v[132:135]
	v_mfma_f32_16x16x32_bf16 v[60:63], v[140:143], v[164:167], v[60:63]
	v_mfma_f32_16x16x32_bf16 v[124:127], v[100:103], v[172:175], v[124:127]
	v_mfma_f32_16x16x32_bf16 v[52:55], v[140:143], v[172:175], v[52:55]
	v_mfma_f32_16x16x32_bf16 v[116:119], v[100:103], v[180:183], v[116:119]
	v_mfma_f32_16x16x32_bf16 v[44:47], v[140:143], v[180:183], v[44:47]
	v_mfma_f32_16x16x32_bf16 v[108:111], v[100:103], v[230:233], v[108:111]
	v_mfma_f32_16x16x32_bf16 v[36:39], v[140:143], v[230:233], v[36:39]
	v_mfma_f32_16x16x32_bf16 v[128:131], v[144:147], v[160:163], v[128:131]
	v_mfma_f32_16x16x32_bf16 v[56:59], v[152:155], v[160:163], v[56:59]
	v_mfma_f32_16x16x32_bf16 v[120:123], v[144:147], v[168:171], v[120:123]
	v_mfma_f32_16x16x32_bf16 v[48:51], v[152:155], v[168:171], v[48:51]
	v_mfma_f32_16x16x32_bf16 v[112:115], v[144:147], v[176:179], v[112:115]
	v_mfma_f32_16x16x32_bf16 v[40:43], v[152:155], v[176:179], v[40:43]
	v_mfma_f32_16x16x32_bf16 v[104:107], v[144:147], v[226:229], v[104:107]
	v_mfma_f32_16x16x32_bf16 v[32:35], v[152:155], v[226:229], v[32:35]
	v_mfma_f32_16x16x32_bf16 v[128:131], v[148:151], v[164:167], v[128:131]
	v_mfma_f32_16x16x32_bf16 v[56:59], v[156:159], v[164:167], v[56:59]
	v_mfma_f32_16x16x32_bf16 v[120:123], v[148:151], v[172:175], v[120:123]
	v_mfma_f32_16x16x32_bf16 v[48:51], v[156:159], v[172:175], v[48:51]
	v_mfma_f32_16x16x32_bf16 v[112:115], v[148:151], v[180:183], v[112:115]
	v_mfma_f32_16x16x32_bf16 v[40:43], v[156:159], v[180:183], v[40:43]
	v_mfma_f32_16x16x32_bf16 v[104:107], v[148:151], v[230:233], v[104:107]
	v_mfma_f32_16x16x32_bf16 v[32:35], v[156:159], v[230:233], v[32:35]
	s_barrier
	s_setprio 1
	s_mov_b32 m0, s43
	v_lshl_add_u64 v[184:185], s[0:1], 0, v[188:189]
	s_add_u32 s4, s0, 0x40000
	ds_read_b128 v[160:163], v206 offset:16384
	ds_read_b128 v[164:167], v206 offset:17408
	ds_read_b128 v[168:171], v206 offset:18432
	ds_read_b128 v[172:175], v206 offset:19456
	ds_read_b128 v[176:179], v206 offset:20480
	ds_read_b128 v[180:183], v206 offset:21504
	ds_read_b128 v[226:229], v206 offset:22528
	ds_read_b128 v[230:233], v206 offset:23552
	global_load_lds_dwordx4 v[184:185], off
	v_lshl_add_u64 v[202:203], s[0:1], 0, v[192:193]
	s_mov_b32 m0, s45
	s_addc_u32 s5, s1, 0
	global_load_lds_dwordx4 v[202:203], off
	v_lshl_add_u64 v[234:235], s[4:5], 0, v[188:189]
	s_mov_b32 m0, s50
	v_lshl_add_u64 v[236:237], s[14:15], 0, v[190:191]
	global_load_lds_dwordx4 v[234:235], off
	v_lshl_add_u64 v[234:235], s[4:5], 0, v[192:193]
	s_mov_b32 m0, s51
	s_nop 0
	global_load_lds_dwordx4 v[234:235], off
	v_lshl_add_u64 v[234:235], s[14:15], 0, v[186:187]
	s_mov_b32 m0, s49
	s_nop 0
	global_load_lds_dwordx4 v[234:235], off
	s_mov_b32 m0, s52
	s_nop 0
	global_load_lds_dwordx4 v[236:237], off
	s_waitcnt vmcnt(8)
	s_waitcnt lgkmcnt(0)
	s_setprio 0
	s_barrier
	v_mfma_f32_16x16x32_bf16 v[96:99], v[72:75], v[160:163], v[96:99]
	v_mfma_f32_16x16x32_bf16 v[28:31], v[136:139], v[160:163], v[28:31]
	v_mfma_f32_16x16x32_bf16 v[88:91], v[72:75], v[168:171], v[88:91]
	v_mfma_f32_16x16x32_bf16 v[20:23], v[136:139], v[168:171], v[20:23]
	v_mfma_f32_16x16x32_bf16 v[80:83], v[72:75], v[176:179], v[80:83]
	v_mfma_f32_16x16x32_bf16 v[12:15], v[136:139], v[176:179], v[12:15]
	v_mfma_f32_16x16x32_bf16 v[68:71], v[72:75], v[226:229], v[68:71]
	v_mfma_f32_16x16x32_bf16 v[4:7], v[136:139], v[226:229], v[4:7]
	v_mfma_f32_16x16x32_bf16 v[96:99], v[100:103], v[164:167], v[96:99]
	v_mfma_f32_16x16x32_bf16 v[28:31], v[140:143], v[164:167], v[28:31]
	v_mfma_f32_16x16x32_bf16 v[88:91], v[100:103], v[172:175], v[88:91]
	v_mfma_f32_16x16x32_bf16 v[20:23], v[140:143], v[172:175], v[20:23]
	v_mfma_f32_16x16x32_bf16 v[80:83], v[100:103], v[180:183], v[80:83]
	v_mfma_f32_16x16x32_bf16 v[12:15], v[140:143], v[180:183], v[12:15]
	v_mfma_f32_16x16x32_bf16 v[68:71], v[100:103], v[230:233], v[68:71]
	v_mfma_f32_16x16x32_bf16 v[4:7], v[140:143], v[230:233], v[4:7]
	v_mfma_f32_16x16x32_bf16 v[24:27], v[152:155], v[160:163], v[24:27]
	v_mfma_f32_16x16x32_bf16 v[84:87], v[144:147], v[168:171], v[84:87]
	v_mfma_f32_16x16x32_bf16 v[16:19], v[152:155], v[168:171], v[16:19]
	v_mfma_f32_16x16x32_bf16 v[76:79], v[144:147], v[176:179], v[76:79]
	v_mfma_f32_16x16x32_bf16 v[8:11], v[152:155], v[176:179], v[8:11]
	v_mfma_f32_16x16x32_bf16 v[64:67], v[144:147], v[226:229], v[64:67]
	v_mfma_f32_16x16x32_bf16 v[0:3], v[152:155], v[226:229], v[0:3]
	v_mfma_f32_16x16x32_bf16 v[72:75], v[144:147], v[160:163], v[92:95]
	v_mfma_f32_16x16x32_bf16 v[24:27], v[156:159], v[164:167], v[24:27]
	v_mfma_f32_16x16x32_bf16 v[84:87], v[148:151], v[172:175], v[84:87]
	v_mfma_f32_16x16x32_bf16 v[16:19], v[156:159], v[172:175], v[16:19]
	v_mfma_f32_16x16x32_bf16 v[76:79], v[148:151], v[180:183], v[76:79]
	v_mfma_f32_16x16x32_bf16 v[8:11], v[156:159], v[180:183], v[8:11]
	v_mfma_f32_16x16x32_bf16 v[64:67], v[148:151], v[230:233], v[64:67]
	v_mfma_f32_16x16x32_bf16 v[0:3], v[156:159], v[230:233], v[0:3]
	v_mfma_f32_16x16x32_bf16 v[72:75], v[148:151], v[164:167], v[72:75]
	s_barrier
; #define PG8_STAGE(bufoff, gbase, voff) do { _Pragma("unroll") for (int _i = 0; _i < 2; ++_i) \
;         __builtin_amdgcn_global_load_lds((const unsigned*)((const char*)(gbase) + (voff)[_i]), (PG8_LAS unsigned*)(lds + (bufoff) + ldsw + _i * 8192), 16, 0, 0); } while (0)
; #define PG8_LDA(dst, b, h) do { _Pragma("unroll") for (int m = 0; m < 4; ++m) _Pragma("unroll") for (int k = 0; k < 2; ++k) dst[m][k] = *(const PG8_LAS bf16x8*)(lds + PG8_SA(b, h) + aoff + m * 2048 + k * 1024); } while (0)
; #define PG8_LDB(dst, b, h) do { _Pragma("unroll") for (int n = 0; n < 2; ++n) _Pragma("unroll") for (int k = 0; k < 2; ++k) dst[n][k] = *(const PG8_LAS bf16x8*)(lds + PG8_SB(b, h) + boff + n * 2048 + k * 1024); } while (0)
; #define PG8_MMA(ai, bj, At, Bt) do { __builtin_amdgcn_s_setprio(1); _Pragma("unroll") for (int m = 0; m < 4; ++m) _Pragma("unroll") for (int n = 0; n < 2; ++n) _Pragma("unroll") for (int k = 0; k < 2; ++k) \
;         acc[ai][bj][m][n] = __builtin_amdgcn_mfma_f32_16x16x32_bf16(Bt[n][k], At[m][k], acc[ai][bj][m][n], 0, 0, 0); __builtin_amdgcn_s_setprio(0); } while (0)
; #define PG8_WAIT_V(n) asm volatile("s_waitcnt vmcnt(" #n ")" ::: "memory")
; #define PG8_WAIT_L(n) asm volatile("s_waitcnt lgkmcnt(" #n ")" ::: "memory")
; #define PG8_BAR __builtin_amdgcn_s_barrier()
; #define PG8_SCHED __builtin_amdgcn_sched_barrier(0)
; template <class Epi, class Sched, bool ALIGN_EPI = false, bool SP2 = false>
; __device__ __forceinline__ void gemm_phase(PG8_LAS unsigned char* lds, const Gemm g, const Sched& S, const Epi& E, const int tid_arg) {
;     ...
;             PG8_LDB(B0, 1, 0); PG8_LDB(B1, 1, 1); PG8_SCHED; PG8_LDA(At, 1, 0); PG8_STAGE(PG8_SA(0, 1), a2 + hstep, voffA);
;             PG8_WAIT_V(8); PG8_WAIT_L(0); PG8_BAR; PG8_MMA(0, 0, At, B0); PG8_MMA(0, 1, At, B1); PG8_BAR; PG8_SCHED;
;             PG8_LDA(At, 1, 1); PG8_STAGE(PG8_SB(1, 0), b3, voffB); PG8_STAGE(PG8_SB(1, 1), b3 + hstep, voffB); PG8_STAGE(PG8_SA(1, 0), a3, voffA);
;             PG8_WAIT_V(8); PG8_WAIT_L(0); PG8_BAR; PG8_MMA(1, 0, At, B0); PG8_MMA(1, 1, At, B1); PG8_BAR; PG8_SCHED;
	s_setprio 1
	ds_read_b128 v[92:95], v215
	ds_read_b128 v[100:103], v216
	ds_read_b128 v[136:139], v217
	ds_read_b128 v[140:143], v218
	ds_read_b128 v[144:147], v219
	ds_read_b128 v[148:151], v220
	ds_read_b128 v[152:155], v221
	ds_read_b128 v[156:159], v222
	s_add_u32 s4, s14, 0x40000
	s_addc_u32 s5, s15, 0
	s_mov_b32 m0, s53
	v_lshl_add_u64 v[238:239], s[4:5], 0, v[186:187]
	ds_read_b128 v[160:163], v206 offset:32768
	ds_read_b128 v[164:167], v206 offset:33792
	ds_read_b128 v[168:171], v206 offset:34816
	ds_read_b128 v[172:175], v206 offset:35840
	ds_read_b128 v[176:179], v206 offset:36864
	ds_read_b128 v[180:183], v206 offset:37888
	ds_read_b128 v[226:229], v206 offset:38912
	ds_read_b128 v[230:233], v206 offset:39936
	global_load_lds_dwordx4 v[238:239], off
	v_lshl_add_u64 v[238:239], s[4:5], 0, v[190:191]
	s_mov_b32 m0, s54
	s_nop 0
	global_load_lds_dwordx4 v[238:239], off
	s_waitcnt vmcnt(8)
	s_waitcnt lgkmcnt(0)
	s_setprio 0
	s_barrier
	v_mfma_f32_16x16x32_bf16 v[132:135], v[92:95], v[160:163], v[132:135]
	v_mfma_f32_16x16x32_bf16 v[60:63], v[136:139], v[160:163], v[60:63]
	v_mfma_f32_16x16x32_bf16 v[124:127], v[92:95], v[168:171], v[124:127]
	v_mfma_f32_16x16x32_bf16 v[52:55], v[136:139], v[168:171], v[52:55]
	v_mfma_f32_16x16x32_bf16 v[116:119], v[92:95], v[176:179], v[116:119]
	v_mfma_f32_16x16x32_bf16 v[44:47], v[136:139], v[176:179], v[44:47]
	v_mfma_f32_16x16x32_bf16 v[108:111], v[92:95], v[226:229], v[108:111]
	v_mfma_f32_16x16x32_bf16 v[36:39], v[136:139], v[226:229], v[36:39]
	v_mfma_f32_16x16x32_bf16 v[132:135], v[100:103], v[164:167], v[132:135]
	v_mfma_f32_16x16x32_bf16 v[60:63], v[140:143], v[164:167], v[60:63]
	v_mfma_f32_16x16x32_bf16 v[124:127], v[100:103], v[172:175], v[124:127]
	v_mfma_f32_16x16x32_bf16 v[52:55], v[140:143], v[172:175], v[52:55]
	v_mfma_f32_16x16x32_bf16 v[116:119], v[100:103], v[180:183], v[116:119]
	v_mfma_f32_16x16x32_bf16 v[44:47], v[140:143], v[180:183], v[44:47]
	v_mfma_f32_16x16x32_bf16 v[108:111], v[100:103], v[230:233], v[108:111]
	v_mfma_f32_16x16x32_bf16 v[36:39], v[140:143], v[230:233], v[36:39]
	v_mfma_f32_16x16x32_bf16 v[128:131], v[144:147], v[160:163], v[128:131]
	v_mfma_f32_16x16x32_bf16 v[56:59], v[152:155], v[160:163], v[56:59]
	v_mfma_f32_16x16x32_bf16 v[120:123], v[144:147], v[168:171], v[120:123]
	v_mfma_f32_16x16x32_bf16 v[48:51], v[152:155], v[168:171], v[48:51]
	v_mfma_f32_16x16x32_bf16 v[112:115], v[144:147], v[176:179], v[112:115]
	v_mfma_f32_16x16x32_bf16 v[40:43], v[152:155], v[176:179], v[40:43]
	v_mfma_f32_16x16x32_bf16 v[104:107], v[144:147], v[226:229], v[104:107]
	v_mfma_f32_16x16x32_bf16 v[32:35], v[152:155], v[226:229], v[32:35]
	v_mfma_f32_16x16x32_bf16 v[128:131], v[148:151], v[164:167], v[128:131]
	v_mfma_f32_16x16x32_bf16 v[56:59], v[156:159], v[164:167], v[56:59]
	v_mfma_f32_16x16x32_bf16 v[120:123], v[148:151], v[172:175], v[120:123]
	v_mfma_f32_16x16x32_bf16 v[48:51], v[156:159], v[172:175], v[48:51]
	v_mfma_f32_16x16x32_bf16 v[112:115], v[148:151], v[180:183], v[112:115]
	v_mfma_f32_16x16x32_bf16 v[40:43], v[156:159], v[180:183], v[40:43]
	v_mfma_f32_16x16x32_bf16 v[104:107], v[148:151], v[230:233], v[104:107]
	v_mfma_f32_16x16x32_bf16 v[32:35], v[156:159], v[230:233], v[32:35]
	s_barrier
	s_setprio 1
	s_mov_b32 m0, s59
	v_lshl_add_u64 v[184:185], v[184:185], 0, s[24:25]
	s_add_u32 s0, s0, 0x40080
	ds_read_b128 v[160:163], v206 offset:49152
	ds_read_b128 v[164:167], v206 offset:50176
	ds_read_b128 v[168:171], v206 offset:51200
	ds_read_b128 v[172:175], v206 offset:52224
	ds_read_b128 v[176:179], v206 offset:53248
	ds_read_b128 v[180:183], v206 offset:54272
	ds_read_b128 v[226:229], v206 offset:55296
	ds_read_b128 v[230:233], v206 offset:56320
	global_load_lds_dwordx4 v[184:185], off
	v_lshl_add_u64 v[184:185], v[202:203], 0, s[24:25]
	s_mov_b32 m0, s60
	s_addc_u32 s1, s1, 0
	global_load_lds_dwordx4 v[184:185], off
	v_lshl_add_u64 v[184:185], s[0:1], 0, v[188:189]
	s_mov_b32 m0, s63
	s_nop 0
	global_load_lds_dwordx4 v[184:185], off
	v_lshl_add_u64 v[184:185], s[0:1], 0, v[192:193]
	s_mov_b32 m0, s64
	s_nop 0
	global_load_lds_dwordx4 v[184:185], off
	v_lshl_add_u64 v[184:185], v[234:235], 0, s[24:25]
	s_mov_b32 m0, s61
	s_nop 0
	global_load_lds_dwordx4 v[184:185], off
	v_lshl_add_u64 v[184:185], v[236:237], 0, s[24:25]
	s_mov_b32 m0, s62
	s_nop 0
	global_load_lds_dwordx4 v[184:185], off
	s_waitcnt vmcnt(8)
	s_waitcnt lgkmcnt(0)
	s_setprio 0
	s_barrier
	v_mfma_f32_16x16x32_bf16 v[96:99], v[92:95], v[160:163], v[96:99]
	v_mfma_f32_16x16x32_bf16 v[28:31], v[136:139], v[160:163], v[28:31]
	v_mfma_f32_16x16x32_bf16 v[88:91], v[92:95], v[168:171], v[88:91]
	v_mfma_f32_16x16x32_bf16 v[20:23], v[136:139], v[168:171], v[20:23]
	v_mfma_f32_16x16x32_bf16 v[80:83], v[92:95], v[176:179], v[80:83]
	v_mfma_f32_16x16x32_bf16 v[12:15], v[136:139], v[176:179], v[12:15]
	v_mfma_f32_16x16x32_bf16 v[68:71], v[92:95], v[226:229], v[68:71]
	v_mfma_f32_16x16x32_bf16 v[4:7], v[136:139], v[226:229], v[4:7]
	v_mfma_f32_16x16x32_bf16 v[96:99], v[100:103], v[164:167], v[96:99]
	v_mfma_f32_16x16x32_bf16 v[28:31], v[140:143], v[164:167], v[28:31]
	v_mfma_f32_16x16x32_bf16 v[88:91], v[100:103], v[172:175], v[88:91]
	v_mfma_f32_16x16x32_bf16 v[20:23], v[140:143], v[172:175], v[20:23]
	v_mfma_f32_16x16x32_bf16 v[80:83], v[100:103], v[180:183], v[80:83]
	v_mfma_f32_16x16x32_bf16 v[12:15], v[140:143], v[180:183], v[12:15]
	v_mfma_f32_16x16x32_bf16 v[68:71], v[100:103], v[230:233], v[68:71]
	v_mfma_f32_16x16x32_bf16 v[4:7], v[140:143], v[230:233], v[4:7]
	v_mfma_f32_16x16x32_bf16 v[72:75], v[144:147], v[160:163], v[72:75]
	v_mfma_f32_16x16x32_bf16 v[92:95], v[148:151], v[164:167], v[72:75]
	v_mfma_f32_16x16x32_bf16 v[72:75], v[144:147], v[168:171], v[84:87]
	v_mfma_f32_16x16x32_bf16 v[24:27], v[152:155], v[160:163], v[24:27]
	v_mfma_f32_16x16x32_bf16 v[84:87], v[148:151], v[172:175], v[72:75]
	v_mfma_f32_16x16x32_bf16 v[16:19], v[152:155], v[168:171], v[16:19]
	v_mfma_f32_16x16x32_bf16 v[72:75], v[144:147], v[176:179], v[76:79]
	v_mfma_f32_16x16x32_bf16 v[8:11], v[152:155], v[176:179], v[8:11]
	v_mfma_f32_16x16x32_bf16 v[64:67], v[144:147], v[226:229], v[64:67]
	v_mfma_f32_16x16x32_bf16 v[0:3], v[152:155], v[226:229], v[0:3]
	v_mfma_f32_16x16x32_bf16 v[24:27], v[156:159], v[164:167], v[24:27]
	v_mfma_f32_16x16x32_bf16 v[16:19], v[156:159], v[172:175], v[16:19]
	v_mfma_f32_16x16x32_bf16 v[76:79], v[148:151], v[180:183], v[72:75]
	v_mfma_f32_16x16x32_bf16 v[8:11], v[156:159], v[180:183], v[8:11]
	v_mfma_f32_16x16x32_bf16 v[64:67], v[148:151], v[230:233], v[64:67]
	v_mfma_f32_16x16x32_bf16 v[0:3], v[156:159], v[230:233], v[0:3]
	s_barrier
	s_setprio 1
	s_add_i32 s79, s79, 2
	s_add_u32 s47, s47, 0x100
	s_addc_u32 s78, s78, 0
	s_cmp_gt_u32 s79, 13
	s_mov_b64 s[4:5], s[10:11]
	s_cbranch_scc0 .LBB0_685
	s_setprio 0
	s_and_b64 vcc, exec, s[26:27]
	s_cbranch_vccz .LBB0_688
	s_barrier

; #define PG8_STAGE(bufoff, gbase, voff) do { _Pragma("unroll") for (int _i = 0; _i < 2; ++_i) \
;         __builtin_amdgcn_global_load_lds((const unsigned*)((const char*)(gbase) + (voff)[_i]), (PG8_LAS unsigned*)(lds + (bufoff) + ldsw + _i * 8192), 16, 0, 0); } while (0)
; #define PG8_LDA(dst, b, h) do { _Pragma("unroll") for (int m = 0; m < 4; ++m) _Pragma("unroll") for (int k = 0; k < 2; ++k) dst[m][k] = *(const PG8_LAS bf16x8*)(lds + PG8_SA(b, h) + aoff + m * 2048 + k * 1024); } while (0)
; #define PG8_LDB(dst, b, h) do { _Pragma("unroll") for (int n = 0; n < 2; ++n) _Pragma("unroll") for (int k = 0; k < 2; ++k) dst[n][k] = *(const PG8_LAS bf16x8*)(lds + PG8_SB(b, h) + boff + n * 2048 + k * 1024); } while (0)
; #define PG8_MMA(ai, bj, At, Bt) do { __builtin_amdgcn_s_setprio(1); _Pragma("unroll") for (int m = 0; m < 4; ++m) _Pragma("unroll") for (int n = 0; n < 2; ++n) _Pragma("unroll") for (int k = 0; k < 2; ++k) \
;         acc[ai][bj][m][n] = __builtin_amdgcn_mfma_f32_16x16x32_bf16(Bt[n][k], At[m][k], acc[ai][bj][m][n], 0, 0, 0); __builtin_amdgcn_s_setprio(0); } while (0)
; #define PG8_WAIT_V(n) asm volatile("s_waitcnt vmcnt(" #n ")" ::: "memory")
; #define PG8_WAIT_L(n) asm volatile("s_waitcnt lgkmcnt(" #n ")" ::: "memory")
; #define PG8_BAR __builtin_amdgcn_s_barrier()
; #define PG8_SCHED __builtin_amdgcn_sched_barrier(0)
; template <class Epi, class Sched, bool ALIGN_EPI = false, bool SP2 = false>
; __device__ __forceinline__ void gemm_phase(PG8_LAS unsigned char* lds, const Gemm g, const Sched& S, const Epi& E, const int tid_arg) {
;     ...
;             PG8_LDB(B0, 0, 0); PG8_LDB(B1, 0, 1); PG8_SCHED; PG8_LDA(At, 0, 0); PG8_STAGE(PG8_SA(1, 1), a1 + hstep, voffA);
;             PG8_WAIT_V(8); PG8_WAIT_L(0); PG8_BAR; PG8_MMA(0, 0, At, B0); PG8_MMA(0, 1, At, B1); PG8_BAR; PG8_SCHED;
;             PG8_LDA(At, 0, 1); PG8_STAGE(PG8_SB(0, 0), b2, voffB); PG8_STAGE(PG8_SB(0, 1), b2 + hstep, voffB); PG8_STAGE(PG8_SA(0, 0), a2, voffA);
;             PG8_WAIT_V(8); PG8_WAIT_L(0); PG8_BAR; PG8_MMA(1, 0, At, B0); PG8_MMA(1, 1, At, B1); PG8_BAR; PG8_SCHED;
.LBB0_871:
	ds_read_b128 v[144:147], v151
	ds_read_b128 v[168:171], v152
	ds_read_b128 v[172:175], v153
	ds_read_b128 v[176:179], v154
	ds_read_b128 v[180:183], v155
	ds_read_b128 v[184:187], v156
	ds_read_b128 v[188:191], v157
	ds_read_b128 v[192:195], v158
	s_add_u32 s22, s4, 0x100
	s_addc_u32 s23, s5, 0
	s_cmp_eq_u32 s57, 40
	s_cselect_b32 s25, s13, s23
	s_cselect_b32 s24, s12, s22
	s_cselect_b32 s1, s21, s56
	s_cselect_b32 s0, s20, s55
	s_mov_b32 m0, s48
	v_lshl_add_u64 v[228:229], s[4:5], 0, v[138:139]
	ds_read_b128 v[196:199], v150
	ds_read_b128 v[200:203], v150 offset:1024
	ds_read_b128 v[204:207], v150 offset:2048
	ds_read_b128 v[208:211], v150 offset:3072
	ds_read_b128 v[212:215], v150 offset:4096
	ds_read_b128 v[216:219], v150 offset:5120
	ds_read_b128 v[220:223], v150 offset:6144
	ds_read_b128 v[224:227], v150 offset:7168
	global_load_lds_dwordx4 v[228:229], off
	v_lshl_add_u64 v[228:229], s[4:5], 0, v[136:137]
	s_mov_b32 m0, s49
	s_nop 0
	global_load_lds_dwordx4 v[228:229], off
	s_waitcnt vmcnt(8)
	s_waitcnt lgkmcnt(0)
	s_setprio 0
	s_barrier
	v_mfma_f32_16x16x32_bf16 v[124:127], v[144:147], v[196:199], v[124:127]
	v_mfma_f32_16x16x32_bf16 v[120:123], v[172:175], v[196:199], v[120:123]
	v_mfma_f32_16x16x32_bf16 v[108:111], v[144:147], v[204:207], v[108:111]
	v_mfma_f32_16x16x32_bf16 v[104:107], v[172:175], v[204:207], v[104:107]
	v_mfma_f32_16x16x32_bf16 v[92:95], v[144:147], v[212:215], v[92:95]
	v_mfma_f32_16x16x32_bf16 v[88:91], v[172:175], v[212:215], v[88:91]
	v_mfma_f32_16x16x32_bf16 v[76:79], v[144:147], v[220:223], v[76:79]
	v_mfma_f32_16x16x32_bf16 v[72:75], v[172:175], v[220:223], v[72:75]
	v_mfma_f32_16x16x32_bf16 v[124:127], v[168:171], v[200:203], v[124:127]
	v_mfma_f32_16x16x32_bf16 v[120:123], v[176:179], v[200:203], v[120:123]
	v_mfma_f32_16x16x32_bf16 v[108:111], v[168:171], v[208:211], v[108:111]
	v_mfma_f32_16x16x32_bf16 v[104:107], v[176:179], v[208:211], v[104:107]
	v_mfma_f32_16x16x32_bf16 v[92:95], v[168:171], v[216:219], v[92:95]
	v_mfma_f32_16x16x32_bf16 v[88:91], v[176:179], v[216:219], v[88:91]
	v_mfma_f32_16x16x32_bf16 v[76:79], v[168:171], v[224:227], v[76:79]
	v_mfma_f32_16x16x32_bf16 v[72:75], v[176:179], v[224:227], v[72:75]
	v_mfma_f32_16x16x32_bf16 v[116:119], v[180:183], v[196:199], v[116:119]
	v_mfma_f32_16x16x32_bf16 v[112:115], v[188:191], v[196:199], v[112:115]
	v_mfma_f32_16x16x32_bf16 v[100:103], v[180:183], v[204:207], v[100:103]
	v_mfma_f32_16x16x32_bf16 v[96:99], v[188:191], v[204:207], v[96:99]
	v_mfma_f32_16x16x32_bf16 v[84:87], v[180:183], v[212:215], v[84:87]
	v_mfma_f32_16x16x32_bf16 v[80:83], v[188:191], v[212:215], v[80:83]
	v_mfma_f32_16x16x32_bf16 v[68:71], v[180:183], v[220:223], v[68:71]
	v_mfma_f32_16x16x32_bf16 v[64:67], v[188:191], v[220:223], v[64:67]
	v_mfma_f32_16x16x32_bf16 v[116:119], v[184:187], v[200:203], v[116:119]
	v_mfma_f32_16x16x32_bf16 v[112:115], v[192:195], v[200:203], v[112:115]
	v_mfma_f32_16x16x32_bf16 v[100:103], v[184:187], v[208:211], v[100:103]
	v_mfma_f32_16x16x32_bf16 v[96:99], v[192:195], v[208:211], v[96:99]
	v_mfma_f32_16x16x32_bf16 v[84:87], v[184:187], v[216:219], v[84:87]
	v_mfma_f32_16x16x32_bf16 v[80:83], v[192:195], v[216:219], v[80:83]
	v_mfma_f32_16x16x32_bf16 v[68:71], v[184:187], v[224:227], v[68:71]
	v_mfma_f32_16x16x32_bf16 v[64:67], v[192:195], v[224:227], v[64:67]
	s_barrier
	s_setprio 1
	s_mov_b32 m0, s29
	v_lshl_add_u64 v[228:229], s[0:1], 0, v[130:131]
	s_add_u32 s4, s0, 0xb0000
	ds_read_b128 v[196:199], v150 offset:16384
	ds_read_b128 v[200:203], v150 offset:17408
	ds_read_b128 v[204:207], v150 offset:18432
	ds_read_b128 v[208:211], v150 offset:19456
	ds_read_b128 v[212:215], v150 offset:20480
	ds_read_b128 v[216:219], v150 offset:21504
	ds_read_b128 v[220:223], v150 offset:22528
	ds_read_b128 v[224:227], v150 offset:23552
	global_load_lds_dwordx4 v[228:229], off
	v_lshl_add_u64 v[230:231], s[0:1], 0, v[134:135]
	s_mov_b32 m0, s30
	s_addc_u32 s5, s1, 0
	global_load_lds_dwordx4 v[230:231], off
	v_lshl_add_u64 v[232:233], s[4:5], 0, v[130:131]
	s_mov_b32 m0, s31
	v_lshl_add_u64 v[234:235], s[24:25], 0, v[132:133]
	global_load_lds_dwordx4 v[232:233], off
	v_lshl_add_u64 v[232:233], s[4:5], 0, v[134:135]
	s_mov_b32 m0, s33
	s_nop 0
	global_load_lds_dwordx4 v[232:233], off
	v_lshl_add_u64 v[232:233], s[24:25], 0, v[128:129]
	s_mov_b32 m0, s28
	s_nop 0
	global_load_lds_dwordx4 v[232:233], off
	s_mov_b32 m0, s34
	s_nop 0
	global_load_lds_dwordx4 v[234:235], off
	s_waitcnt vmcnt(8)
	s_waitcnt lgkmcnt(0)
	s_setprio 0
	s_barrier
	v_mfma_f32_16x16x32_bf16 v[60:63], v[144:147], v[196:199], v[60:63]
	v_mfma_f32_16x16x32_bf16 v[56:59], v[172:175], v[196:199], v[56:59]
	v_mfma_f32_16x16x32_bf16 v[44:47], v[144:147], v[204:207], v[44:47]
	v_mfma_f32_16x16x32_bf16 v[40:43], v[172:175], v[204:207], v[40:43]
	v_mfma_f32_16x16x32_bf16 v[28:31], v[144:147], v[212:215], v[28:31]
	v_mfma_f32_16x16x32_bf16 v[24:27], v[172:175], v[212:215], v[24:27]
	v_mfma_f32_16x16x32_bf16 v[12:15], v[144:147], v[220:223], v[12:15]
	v_mfma_f32_16x16x32_bf16 v[8:11], v[172:175], v[220:223], v[8:11]
	v_mfma_f32_16x16x32_bf16 v[60:63], v[168:171], v[200:203], v[60:63]
	v_mfma_f32_16x16x32_bf16 v[56:59], v[176:179], v[200:203], v[56:59]
	v_mfma_f32_16x16x32_bf16 v[44:47], v[168:171], v[208:211], v[44:47]
	v_mfma_f32_16x16x32_bf16 v[40:43], v[176:179], v[208:211], v[40:43]
	v_mfma_f32_16x16x32_bf16 v[28:31], v[168:171], v[216:219], v[28:31]
	v_mfma_f32_16x16x32_bf16 v[24:27], v[176:179], v[216:219], v[24:27]
	v_mfma_f32_16x16x32_bf16 v[12:15], v[168:171], v[224:227], v[12:15]
	v_mfma_f32_16x16x32_bf16 v[8:11], v[176:179], v[224:227], v[8:11]
	v_mfma_f32_16x16x32_bf16 v[52:55], v[180:183], v[196:199], v[52:55]
	v_mfma_f32_16x16x32_bf16 v[48:51], v[188:191], v[196:199], v[48:51]
	v_mfma_f32_16x16x32_bf16 v[36:39], v[180:183], v[204:207], v[36:39]
	v_mfma_f32_16x16x32_bf16 v[32:35], v[188:191], v[204:207], v[32:35]
	v_mfma_f32_16x16x32_bf16 v[20:23], v[180:183], v[212:215], v[20:23]
	v_mfma_f32_16x16x32_bf16 v[16:19], v[188:191], v[212:215], v[16:19]
	v_mfma_f32_16x16x32_bf16 v[4:7], v[180:183], v[220:223], v[4:7]
	v_mfma_f32_16x16x32_bf16 v[0:3], v[188:191], v[220:223], v[0:3]
	v_mfma_f32_16x16x32_bf16 v[52:55], v[184:187], v[200:203], v[52:55]
	v_mfma_f32_16x16x32_bf16 v[48:51], v[192:195], v[200:203], v[48:51]
	v_mfma_f32_16x16x32_bf16 v[36:39], v[184:187], v[208:211], v[36:39]
	v_mfma_f32_16x16x32_bf16 v[32:35], v[192:195], v[208:211], v[32:35]
	v_mfma_f32_16x16x32_bf16 v[20:23], v[184:187], v[216:219], v[20:23]
	v_mfma_f32_16x16x32_bf16 v[16:19], v[192:195], v[216:219], v[16:19]
	v_mfma_f32_16x16x32_bf16 v[4:7], v[184:187], v[224:227], v[4:7]
	v_mfma_f32_16x16x32_bf16 v[0:3], v[192:195], v[224:227], v[0:3]
	s_barrier
; #define PG8_STAGE(bufoff, gbase, voff) do { _Pragma("unroll") for (int _i = 0; _i < 2; ++_i) \
;         __builtin_amdgcn_global_load_lds((const unsigned*)((const char*)(gbase) + (voff)[_i]), (PG8_LAS unsigned*)(lds + (bufoff) + ldsw + _i * 8192), 16, 0, 0); } while (0)
; #define PG8_LDA(dst, b, h) do { _Pragma("unroll") for (int m = 0; m < 4; ++m) _Pragma("unroll") for (int k = 0; k < 2; ++k) dst[m][k] = *(const PG8_LAS bf16x8*)(lds + PG8_SA(b, h) + aoff + m * 2048 + k * 1024); } while (0)
; #define PG8_LDB(dst, b, h) do { _Pragma("unroll") for (int n = 0; n < 2; ++n) _Pragma("unroll") for (int k = 0; k < 2; ++k) dst[n][k] = *(const PG8_LAS bf16x8*)(lds + PG8_SB(b, h) + boff + n * 2048 + k * 1024); } while (0)
; #define PG8_MMA(ai, bj, At, Bt) do { __builtin_amdgcn_s_setprio(1); _Pragma("unroll") for (int m = 0; m < 4; ++m) _Pragma("unroll") for (int n = 0; n < 2; ++n) _Pragma("unroll") for (int k = 0; k < 2; ++k) \
;         acc[ai][bj][m][n] = __builtin_amdgcn_mfma_f32_16x16x32_bf16(Bt[n][k], At[m][k], acc[ai][bj][m][n], 0, 0, 0); __builtin_amdgcn_s_setprio(0); } while (0)
; #define PG8_WAIT_V(n) asm volatile("s_waitcnt vmcnt(" #n ")" ::: "memory")
; #define PG8_WAIT_L(n) asm volatile("s_waitcnt lgkmcnt(" #n ")" ::: "memory")
; #define PG8_BAR __builtin_amdgcn_s_barrier()
; #define PG8_SCHED __builtin_amdgcn_sched_barrier(0)
; template <class Epi, class Sched, bool ALIGN_EPI = false, bool SP2 = false>
; __device__ __forceinline__ void gemm_phase(PG8_LAS unsigned char* lds, const Gemm g, const Sched& S, const Epi& E, const int tid_arg) {
;     ...
;             PG8_LDB(B0, 1, 0); PG8_LDB(B1, 1, 1); PG8_SCHED; PG8_LDA(At, 1, 0); PG8_STAGE(PG8_SA(0, 1), a2 + hstep, voffA);
;             PG8_WAIT_V(8); PG8_WAIT_L(0); PG8_BAR; PG8_MMA(0, 0, At, B0); PG8_MMA(0, 1, At, B1); PG8_BAR; PG8_SCHED;
;             PG8_LDA(At, 1, 1); PG8_STAGE(PG8_SB(1, 0), b3, voffB); PG8_STAGE(PG8_SB(1, 1), b3 + hstep, voffB); PG8_STAGE(PG8_SA(1, 0), a3, voffA);
;             PG8_WAIT_V(8); PG8_WAIT_L(0); PG8_BAR; PG8_MMA(1, 0, At, B0); PG8_MMA(1, 1, At, B1); PG8_BAR; PG8_SCHED;
	s_setprio 1
	ds_read_b128 v[144:147], v159
	ds_read_b128 v[168:171], v160
	ds_read_b128 v[172:175], v161
	ds_read_b128 v[176:179], v162
	ds_read_b128 v[180:183], v163
	ds_read_b128 v[184:187], v164
	ds_read_b128 v[188:191], v165
	ds_read_b128 v[192:195], v166
	s_add_u32 s4, s24, 0xb0000
	s_addc_u32 s5, s25, 0
	s_mov_b32 m0, s35
	v_lshl_add_u64 v[236:237], s[4:5], 0, v[128:129]
	ds_read_b128 v[196:199], v150 offset:32768
	ds_read_b128 v[200:203], v150 offset:33792
	ds_read_b128 v[204:207], v150 offset:34816
	ds_read_b128 v[208:211], v150 offset:35840
	ds_read_b128 v[212:215], v150 offset:36864
	ds_read_b128 v[216:219], v150 offset:37888
	ds_read_b128 v[220:223], v150 offset:38912
	ds_read_b128 v[224:227], v150 offset:39936
	global_load_lds_dwordx4 v[236:237], off
	v_lshl_add_u64 v[236:237], s[4:5], 0, v[132:133]
	s_mov_b32 m0, s36
	s_nop 0
	global_load_lds_dwordx4 v[236:237], off
	s_waitcnt vmcnt(8)
	s_waitcnt lgkmcnt(0)
	s_setprio 0
	s_barrier
	v_mfma_f32_16x16x32_bf16 v[124:127], v[144:147], v[196:199], v[124:127]
	v_mfma_f32_16x16x32_bf16 v[120:123], v[172:175], v[196:199], v[120:123]
	v_mfma_f32_16x16x32_bf16 v[108:111], v[144:147], v[204:207], v[108:111]
	v_mfma_f32_16x16x32_bf16 v[104:107], v[172:175], v[204:207], v[104:107]
	v_mfma_f32_16x16x32_bf16 v[92:95], v[144:147], v[212:215], v[92:95]
	v_mfma_f32_16x16x32_bf16 v[88:91], v[172:175], v[212:215], v[88:91]
	v_mfma_f32_16x16x32_bf16 v[76:79], v[144:147], v[220:223], v[76:79]
	v_mfma_f32_16x16x32_bf16 v[72:75], v[172:175], v[220:223], v[72:75]
	v_mfma_f32_16x16x32_bf16 v[124:127], v[168:171], v[200:203], v[124:127]
	v_mfma_f32_16x16x32_bf16 v[120:123], v[176:179], v[200:203], v[120:123]
	v_mfma_f32_16x16x32_bf16 v[108:111], v[168:171], v[208:211], v[108:111]
	v_mfma_f32_16x16x32_bf16 v[104:107], v[176:179], v[208:211], v[104:107]
	v_mfma_f32_16x16x32_bf16 v[92:95], v[168:171], v[216:219], v[92:95]
	v_mfma_f32_16x16x32_bf16 v[88:91], v[176:179], v[216:219], v[88:91]
	v_mfma_f32_16x16x32_bf16 v[76:79], v[168:171], v[224:227], v[76:79]
	v_mfma_f32_16x16x32_bf16 v[72:75], v[176:179], v[224:227], v[72:75]
	v_mfma_f32_16x16x32_bf16 v[116:119], v[180:183], v[196:199], v[116:119]
	v_mfma_f32_16x16x32_bf16 v[112:115], v[188:191], v[196:199], v[112:115]
	v_mfma_f32_16x16x32_bf16 v[100:103], v[180:183], v[204:207], v[100:103]
	v_mfma_f32_16x16x32_bf16 v[96:99], v[188:191], v[204:207], v[96:99]
	v_mfma_f32_16x16x32_bf16 v[84:87], v[180:183], v[212:215], v[84:87]
	v_mfma_f32_16x16x32_bf16 v[80:83], v[188:191], v[212:215], v[80:83]
	v_mfma_f32_16x16x32_bf16 v[68:71], v[180:183], v[220:223], v[68:71]
	v_mfma_f32_16x16x32_bf16 v[64:67], v[188:191], v[220:223], v[64:67]
	v_mfma_f32_16x16x32_bf16 v[116:119], v[184:187], v[200:203], v[116:119]
	v_mfma_f32_16x16x32_bf16 v[112:115], v[192:195], v[200:203], v[112:115]
	v_mfma_f32_16x16x32_bf16 v[100:103], v[184:187], v[208:211], v[100:103]
	v_mfma_f32_16x16x32_bf16 v[96:99], v[192:195], v[208:211], v[96:99]
	v_mfma_f32_16x16x32_bf16 v[84:87], v[184:187], v[216:219], v[84:87]
	v_mfma_f32_16x16x32_bf16 v[80:83], v[192:195], v[216:219], v[80:83]
	v_mfma_f32_16x16x32_bf16 v[68:71], v[184:187], v[224:227], v[68:71]
	v_mfma_f32_16x16x32_bf16 v[64:67], v[192:195], v[224:227], v[64:67]
	s_barrier
	s_setprio 1
	s_mov_b32 m0, s40
	v_lshl_add_u64 v[228:229], v[228:229], 0, s[16:17]
	s_add_u32 s0, s0, 0xb0080
	ds_read_b128 v[196:199], v150 offset:49152
	ds_read_b128 v[200:203], v150 offset:50176
	ds_read_b128 v[204:207], v150 offset:51200
	ds_read_b128 v[208:211], v150 offset:52224
	ds_read_b128 v[212:215], v150 offset:53248
	ds_read_b128 v[216:219], v150 offset:54272
	ds_read_b128 v[220:223], v150 offset:55296
	ds_read_b128 v[224:227], v150 offset:56320
	global_load_lds_dwordx4 v[228:229], off
	v_lshl_add_u64 v[228:229], v[230:231], 0, s[16:17]
	s_mov_b32 m0, s41
	s_addc_u32 s1, s1, 0
	global_load_lds_dwordx4 v[228:229], off
	v_lshl_add_u64 v[228:229], s[0:1], 0, v[130:131]
	s_mov_b32 m0, s44
	s_nop 0
	global_load_lds_dwordx4 v[228:229], off
	v_lshl_add_u64 v[228:229], s[0:1], 0, v[134:135]
	s_mov_b32 m0, s45
	s_nop 0
	global_load_lds_dwordx4 v[228:229], off
	v_lshl_add_u64 v[228:229], v[232:233], 0, s[16:17]
	s_mov_b32 m0, s42
	s_nop 0
	global_load_lds_dwordx4 v[228:229], off
	v_lshl_add_u64 v[228:229], v[234:235], 0, s[16:17]
	s_mov_b32 m0, s43
	s_nop 0
	global_load_lds_dwordx4 v[228:229], off
	s_waitcnt vmcnt(8)
	s_waitcnt lgkmcnt(0)
	s_setprio 0
	s_barrier
	v_mfma_f32_16x16x32_bf16 v[60:63], v[144:147], v[196:199], v[60:63]
	v_mfma_f32_16x16x32_bf16 v[56:59], v[172:175], v[196:199], v[56:59]
	v_mfma_f32_16x16x32_bf16 v[44:47], v[144:147], v[204:207], v[44:47]
	v_mfma_f32_16x16x32_bf16 v[40:43], v[172:175], v[204:207], v[40:43]
	v_mfma_f32_16x16x32_bf16 v[28:31], v[144:147], v[212:215], v[28:31]
	v_mfma_f32_16x16x32_bf16 v[24:27], v[172:175], v[212:215], v[24:27]
	v_mfma_f32_16x16x32_bf16 v[12:15], v[144:147], v[220:223], v[12:15]
	v_mfma_f32_16x16x32_bf16 v[8:11], v[172:175], v[220:223], v[8:11]
	v_mfma_f32_16x16x32_bf16 v[60:63], v[168:171], v[200:203], v[60:63]
	v_mfma_f32_16x16x32_bf16 v[56:59], v[176:179], v[200:203], v[56:59]
	v_mfma_f32_16x16x32_bf16 v[44:47], v[168:171], v[208:211], v[44:47]
	v_mfma_f32_16x16x32_bf16 v[40:43], v[176:179], v[208:211], v[40:43]
	v_mfma_f32_16x16x32_bf16 v[28:31], v[168:171], v[216:219], v[28:31]
	v_mfma_f32_16x16x32_bf16 v[24:27], v[176:179], v[216:219], v[24:27]
	v_mfma_f32_16x16x32_bf16 v[12:15], v[168:171], v[224:227], v[12:15]
	v_mfma_f32_16x16x32_bf16 v[8:11], v[176:179], v[224:227], v[8:11]
	v_mfma_f32_16x16x32_bf16 v[52:55], v[180:183], v[196:199], v[52:55]
	v_mfma_f32_16x16x32_bf16 v[48:51], v[188:191], v[196:199], v[48:51]
	v_mfma_f32_16x16x32_bf16 v[36:39], v[180:183], v[204:207], v[36:39]
	v_mfma_f32_16x16x32_bf16 v[32:35], v[188:191], v[204:207], v[32:35]
	v_mfma_f32_16x16x32_bf16 v[20:23], v[180:183], v[212:215], v[20:23]
	v_mfma_f32_16x16x32_bf16 v[16:19], v[188:191], v[212:215], v[16:19]
	v_mfma_f32_16x16x32_bf16 v[4:7], v[180:183], v[220:223], v[4:7]
	v_mfma_f32_16x16x32_bf16 v[0:3], v[188:191], v[220:223], v[0:3]
	v_mfma_f32_16x16x32_bf16 v[52:55], v[184:187], v[200:203], v[52:55]
	v_mfma_f32_16x16x32_bf16 v[48:51], v[192:195], v[200:203], v[48:51]
	v_mfma_f32_16x16x32_bf16 v[36:39], v[184:187], v[208:211], v[36:39]
	v_mfma_f32_16x16x32_bf16 v[32:35], v[192:195], v[208:211], v[32:35]
	v_mfma_f32_16x16x32_bf16 v[20:23], v[184:187], v[216:219], v[20:23]
	v_mfma_f32_16x16x32_bf16 v[16:19], v[192:195], v[216:219], v[16:19]
	v_mfma_f32_16x16x32_bf16 v[4:7], v[184:187], v[224:227], v[4:7]
	v_mfma_f32_16x16x32_bf16 v[0:3], v[192:195], v[224:227], v[0:3]
	s_barrier
	s_setprio 1
	s_add_i32 s57, s57, 2
	s_add_u32 s55, s55, 0x100
	s_addc_u32 s56, s56, 0
	s_cmp_gt_u32 s57, 41
	s_mov_b64 s[4:5], s[22:23]
	s_cbranch_scc0 .LBB0_871
	s_setprio 0
	s_and_b64 vcc, exec, s[18:19]
	s_cbranch_vccz .LBB0_874
	s_barrier

; #define PG8_STAGE(bufoff, gbase, voff) do { _Pragma("unroll") for (int _i = 0; _i < 2; ++_i) \
;         __builtin_amdgcn_global_load_lds((const unsigned*)((const char*)(gbase) + (voff)[_i]), (PG8_LAS unsigned*)(lds + (bufoff) + ldsw + _i * 8192), 16, 0, 0); } while (0)
; #define PG8_LDA(dst, b, h) do { _Pragma("unroll") for (int m = 0; m < 4; ++m) _Pragma("unroll") for (int k = 0; k < 2; ++k) dst[m][k] = *(const PG8_LAS bf16x8*)(lds + PG8_SA(b, h) + aoff + m * 2048 + k * 1024); } while (0)
; #define PG8_LDB(dst, b, h) do { _Pragma("unroll") for (int n = 0; n < 2; ++n) _Pragma("unroll") for (int k = 0; k < 2; ++k) dst[n][k] = *(const PG8_LAS bf16x8*)(lds + PG8_SB(b, h) + boff + n * 2048 + k * 1024); } while (0)
; #define PG8_MMA(ai, bj, At, Bt) do { __builtin_amdgcn_s_setprio(1); _Pragma("unroll") for (int m = 0; m < 4; ++m) _Pragma("unroll") for (int n = 0; n < 2; ++n) _Pragma("unroll") for (int k = 0; k < 2; ++k) \
;         acc[ai][bj][m][n] = __builtin_amdgcn_mfma_f32_16x16x32_bf16(Bt[n][k], At[m][k], acc[ai][bj][m][n], 0, 0, 0); __builtin_amdgcn_s_setprio(0); } while (0)
; #define PG8_WAIT_V(n) asm volatile("s_waitcnt vmcnt(" #n ")" ::: "memory")
; #define PG8_WAIT_L(n) asm volatile("s_waitcnt lgkmcnt(" #n ")" ::: "memory")
; #define PG8_BAR __builtin_amdgcn_s_barrier()
; #define PG8_SCHED __builtin_amdgcn_sched_barrier(0)
; template <class Epi, class Sched, bool ALIGN_EPI = false, bool SP2 = false>
; __device__ __forceinline__ void gemm_phase(PG8_LAS unsigned char* lds, const Gemm g, const Sched& S, const Epi& E, const int tid_arg) {
;     ...
;             PG8_LDB(B0, 0, 0); PG8_LDB(B1, 0, 1); PG8_SCHED; PG8_LDA(At, 0, 0); PG8_STAGE(PG8_SA(1, 1), a1 + hstep, voffA);
;             PG8_WAIT_V(8); PG8_WAIT_L(0); PG8_BAR; PG8_MMA(0, 0, At, B0); PG8_MMA(0, 1, At, B1); PG8_BAR; PG8_SCHED;
;             PG8_LDA(At, 0, 1); PG8_STAGE(PG8_SB(0, 0), b2, voffB); PG8_STAGE(PG8_SB(0, 1), b2 + hstep, voffB); PG8_STAGE(PG8_SA(0, 0), a2, voffA);
;             PG8_WAIT_V(8); PG8_WAIT_L(0); PG8_BAR; PG8_MMA(1, 0, At, B0); PG8_MMA(1, 1, At, B1); PG8_BAR; PG8_SCHED;
.LBB0_965:
	ds_read_b128 v[170:173], v151
	ds_read_b128 v[174:177], v153
	ds_read_b128 v[178:181], v155
	ds_read_b128 v[182:185], v156
	ds_read_b128 v[186:189], v157
	ds_read_b128 v[190:193], v158
	ds_read_b128 v[194:197], v159
	ds_read_b128 v[198:201], v160
	s_add_u32 s0, s40, 0xfffc0080
	s_addc_u32 s1, s41, -1
	s_cmp_eq_u32 s72, 12
	s_cselect_b32 s43, s35, s1
	s_cselect_b32 s42, s68, s0
	s_cselect_b32 s1, s31, s71
	s_cselect_b32 s0, s69, s70
	s_mov_b32 m0, s60
	v_lshl_add_u64 v[234:235], s[40:41], 0, v[138:139]
	ds_read_b128 v[202:205], v149
	ds_read_b128 v[206:209], v149 offset:1024
	ds_read_b128 v[210:213], v149 offset:2048
	ds_read_b128 v[214:217], v149 offset:3072
	ds_read_b128 v[218:221], v149 offset:4096
	ds_read_b128 v[222:225], v149 offset:5120
	ds_read_b128 v[226:229], v149 offset:6144
	ds_read_b128 v[230:233], v149 offset:7168
	global_load_lds_dwordx4 v[234:235], off
	v_lshl_add_u64 v[234:235], s[40:41], 0, v[136:137]
	s_mov_b32 m0, s61
	s_nop 0
	global_load_lds_dwordx4 v[234:235], off
	s_waitcnt vmcnt(8)
	s_waitcnt lgkmcnt(0)
	s_setprio 0
	s_barrier
	v_mfma_f32_16x16x32_bf16 v[124:127], v[170:173], v[202:205], v[124:127]
	v_mfma_f32_16x16x32_bf16 v[120:123], v[178:181], v[202:205], v[120:123]
	v_mfma_f32_16x16x32_bf16 v[108:111], v[170:173], v[210:213], v[108:111]
	v_mfma_f32_16x16x32_bf16 v[104:107], v[178:181], v[210:213], v[104:107]
	v_mfma_f32_16x16x32_bf16 v[92:95], v[170:173], v[218:221], v[92:95]
	v_mfma_f32_16x16x32_bf16 v[88:91], v[178:181], v[218:221], v[88:91]
	v_mfma_f32_16x16x32_bf16 v[76:79], v[170:173], v[226:229], v[76:79]
	v_mfma_f32_16x16x32_bf16 v[72:75], v[178:181], v[226:229], v[72:75]
	v_mfma_f32_16x16x32_bf16 v[124:127], v[174:177], v[206:209], v[124:127]
	v_mfma_f32_16x16x32_bf16 v[120:123], v[182:185], v[206:209], v[120:123]
	v_mfma_f32_16x16x32_bf16 v[108:111], v[174:177], v[214:217], v[108:111]
	v_mfma_f32_16x16x32_bf16 v[104:107], v[182:185], v[214:217], v[104:107]
	v_mfma_f32_16x16x32_bf16 v[92:95], v[174:177], v[222:225], v[92:95]
	v_mfma_f32_16x16x32_bf16 v[88:91], v[182:185], v[222:225], v[88:91]
	v_mfma_f32_16x16x32_bf16 v[76:79], v[174:177], v[230:233], v[76:79]
	v_mfma_f32_16x16x32_bf16 v[72:75], v[182:185], v[230:233], v[72:75]
	v_mfma_f32_16x16x32_bf16 v[116:119], v[186:189], v[202:205], v[116:119]
	v_mfma_f32_16x16x32_bf16 v[112:115], v[194:197], v[202:205], v[112:115]
	v_mfma_f32_16x16x32_bf16 v[100:103], v[186:189], v[210:213], v[100:103]
	v_mfma_f32_16x16x32_bf16 v[96:99], v[194:197], v[210:213], v[96:99]
	v_mfma_f32_16x16x32_bf16 v[84:87], v[186:189], v[218:221], v[84:87]
	v_mfma_f32_16x16x32_bf16 v[80:83], v[194:197], v[218:221], v[80:83]
	v_mfma_f32_16x16x32_bf16 v[68:71], v[186:189], v[226:229], v[68:71]
	v_mfma_f32_16x16x32_bf16 v[64:67], v[194:197], v[226:229], v[64:67]
	v_mfma_f32_16x16x32_bf16 v[116:119], v[190:193], v[206:209], v[116:119]
	v_mfma_f32_16x16x32_bf16 v[112:115], v[198:201], v[206:209], v[112:115]
	v_mfma_f32_16x16x32_bf16 v[100:103], v[190:193], v[214:217], v[100:103]
	v_mfma_f32_16x16x32_bf16 v[96:99], v[198:201], v[214:217], v[96:99]
	v_mfma_f32_16x16x32_bf16 v[84:87], v[190:193], v[222:225], v[84:87]
	v_mfma_f32_16x16x32_bf16 v[80:83], v[198:201], v[222:225], v[80:83]
	v_mfma_f32_16x16x32_bf16 v[68:71], v[190:193], v[230:233], v[68:71]
	v_mfma_f32_16x16x32_bf16 v[64:67], v[198:201], v[230:233], v[64:67]
	s_barrier
	s_setprio 1
	s_mov_b32 m0, s5
	v_lshl_add_u64 v[234:235], s[0:1], 0, v[130:131]
	s_add_u32 s74, s0, 0x40000
	ds_read_b128 v[202:205], v149 offset:16384
	ds_read_b128 v[206:209], v149 offset:17408
	ds_read_b128 v[210:213], v149 offset:18432
	ds_read_b128 v[214:217], v149 offset:19456
	ds_read_b128 v[218:221], v149 offset:20480
	ds_read_b128 v[222:225], v149 offset:21504
	ds_read_b128 v[226:229], v149 offset:22528
	ds_read_b128 v[230:233], v149 offset:23552
	global_load_lds_dwordx4 v[234:235], off
	v_lshl_add_u64 v[236:237], s[0:1], 0, v[134:135]
	s_mov_b32 m0, s47
	s_addc_u32 s75, s1, 0
	global_load_lds_dwordx4 v[236:237], off
	v_lshl_add_u64 v[238:239], s[74:75], 0, v[130:131]
	s_mov_b32 m0, s48
	v_lshl_add_u64 v[240:241], s[42:43], 0, v[132:133]
	global_load_lds_dwordx4 v[238:239], off
	v_lshl_add_u64 v[238:239], s[74:75], 0, v[134:135]
	s_mov_b32 m0, s49
	s_nop 0
	global_load_lds_dwordx4 v[238:239], off
	v_lshl_add_u64 v[238:239], s[42:43], 0, v[128:129]
	s_mov_b32 m0, s46
	s_nop 0
	global_load_lds_dwordx4 v[238:239], off
	s_mov_b32 m0, s50
	s_nop 0
	global_load_lds_dwordx4 v[240:241], off
	s_waitcnt vmcnt(8)
	s_waitcnt lgkmcnt(0)
	s_setprio 0
	s_barrier
	v_mfma_f32_16x16x32_bf16 v[60:63], v[170:173], v[202:205], v[60:63]
	v_mfma_f32_16x16x32_bf16 v[56:59], v[178:181], v[202:205], v[56:59]
	v_mfma_f32_16x16x32_bf16 v[44:47], v[170:173], v[210:213], v[44:47]
	v_mfma_f32_16x16x32_bf16 v[40:43], v[178:181], v[210:213], v[40:43]
	v_mfma_f32_16x16x32_bf16 v[28:31], v[170:173], v[218:221], v[28:31]
	v_mfma_f32_16x16x32_bf16 v[24:27], v[178:181], v[218:221], v[24:27]
	v_mfma_f32_16x16x32_bf16 v[12:15], v[170:173], v[226:229], v[12:15]
	v_mfma_f32_16x16x32_bf16 v[8:11], v[178:181], v[226:229], v[8:11]
	v_mfma_f32_16x16x32_bf16 v[60:63], v[174:177], v[206:209], v[60:63]
	v_mfma_f32_16x16x32_bf16 v[56:59], v[182:185], v[206:209], v[56:59]
	v_mfma_f32_16x16x32_bf16 v[44:47], v[174:177], v[214:217], v[44:47]
	v_mfma_f32_16x16x32_bf16 v[40:43], v[182:185], v[214:217], v[40:43]
	v_mfma_f32_16x16x32_bf16 v[28:31], v[174:177], v[222:225], v[28:31]
	v_mfma_f32_16x16x32_bf16 v[24:27], v[182:185], v[222:225], v[24:27]
	v_mfma_f32_16x16x32_bf16 v[12:15], v[174:177], v[230:233], v[12:15]
	v_mfma_f32_16x16x32_bf16 v[8:11], v[182:185], v[230:233], v[8:11]
	v_mfma_f32_16x16x32_bf16 v[52:55], v[186:189], v[202:205], v[52:55]
	v_mfma_f32_16x16x32_bf16 v[48:51], v[194:197], v[202:205], v[48:51]
	v_mfma_f32_16x16x32_bf16 v[36:39], v[186:189], v[210:213], v[36:39]
	v_mfma_f32_16x16x32_bf16 v[32:35], v[194:197], v[210:213], v[32:35]
	v_mfma_f32_16x16x32_bf16 v[20:23], v[186:189], v[218:221], v[20:23]
	v_mfma_f32_16x16x32_bf16 v[16:19], v[194:197], v[218:221], v[16:19]
	v_mfma_f32_16x16x32_bf16 v[4:7], v[186:189], v[226:229], v[4:7]
	v_mfma_f32_16x16x32_bf16 v[0:3], v[194:197], v[226:229], v[0:3]
	v_mfma_f32_16x16x32_bf16 v[52:55], v[190:193], v[206:209], v[52:55]
	v_mfma_f32_16x16x32_bf16 v[48:51], v[198:201], v[206:209], v[48:51]
	v_mfma_f32_16x16x32_bf16 v[36:39], v[190:193], v[214:217], v[36:39]
	v_mfma_f32_16x16x32_bf16 v[32:35], v[198:201], v[214:217], v[32:35]
	v_mfma_f32_16x16x32_bf16 v[20:23], v[190:193], v[222:225], v[20:23]
	v_mfma_f32_16x16x32_bf16 v[16:19], v[198:201], v[222:225], v[16:19]
	v_mfma_f32_16x16x32_bf16 v[4:7], v[190:193], v[230:233], v[4:7]
	v_mfma_f32_16x16x32_bf16 v[0:3], v[198:201], v[230:233], v[0:3]
	s_barrier
; #define PG8_STAGE(bufoff, gbase, voff) do { _Pragma("unroll") for (int _i = 0; _i < 2; ++_i) \
;         __builtin_amdgcn_global_load_lds((const unsigned*)((const char*)(gbase) + (voff)[_i]), (PG8_LAS unsigned*)(lds + (bufoff) + ldsw + _i * 8192), 16, 0, 0); } while (0)
; #define PG8_LDA(dst, b, h) do { _Pragma("unroll") for (int m = 0; m < 4; ++m) _Pragma("unroll") for (int k = 0; k < 2; ++k) dst[m][k] = *(const PG8_LAS bf16x8*)(lds + PG8_SA(b, h) + aoff + m * 2048 + k * 1024); } while (0)
; #define PG8_LDB(dst, b, h) do { _Pragma("unroll") for (int n = 0; n < 2; ++n) _Pragma("unroll") for (int k = 0; k < 2; ++k) dst[n][k] = *(const PG8_LAS bf16x8*)(lds + PG8_SB(b, h) + boff + n * 2048 + k * 1024); } while (0)
; #define PG8_MMA(ai, bj, At, Bt) do { __builtin_amdgcn_s_setprio(1); _Pragma("unroll") for (int m = 0; m < 4; ++m) _Pragma("unroll") for (int n = 0; n < 2; ++n) _Pragma("unroll") for (int k = 0; k < 2; ++k) \
;         acc[ai][bj][m][n] = __builtin_amdgcn_mfma_f32_16x16x32_bf16(Bt[n][k], At[m][k], acc[ai][bj][m][n], 0, 0, 0); __builtin_amdgcn_s_setprio(0); } while (0)
; #define PG8_WAIT_V(n) asm volatile("s_waitcnt vmcnt(" #n ")" ::: "memory")
; #define PG8_WAIT_L(n) asm volatile("s_waitcnt lgkmcnt(" #n ")" ::: "memory")
; #define PG8_BAR __builtin_amdgcn_s_barrier()
; #define PG8_SCHED __builtin_amdgcn_sched_barrier(0)
; template <class Epi, class Sched, bool ALIGN_EPI = false, bool SP2 = false>
; __device__ __forceinline__ void gemm_phase(PG8_LAS unsigned char* lds, const Gemm g, const Sched& S, const Epi& E, const int tid_arg) {
;     ...
;             PG8_LDB(B0, 1, 0); PG8_LDB(B1, 1, 1); PG8_SCHED; PG8_LDA(At, 1, 0); PG8_STAGE(PG8_SA(0, 1), a2 + hstep, voffA);
;             PG8_WAIT_V(8); PG8_WAIT_L(0); PG8_BAR; PG8_MMA(0, 0, At, B0); PG8_MMA(0, 1, At, B1); PG8_BAR; PG8_SCHED;
;             PG8_LDA(At, 1, 1); PG8_STAGE(PG8_SB(1, 0), b3, voffB); PG8_STAGE(PG8_SB(1, 1), b3 + hstep, voffB); PG8_STAGE(PG8_SA(1, 0), a3, voffA);
;             PG8_WAIT_V(8); PG8_WAIT_L(0); PG8_BAR; PG8_MMA(1, 0, At, B0); PG8_MMA(1, 1, At, B1); PG8_BAR; PG8_SCHED;
	s_setprio 1
	ds_read_b128 v[170:173], v161
	ds_read_b128 v[174:177], v162
	ds_read_b128 v[178:181], v163
	ds_read_b128 v[182:185], v164
	ds_read_b128 v[186:189], v165
	ds_read_b128 v[190:193], v166
	ds_read_b128 v[194:197], v167
	ds_read_b128 v[198:201], v168
	s_add_u32 s42, s42, 0x40000
	s_addc_u32 s43, s43, 0
	s_mov_b32 m0, s51
	v_lshl_add_u64 v[242:243], s[42:43], 0, v[128:129]
	ds_read_b128 v[202:205], v149 offset:32768
	ds_read_b128 v[206:209], v149 offset:33792
	ds_read_b128 v[210:213], v149 offset:34816
	ds_read_b128 v[214:217], v149 offset:35840
	ds_read_b128 v[218:221], v149 offset:36864
	ds_read_b128 v[222:225], v149 offset:37888
	ds_read_b128 v[226:229], v149 offset:38912
	ds_read_b128 v[230:233], v149 offset:39936
	global_load_lds_dwordx4 v[242:243], off
	v_lshl_add_u64 v[242:243], s[42:43], 0, v[132:133]
	s_mov_b32 m0, s52
	s_nop 0
	global_load_lds_dwordx4 v[242:243], off
	s_waitcnt vmcnt(8)
	s_waitcnt lgkmcnt(0)
	s_setprio 0
	s_barrier
	v_mfma_f32_16x16x32_bf16 v[124:127], v[170:173], v[202:205], v[124:127]
	v_mfma_f32_16x16x32_bf16 v[120:123], v[178:181], v[202:205], v[120:123]
	v_mfma_f32_16x16x32_bf16 v[108:111], v[170:173], v[210:213], v[108:111]
	v_mfma_f32_16x16x32_bf16 v[104:107], v[178:181], v[210:213], v[104:107]
	v_mfma_f32_16x16x32_bf16 v[92:95], v[170:173], v[218:221], v[92:95]
	v_mfma_f32_16x16x32_bf16 v[88:91], v[178:181], v[218:221], v[88:91]
	v_mfma_f32_16x16x32_bf16 v[76:79], v[170:173], v[226:229], v[76:79]
	v_mfma_f32_16x16x32_bf16 v[72:75], v[178:181], v[226:229], v[72:75]
	v_mfma_f32_16x16x32_bf16 v[124:127], v[174:177], v[206:209], v[124:127]
	v_mfma_f32_16x16x32_bf16 v[120:123], v[182:185], v[206:209], v[120:123]
	v_mfma_f32_16x16x32_bf16 v[108:111], v[174:177], v[214:217], v[108:111]
	v_mfma_f32_16x16x32_bf16 v[104:107], v[182:185], v[214:217], v[104:107]
	v_mfma_f32_16x16x32_bf16 v[92:95], v[174:177], v[222:225], v[92:95]
	v_mfma_f32_16x16x32_bf16 v[88:91], v[182:185], v[222:225], v[88:91]
	v_mfma_f32_16x16x32_bf16 v[76:79], v[174:177], v[230:233], v[76:79]
	v_mfma_f32_16x16x32_bf16 v[72:75], v[182:185], v[230:233], v[72:75]
	v_mfma_f32_16x16x32_bf16 v[116:119], v[186:189], v[202:205], v[116:119]
	v_mfma_f32_16x16x32_bf16 v[112:115], v[194:197], v[202:205], v[112:115]
	v_mfma_f32_16x16x32_bf16 v[100:103], v[186:189], v[210:213], v[100:103]
	v_mfma_f32_16x16x32_bf16 v[96:99], v[194:197], v[210:213], v[96:99]
	v_mfma_f32_16x16x32_bf16 v[84:87], v[186:189], v[218:221], v[84:87]
	v_mfma_f32_16x16x32_bf16 v[80:83], v[194:197], v[218:221], v[80:83]
	v_mfma_f32_16x16x32_bf16 v[68:71], v[186:189], v[226:229], v[68:71]
	v_mfma_f32_16x16x32_bf16 v[64:67], v[194:197], v[226:229], v[64:67]
	v_mfma_f32_16x16x32_bf16 v[116:119], v[190:193], v[206:209], v[116:119]
	v_mfma_f32_16x16x32_bf16 v[112:115], v[198:201], v[206:209], v[112:115]
	v_mfma_f32_16x16x32_bf16 v[100:103], v[190:193], v[214:217], v[100:103]
	v_mfma_f32_16x16x32_bf16 v[96:99], v[198:201], v[214:217], v[96:99]
	v_mfma_f32_16x16x32_bf16 v[84:87], v[190:193], v[222:225], v[84:87]
	v_mfma_f32_16x16x32_bf16 v[80:83], v[198:201], v[222:225], v[80:83]
	v_mfma_f32_16x16x32_bf16 v[68:71], v[190:193], v[230:233], v[68:71]
	v_mfma_f32_16x16x32_bf16 v[64:67], v[198:201], v[230:233], v[64:67]
	s_barrier
	s_setprio 1
	s_mov_b32 m0, s54
	v_lshl_add_u64 v[234:235], v[234:235], 0, s[12:13]
	s_add_u32 s0, s0, 0x40080
	ds_read_b128 v[202:205], v149 offset:49152
	ds_read_b128 v[206:209], v149 offset:50176
	ds_read_b128 v[210:213], v149 offset:51200
	ds_read_b128 v[214:217], v149 offset:52224
	ds_read_b128 v[218:221], v149 offset:53248
	ds_read_b128 v[222:225], v149 offset:54272
	ds_read_b128 v[226:229], v149 offset:55296
	ds_read_b128 v[230:233], v149 offset:56320
	global_load_lds_dwordx4 v[234:235], off
	v_lshl_add_u64 v[234:235], v[236:237], 0, s[12:13]
	s_mov_b32 m0, s55
	s_addc_u32 s1, s1, 0
	global_load_lds_dwordx4 v[234:235], off
	v_lshl_add_u64 v[234:235], s[0:1], 0, v[130:131]
	s_mov_b32 m0, s58
	s_nop 0
	global_load_lds_dwordx4 v[234:235], off
	v_lshl_add_u64 v[234:235], s[0:1], 0, v[134:135]
	s_mov_b32 m0, s59
	s_nop 0
	global_load_lds_dwordx4 v[234:235], off
	v_lshl_add_u64 v[234:235], v[238:239], 0, s[12:13]
	s_mov_b32 m0, s56
	s_nop 0
	global_load_lds_dwordx4 v[234:235], off
	v_lshl_add_u64 v[234:235], v[240:241], 0, s[12:13]
	s_mov_b32 m0, s57
	s_nop 0
	global_load_lds_dwordx4 v[234:235], off
	s_waitcnt vmcnt(8)
	s_waitcnt lgkmcnt(0)
	s_setprio 0
	s_barrier
	v_mfma_f32_16x16x32_bf16 v[60:63], v[170:173], v[202:205], v[60:63]
	v_mfma_f32_16x16x32_bf16 v[56:59], v[178:181], v[202:205], v[56:59]
	v_mfma_f32_16x16x32_bf16 v[44:47], v[170:173], v[210:213], v[44:47]
	v_mfma_f32_16x16x32_bf16 v[40:43], v[178:181], v[210:213], v[40:43]
	v_mfma_f32_16x16x32_bf16 v[28:31], v[170:173], v[218:221], v[28:31]
	v_mfma_f32_16x16x32_bf16 v[24:27], v[178:181], v[218:221], v[24:27]
	v_mfma_f32_16x16x32_bf16 v[12:15], v[170:173], v[226:229], v[12:15]
	v_mfma_f32_16x16x32_bf16 v[8:11], v[178:181], v[226:229], v[8:11]
	v_mfma_f32_16x16x32_bf16 v[60:63], v[174:177], v[206:209], v[60:63]
	v_mfma_f32_16x16x32_bf16 v[56:59], v[182:185], v[206:209], v[56:59]
	v_mfma_f32_16x16x32_bf16 v[44:47], v[174:177], v[214:217], v[44:47]
	v_mfma_f32_16x16x32_bf16 v[40:43], v[182:185], v[214:217], v[40:43]
	v_mfma_f32_16x16x32_bf16 v[28:31], v[174:177], v[222:225], v[28:31]
	v_mfma_f32_16x16x32_bf16 v[24:27], v[182:185], v[222:225], v[24:27]
	v_mfma_f32_16x16x32_bf16 v[12:15], v[174:177], v[230:233], v[12:15]
	v_mfma_f32_16x16x32_bf16 v[8:11], v[182:185], v[230:233], v[8:11]
	v_mfma_f32_16x16x32_bf16 v[52:55], v[186:189], v[202:205], v[52:55]
	v_mfma_f32_16x16x32_bf16 v[48:51], v[194:197], v[202:205], v[48:51]
	v_mfma_f32_16x16x32_bf16 v[36:39], v[186:189], v[210:213], v[36:39]
	v_mfma_f32_16x16x32_bf16 v[32:35], v[194:197], v[210:213], v[32:35]
	v_mfma_f32_16x16x32_bf16 v[20:23], v[186:189], v[218:221], v[20:23]
	v_mfma_f32_16x16x32_bf16 v[16:19], v[194:197], v[218:221], v[16:19]
	v_mfma_f32_16x16x32_bf16 v[4:7], v[186:189], v[226:229], v[4:7]
	v_mfma_f32_16x16x32_bf16 v[0:3], v[194:197], v[226:229], v[0:3]
	v_mfma_f32_16x16x32_bf16 v[52:55], v[190:193], v[206:209], v[52:55]
	v_mfma_f32_16x16x32_bf16 v[48:51], v[198:201], v[206:209], v[48:51]
	v_mfma_f32_16x16x32_bf16 v[36:39], v[190:193], v[214:217], v[36:39]
	v_mfma_f32_16x16x32_bf16 v[32:35], v[198:201], v[214:217], v[32:35]
	v_mfma_f32_16x16x32_bf16 v[20:23], v[190:193], v[222:225], v[20:23]
	v_mfma_f32_16x16x32_bf16 v[16:19], v[198:201], v[222:225], v[16:19]
	v_mfma_f32_16x16x32_bf16 v[4:7], v[190:193], v[230:233], v[4:7]
	v_mfma_f32_16x16x32_bf16 v[0:3], v[198:201], v[230:233], v[0:3]
	s_barrier
	s_setprio 1
	s_add_i32 s72, s72, 2
	s_add_u32 s70, s70, 0x100
	s_addc_u32 s71, s71, 0
	s_add_u32 s40, s40, 0x100
	s_addc_u32 s41, s41, 0
	s_cmp_gt_u32 s72, 13
	s_cbranch_scc0 .LBB0_965
	s_setprio 0
	s_and_b64 vcc, exec, s[14:15]
	s_cbranch_vccz .LBB0_968
	s_barrier

; #define PG8_STAGE(bufoff, gbase, voff) do { _Pragma("unroll") for (int _i = 0; _i < 2; ++_i) \
;         __builtin_amdgcn_global_load_lds((const unsigned*)((const char*)(gbase) + (voff)[_i]), (PG8_LAS unsigned*)(lds + (bufoff) + ldsw + _i * 8192), 16, 0, 0); } while (0)
; #define PG8_LDA(dst, b, h) do { _Pragma("unroll") for (int m = 0; m < 4; ++m) _Pragma("unroll") for (int k = 0; k < 2; ++k) dst[m][k] = *(const PG8_LAS bf16x8*)(lds + PG8_SA(b, h) + aoff + m * 2048 + k * 1024); } while (0)
; #define PG8_LDB(dst, b, h) do { _Pragma("unroll") for (int n = 0; n < 2; ++n) _Pragma("unroll") for (int k = 0; k < 2; ++k) dst[n][k] = *(const PG8_LAS bf16x8*)(lds + PG8_SB(b, h) + boff + n * 2048 + k * 1024); } while (0)
; #define PG8_MMA(ai, bj, At, Bt) do { __builtin_amdgcn_s_setprio(1); _Pragma("unroll") for (int m = 0; m < 4; ++m) _Pragma("unroll") for (int n = 0; n < 2; ++n) _Pragma("unroll") for (int k = 0; k < 2; ++k) \
;         acc[ai][bj][m][n] = __builtin_amdgcn_mfma_f32_16x16x32_bf16(Bt[n][k], At[m][k], acc[ai][bj][m][n], 0, 0, 0); __builtin_amdgcn_s_setprio(0); } while (0)
; #define PG8_WAIT_V(n) asm volatile("s_waitcnt vmcnt(" #n ")" ::: "memory")
; #define PG8_WAIT_L(n) asm volatile("s_waitcnt lgkmcnt(" #n ")" ::: "memory")
; #define PG8_BAR __builtin_amdgcn_s_barrier()
; #define PG8_SCHED __builtin_amdgcn_sched_barrier(0)
; template <class Epi, class Sched, bool ALIGN_EPI = false, bool SP2 = false>
; __device__ __forceinline__ void gemm_phase(PG8_LAS unsigned char* lds, const Gemm g, const Sched& S, const Epi& E, const int tid_arg) {
;     ...
;             PG8_LDB(B0, 0, 0); PG8_LDB(B1, 0, 1); PG8_SCHED; PG8_LDA(At, 0, 0); PG8_STAGE(PG8_SA(1, 1), a1 + hstep, voffA);
;             PG8_WAIT_V(8); PG8_WAIT_L(0); PG8_BAR; PG8_MMA(0, 0, At, B0); PG8_MMA(0, 1, At, B1); PG8_BAR; PG8_SCHED;
;             PG8_LDA(At, 0, 1); PG8_STAGE(PG8_SB(0, 0), b2, voffB); PG8_STAGE(PG8_SB(0, 1), b2 + hstep, voffB); PG8_STAGE(PG8_SA(0, 0), a2, voffA);
;             PG8_WAIT_V(8); PG8_WAIT_L(0); PG8_BAR; PG8_MMA(1, 0, At, B0); PG8_MMA(1, 1, At, B1); PG8_BAR; PG8_SCHED;
.LBB0_1046:
	ds_read_b128 v[144:147], v151
	ds_read_b128 v[168:171], v152
	ds_read_b128 v[172:175], v153
	ds_read_b128 v[176:179], v154
	ds_read_b128 v[180:183], v155
	ds_read_b128 v[184:187], v156
	ds_read_b128 v[188:191], v157
	ds_read_b128 v[192:195], v158
	s_add_i32 s30, s0, 2
	s_add_u32 s31, s4, 0x80
	s_addc_u32 s1, s5, 0
	s_cmp_eq_u32 s52, s0
	s_cselect_b32 s0, s14, s31
	s_cselect_b32 s1, s15, s1
	s_cselect_b32 s63, s29, s61
	s_cselect_b32 s62, s28, s60
	s_mov_b32 m0, s53
	v_lshl_add_u64 v[228:229], s[4:5], 0, v[138:139]
	ds_read_b128 v[196:199], v150
	ds_read_b128 v[200:203], v150 offset:1024
	ds_read_b128 v[204:207], v150 offset:2048
	ds_read_b128 v[208:211], v150 offset:3072
	ds_read_b128 v[212:215], v150 offset:4096
	ds_read_b128 v[216:219], v150 offset:5120
	ds_read_b128 v[220:223], v150 offset:6144
	ds_read_b128 v[224:227], v150 offset:7168
	global_load_lds_dwordx4 v[228:229], off
	v_lshl_add_u64 v[228:229], s[4:5], 0, v[136:137]
	s_mov_b32 m0, s54
	s_nop 0
	global_load_lds_dwordx4 v[228:229], off
	s_waitcnt vmcnt(8)
	s_waitcnt lgkmcnt(0)
	s_setprio 0
	s_barrier
	v_mfma_f32_16x16x32_bf16 v[124:127], v[144:147], v[196:199], v[124:127]
	v_mfma_f32_16x16x32_bf16 v[120:123], v[172:175], v[196:199], v[120:123]
	v_mfma_f32_16x16x32_bf16 v[108:111], v[144:147], v[204:207], v[108:111]
	v_mfma_f32_16x16x32_bf16 v[104:107], v[172:175], v[204:207], v[104:107]
	v_mfma_f32_16x16x32_bf16 v[92:95], v[144:147], v[212:215], v[92:95]
	v_mfma_f32_16x16x32_bf16 v[88:91], v[172:175], v[212:215], v[88:91]
	v_mfma_f32_16x16x32_bf16 v[76:79], v[144:147], v[220:223], v[76:79]
	v_mfma_f32_16x16x32_bf16 v[72:75], v[172:175], v[220:223], v[72:75]
	v_mfma_f32_16x16x32_bf16 v[124:127], v[168:171], v[200:203], v[124:127]
	v_mfma_f32_16x16x32_bf16 v[120:123], v[176:179], v[200:203], v[120:123]
	v_mfma_f32_16x16x32_bf16 v[108:111], v[168:171], v[208:211], v[108:111]
	v_mfma_f32_16x16x32_bf16 v[104:107], v[176:179], v[208:211], v[104:107]
	v_mfma_f32_16x16x32_bf16 v[92:95], v[168:171], v[216:219], v[92:95]
	v_mfma_f32_16x16x32_bf16 v[88:91], v[176:179], v[216:219], v[88:91]
	v_mfma_f32_16x16x32_bf16 v[76:79], v[168:171], v[224:227], v[76:79]
	v_mfma_f32_16x16x32_bf16 v[72:75], v[176:179], v[224:227], v[72:75]
	v_mfma_f32_16x16x32_bf16 v[116:119], v[180:183], v[196:199], v[116:119]
	v_mfma_f32_16x16x32_bf16 v[112:115], v[188:191], v[196:199], v[112:115]
	v_mfma_f32_16x16x32_bf16 v[100:103], v[180:183], v[204:207], v[100:103]
	v_mfma_f32_16x16x32_bf16 v[96:99], v[188:191], v[204:207], v[96:99]
	v_mfma_f32_16x16x32_bf16 v[84:87], v[180:183], v[212:215], v[84:87]
	v_mfma_f32_16x16x32_bf16 v[80:83], v[188:191], v[212:215], v[80:83]
	v_mfma_f32_16x16x32_bf16 v[68:71], v[180:183], v[220:223], v[68:71]
	v_mfma_f32_16x16x32_bf16 v[64:67], v[188:191], v[220:223], v[64:67]
	v_mfma_f32_16x16x32_bf16 v[116:119], v[184:187], v[200:203], v[116:119]
	v_mfma_f32_16x16x32_bf16 v[112:115], v[192:195], v[200:203], v[112:115]
	v_mfma_f32_16x16x32_bf16 v[100:103], v[184:187], v[208:211], v[100:103]
	v_mfma_f32_16x16x32_bf16 v[96:99], v[192:195], v[208:211], v[96:99]
	v_mfma_f32_16x16x32_bf16 v[84:87], v[184:187], v[216:219], v[84:87]
	v_mfma_f32_16x16x32_bf16 v[80:83], v[192:195], v[216:219], v[80:83]
	v_mfma_f32_16x16x32_bf16 v[68:71], v[184:187], v[224:227], v[68:71]
	v_mfma_f32_16x16x32_bf16 v[64:67], v[192:195], v[224:227], v[64:67]
	s_barrier
	s_setprio 1
	s_mov_b32 m0, s37
	v_lshl_add_u64 v[228:229], s[62:63], 0, v[130:131]
	v_lshl_add_u64 v[230:231], s[62:63], 0, v[134:135]
	s_add_u32 s62, s62, s6
	ds_read_b128 v[196:199], v150 offset:16384
	ds_read_b128 v[200:203], v150 offset:17408
	ds_read_b128 v[204:207], v150 offset:18432
	ds_read_b128 v[208:211], v150 offset:19456
	ds_read_b128 v[212:215], v150 offset:20480
	ds_read_b128 v[216:219], v150 offset:21504
	ds_read_b128 v[220:223], v150 offset:22528
	ds_read_b128 v[224:227], v150 offset:23552
	global_load_lds_dwordx4 v[228:229], off
	s_mov_b32 m0, s38
	s_addc_u32 s63, s63, s7
	global_load_lds_dwordx4 v[230:231], off
	v_lshl_add_u64 v[232:233], s[62:63], 0, v[130:131]
	s_mov_b32 m0, s39
	v_lshl_add_u64 v[234:235], s[62:63], 0, v[134:135]
	global_load_lds_dwordx4 v[232:233], off
	s_mov_b32 m0, s40
	v_lshl_add_u64 v[236:237], s[0:1], 0, v[128:129]
	global_load_lds_dwordx4 v[234:235], off
	s_mov_b32 m0, s36
	v_lshl_add_u64 v[238:239], s[0:1], 0, v[132:133]
	global_load_lds_dwordx4 v[236:237], off
	s_mov_b32 m0, s41
	s_nop 0
	global_load_lds_dwordx4 v[238:239], off
	s_waitcnt vmcnt(8)
	s_waitcnt lgkmcnt(0)
	s_setprio 0
	s_barrier
	v_mfma_f32_16x16x32_bf16 v[60:63], v[144:147], v[196:199], v[60:63]
	v_mfma_f32_16x16x32_bf16 v[56:59], v[172:175], v[196:199], v[56:59]
	v_mfma_f32_16x16x32_bf16 v[44:47], v[144:147], v[204:207], v[44:47]
	v_mfma_f32_16x16x32_bf16 v[40:43], v[172:175], v[204:207], v[40:43]
	v_mfma_f32_16x16x32_bf16 v[28:31], v[144:147], v[212:215], v[28:31]
	v_mfma_f32_16x16x32_bf16 v[24:27], v[172:175], v[212:215], v[24:27]
	v_mfma_f32_16x16x32_bf16 v[12:15], v[144:147], v[220:223], v[12:15]
	v_mfma_f32_16x16x32_bf16 v[8:11], v[172:175], v[220:223], v[8:11]
	v_mfma_f32_16x16x32_bf16 v[60:63], v[168:171], v[200:203], v[60:63]
	v_mfma_f32_16x16x32_bf16 v[56:59], v[176:179], v[200:203], v[56:59]
	v_mfma_f32_16x16x32_bf16 v[44:47], v[168:171], v[208:211], v[44:47]
	v_mfma_f32_16x16x32_bf16 v[40:43], v[176:179], v[208:211], v[40:43]
	v_mfma_f32_16x16x32_bf16 v[28:31], v[168:171], v[216:219], v[28:31]
	v_mfma_f32_16x16x32_bf16 v[24:27], v[176:179], v[216:219], v[24:27]
	v_mfma_f32_16x16x32_bf16 v[12:15], v[168:171], v[224:227], v[12:15]
	v_mfma_f32_16x16x32_bf16 v[8:11], v[176:179], v[224:227], v[8:11]
	v_mfma_f32_16x16x32_bf16 v[52:55], v[180:183], v[196:199], v[52:55]
	v_mfma_f32_16x16x32_bf16 v[48:51], v[188:191], v[196:199], v[48:51]
	v_mfma_f32_16x16x32_bf16 v[36:39], v[180:183], v[204:207], v[36:39]
	v_mfma_f32_16x16x32_bf16 v[32:35], v[188:191], v[204:207], v[32:35]
	v_mfma_f32_16x16x32_bf16 v[20:23], v[180:183], v[212:215], v[20:23]
	v_mfma_f32_16x16x32_bf16 v[16:19], v[188:191], v[212:215], v[16:19]
	v_mfma_f32_16x16x32_bf16 v[4:7], v[180:183], v[220:223], v[4:7]
	v_mfma_f32_16x16x32_bf16 v[0:3], v[188:191], v[220:223], v[0:3]
	v_mfma_f32_16x16x32_bf16 v[52:55], v[184:187], v[200:203], v[52:55]
	v_mfma_f32_16x16x32_bf16 v[48:51], v[192:195], v[200:203], v[48:51]
	v_mfma_f32_16x16x32_bf16 v[36:39], v[184:187], v[208:211], v[36:39]
	v_mfma_f32_16x16x32_bf16 v[32:35], v[192:195], v[208:211], v[32:35]
	v_mfma_f32_16x16x32_bf16 v[20:23], v[184:187], v[216:219], v[20:23]
	v_mfma_f32_16x16x32_bf16 v[16:19], v[192:195], v[216:219], v[16:19]
	v_mfma_f32_16x16x32_bf16 v[4:7], v[184:187], v[224:227], v[4:7]
	v_mfma_f32_16x16x32_bf16 v[0:3], v[192:195], v[224:227], v[0:3]
	s_barrier
; #define PG8_STAGE(bufoff, gbase, voff) do { _Pragma("unroll") for (int _i = 0; _i < 2; ++_i) \
;         __builtin_amdgcn_global_load_lds((const unsigned*)((const char*)(gbase) + (voff)[_i]), (PG8_LAS unsigned*)(lds + (bufoff) + ldsw + _i * 8192), 16, 0, 0); } while (0)
; #define PG8_LDA(dst, b, h) do { _Pragma("unroll") for (int m = 0; m < 4; ++m) _Pragma("unroll") for (int k = 0; k < 2; ++k) dst[m][k] = *(const PG8_LAS bf16x8*)(lds + PG8_SA(b, h) + aoff + m * 2048 + k * 1024); } while (0)
; #define PG8_WAIT_V(n) asm volatile("s_waitcnt vmcnt(" #n ")" ::: "memory")
; #define PG8_WAIT_L(n) asm volatile("s_waitcnt lgkmcnt(" #n ")" ::: "memory")
; #define PG8_BAR __builtin_amdgcn_s_barrier()
; template <class Epi, class Sched, bool ALIGN_EPI = false, bool SP2 = false>
; __device__ __forceinline__ void gemm_phase(PG8_LAS unsigned char* lds, const Gemm g, const Sched& S, const Epi& E, const int tid_arg) {
;     ...
;         for (int t = 0; t < nt; t += 2) {
;             const bool last = (t == nt - 2);
;             const char* a1 = cA + (size_t)(t + 1) * kstep;
;             const char* a2 = last ? nA : cA + (size_t)(t + 2) * kstep; const char* b2 = last ? nB : cB + (size_t)(t + 2) * kstep;
;             const char* a3 = a2 + kstep; const char* b3 = b2 + kstep;
;             if (last && has_next) S.a_ready(nxt);
;             if constexpr (SP2) {
;             PG8_LDB(B0, 0, 0); PG8_LDB(B1, 0, 1); PG8_SCHED; PG8_LDA(At, 0, 0); PG8_STAGE(PG8_SA(1, 1), a1 + hstep, voffA);
;             PG8_WAIT_V(8); PG8_WAIT_L(0); PG8_BAR; PG8_MMA(0, 0, At, B0); PG8_MMA(0, 1, At, B1); PG8_BAR; PG8_SCHED;
;             PG8_LDA(At, 0, 1); PG8_STAGE(PG8_SB(0, 0), b2, voffB); PG8_STAGE(PG8_SB(0, 1), b2 + hstep, voffB); PG8_STAGE(PG8_SA(0, 0), a2, voffA);
;             PG8_WAIT_V(8); PG8_WAIT_L(0); PG8_BAR; PG8_MMA(1, 0, At, B0); PG8_MMA(1, 1, At, B1); PG8_BAR; PG8_SCHED;
;             PG8_LDB(B0, 1, 0); PG8_LDB(B1, 1, 1); PG8_SCHED; PG8_LDA(At, 1, 0); PG8_STAGE(PG8_SA(0, 1), a2 + hstep, voffA);
;             PG8_WAIT_V(8); PG8_WAIT_L(0); PG8_BAR; PG8_MMA(0, 0, At, B0); PG8_MMA(0, 1, At, B1); PG8_BAR; PG8_SCHED;
;             PG8_LDA(At, 1, 1); PG8_STAGE(PG8_SB(1, 0), b3, voffB); PG8_STAGE(PG8_SB(1, 1), b3 + hstep, voffB); PG8_STAGE(PG8_SA(1, 0), a3, voffA);
;             PG8_WAIT_V(8); PG8_WAIT_L(0); PG8_BAR; PG8_MMA(1, 0, At, B0); PG8_MMA(1, 1, At, B1); PG8_BAR; PG8_SCHED;
	s_setprio 1
	ds_read_b128 v[144:147], v159
	ds_read_b128 v[168:171], v160
	ds_read_b128 v[172:175], v161
	ds_read_b128 v[176:179], v162
	ds_read_b128 v[180:183], v163
	ds_read_b128 v[184:187], v164
	ds_read_b128 v[188:191], v165
	ds_read_b128 v[192:195], v166
	s_add_u32 s0, s0, s6
	s_addc_u32 s1, s1, s7
	s_mov_b32 m0, s42
	v_lshl_add_u64 v[240:241], s[0:1], 0, v[128:129]
	ds_read_b128 v[196:199], v150 offset:32768
	ds_read_b128 v[200:203], v150 offset:33792
	ds_read_b128 v[204:207], v150 offset:34816
	ds_read_b128 v[208:211], v150 offset:35840
	ds_read_b128 v[212:215], v150 offset:36864
	ds_read_b128 v[216:219], v150 offset:37888
	ds_read_b128 v[220:223], v150 offset:38912
	ds_read_b128 v[224:227], v150 offset:39936
	global_load_lds_dwordx4 v[240:241], off
	v_lshl_add_u64 v[240:241], s[0:1], 0, v[132:133]
	s_mov_b32 m0, s43
	s_nop 0
	global_load_lds_dwordx4 v[240:241], off
	s_waitcnt vmcnt(8)
	s_waitcnt lgkmcnt(0)
	s_setprio 0
	s_barrier
	v_mfma_f32_16x16x32_bf16 v[124:127], v[144:147], v[196:199], v[124:127]
	v_mfma_f32_16x16x32_bf16 v[120:123], v[172:175], v[196:199], v[120:123]
	v_mfma_f32_16x16x32_bf16 v[108:111], v[144:147], v[204:207], v[108:111]
	v_mfma_f32_16x16x32_bf16 v[104:107], v[172:175], v[204:207], v[104:107]
	v_mfma_f32_16x16x32_bf16 v[92:95], v[144:147], v[212:215], v[92:95]
	v_mfma_f32_16x16x32_bf16 v[88:91], v[172:175], v[212:215], v[88:91]
	v_mfma_f32_16x16x32_bf16 v[76:79], v[144:147], v[220:223], v[76:79]
	v_mfma_f32_16x16x32_bf16 v[72:75], v[172:175], v[220:223], v[72:75]
	v_mfma_f32_16x16x32_bf16 v[124:127], v[168:171], v[200:203], v[124:127]
	v_mfma_f32_16x16x32_bf16 v[120:123], v[176:179], v[200:203], v[120:123]
	v_mfma_f32_16x16x32_bf16 v[108:111], v[168:171], v[208:211], v[108:111]
	v_mfma_f32_16x16x32_bf16 v[104:107], v[176:179], v[208:211], v[104:107]
	v_mfma_f32_16x16x32_bf16 v[92:95], v[168:171], v[216:219], v[92:95]
	v_mfma_f32_16x16x32_bf16 v[88:91], v[176:179], v[216:219], v[88:91]
	v_mfma_f32_16x16x32_bf16 v[76:79], v[168:171], v[224:227], v[76:79]
	v_mfma_f32_16x16x32_bf16 v[72:75], v[176:179], v[224:227], v[72:75]
	v_mfma_f32_16x16x32_bf16 v[116:119], v[180:183], v[196:199], v[116:119]
	v_mfma_f32_16x16x32_bf16 v[112:115], v[188:191], v[196:199], v[112:115]
	v_mfma_f32_16x16x32_bf16 v[100:103], v[180:183], v[204:207], v[100:103]
	v_mfma_f32_16x16x32_bf16 v[96:99], v[188:191], v[204:207], v[96:99]
	v_mfma_f32_16x16x32_bf16 v[84:87], v[180:183], v[212:215], v[84:87]
	v_mfma_f32_16x16x32_bf16 v[80:83], v[188:191], v[212:215], v[80:83]
	v_mfma_f32_16x16x32_bf16 v[68:71], v[180:183], v[220:223], v[68:71]
	v_mfma_f32_16x16x32_bf16 v[64:67], v[188:191], v[220:223], v[64:67]
	v_mfma_f32_16x16x32_bf16 v[116:119], v[184:187], v[200:203], v[116:119]
	v_mfma_f32_16x16x32_bf16 v[112:115], v[192:195], v[200:203], v[112:115]
	v_mfma_f32_16x16x32_bf16 v[100:103], v[184:187], v[208:211], v[100:103]
	v_mfma_f32_16x16x32_bf16 v[96:99], v[192:195], v[208:211], v[96:99]
	v_mfma_f32_16x16x32_bf16 v[84:87], v[184:187], v[216:219], v[84:87]
	v_mfma_f32_16x16x32_bf16 v[80:83], v[192:195], v[216:219], v[80:83]
	v_mfma_f32_16x16x32_bf16 v[68:71], v[184:187], v[224:227], v[68:71]
	v_mfma_f32_16x16x32_bf16 v[64:67], v[192:195], v[224:227], v[64:67]
	s_barrier
	s_setprio 1
	s_mov_b32 m0, s44
	v_lshl_add_u64 v[228:229], v[228:229], 0, s[22:23]
	ds_read_b128 v[196:199], v150 offset:49152
	ds_read_b128 v[200:203], v150 offset:50176
	ds_read_b128 v[204:207], v150 offset:51200
	ds_read_b128 v[208:211], v150 offset:52224
	ds_read_b128 v[212:215], v150 offset:53248
	ds_read_b128 v[216:219], v150 offset:54272
	ds_read_b128 v[220:223], v150 offset:55296
	ds_read_b128 v[224:227], v150 offset:56320
	global_load_lds_dwordx4 v[228:229], off
	v_lshl_add_u64 v[228:229], v[230:231], 0, s[22:23]
	s_mov_b32 m0, s45
	s_nop 0
	global_load_lds_dwordx4 v[228:229], off
	v_lshl_add_u64 v[228:229], v[232:233], 0, s[22:23]
	s_mov_b32 m0, s48
	s_nop 0
	global_load_lds_dwordx4 v[228:229], off
	v_lshl_add_u64 v[228:229], v[234:235], 0, s[22:23]
	s_mov_b32 m0, s49
	s_nop 0
	global_load_lds_dwordx4 v[228:229], off
	v_lshl_add_u64 v[228:229], v[236:237], 0, s[22:23]
	s_mov_b32 m0, s46
	s_nop 0
	global_load_lds_dwordx4 v[228:229], off
	v_lshl_add_u64 v[228:229], v[238:239], 0, s[22:23]
	s_mov_b32 m0, s47
	s_nop 0
	global_load_lds_dwordx4 v[228:229], off
	s_waitcnt vmcnt(8)
	s_waitcnt lgkmcnt(0)
	s_setprio 0
	s_barrier
	v_mfma_f32_16x16x32_bf16 v[60:63], v[144:147], v[196:199], v[60:63]
	v_mfma_f32_16x16x32_bf16 v[56:59], v[172:175], v[196:199], v[56:59]
	v_mfma_f32_16x16x32_bf16 v[44:47], v[144:147], v[204:207], v[44:47]
	v_mfma_f32_16x16x32_bf16 v[40:43], v[172:175], v[204:207], v[40:43]
	v_mfma_f32_16x16x32_bf16 v[28:31], v[144:147], v[212:215], v[28:31]
	v_mfma_f32_16x16x32_bf16 v[24:27], v[172:175], v[212:215], v[24:27]
	v_mfma_f32_16x16x32_bf16 v[12:15], v[144:147], v[220:223], v[12:15]
	v_mfma_f32_16x16x32_bf16 v[8:11], v[172:175], v[220:223], v[8:11]
	v_mfma_f32_16x16x32_bf16 v[60:63], v[168:171], v[200:203], v[60:63]
	v_mfma_f32_16x16x32_bf16 v[56:59], v[176:179], v[200:203], v[56:59]
	v_mfma_f32_16x16x32_bf16 v[44:47], v[168:171], v[208:211], v[44:47]
	v_mfma_f32_16x16x32_bf16 v[40:43], v[176:179], v[208:211], v[40:43]
	v_mfma_f32_16x16x32_bf16 v[28:31], v[168:171], v[216:219], v[28:31]
	v_mfma_f32_16x16x32_bf16 v[24:27], v[176:179], v[216:219], v[24:27]
	v_mfma_f32_16x16x32_bf16 v[12:15], v[168:171], v[224:227], v[12:15]
	v_mfma_f32_16x16x32_bf16 v[8:11], v[176:179], v[224:227], v[8:11]
	v_mfma_f32_16x16x32_bf16 v[52:55], v[180:183], v[196:199], v[52:55]
	v_mfma_f32_16x16x32_bf16 v[48:51], v[188:191], v[196:199], v[48:51]
	v_mfma_f32_16x16x32_bf16 v[36:39], v[180:183], v[204:207], v[36:39]
	v_mfma_f32_16x16x32_bf16 v[32:35], v[188:191], v[204:207], v[32:35]
	v_mfma_f32_16x16x32_bf16 v[20:23], v[180:183], v[212:215], v[20:23]
	v_mfma_f32_16x16x32_bf16 v[16:19], v[188:191], v[212:215], v[16:19]
	v_mfma_f32_16x16x32_bf16 v[4:7], v[180:183], v[220:223], v[4:7]
	v_mfma_f32_16x16x32_bf16 v[0:3], v[188:191], v[220:223], v[0:3]
	v_mfma_f32_16x16x32_bf16 v[52:55], v[184:187], v[200:203], v[52:55]
	v_mfma_f32_16x16x32_bf16 v[48:51], v[192:195], v[200:203], v[48:51]
	v_mfma_f32_16x16x32_bf16 v[36:39], v[184:187], v[208:211], v[36:39]
	v_mfma_f32_16x16x32_bf16 v[32:35], v[192:195], v[208:211], v[32:35]
	v_mfma_f32_16x16x32_bf16 v[20:23], v[184:187], v[216:219], v[20:23]
	v_mfma_f32_16x16x32_bf16 v[16:19], v[192:195], v[216:219], v[16:19]
	v_mfma_f32_16x16x32_bf16 v[4:7], v[184:187], v[224:227], v[4:7]
	v_mfma_f32_16x16x32_bf16 v[0:3], v[192:195], v[224:227], v[0:3]
	s_barrier
	s_setprio 1
	s_add_u32 s60, s60, 0x100
	s_addc_u32 s61, s61, 0
	s_add_u32 s4, s4, 0x100
	s_addc_u32 s5, s5, 0
	s_cmp_ge_i32 s30, s50
	s_mov_b32 s0, s30
	s_cbranch_scc0 .LBB0_1046
.LBB0_1047:
	s_setprio 0
	s_and_b64 vcc, exec, s[26:27]
	s_cbranch_vccz .LBB0_1049
	s_barrier

; #define PG8_STAGE(bufoff, gbase, voff) do { _Pragma("unroll") for (int _i = 0; _i < 2; ++_i) \
;         __builtin_amdgcn_global_load_lds((const unsigned*)((const char*)(gbase) + (voff)[_i]), (PG8_LAS unsigned*)(lds + (bufoff) + ldsw + _i * 8192), 16, 0, 0); } while (0)
; #define PG8_LDA(dst, b, h) do { _Pragma("unroll") for (int m = 0; m < 4; ++m) _Pragma("unroll") for (int k = 0; k < 2; ++k) dst[m][k] = *(const PG8_LAS bf16x8*)(lds + PG8_SA(b, h) + aoff + m * 2048 + k * 1024); } while (0)
; #define PG8_WAIT_V(n) asm volatile("s_waitcnt vmcnt(" #n ")" ::: "memory")
; #define PG8_WAIT_L(n) asm volatile("s_waitcnt lgkmcnt(" #n ")" ::: "memory")
; #define PG8_BAR __builtin_amdgcn_s_barrier()
; template <class Epi, class Sched, bool ALIGN_EPI = false, bool SP2 = false>
; __device__ __forceinline__ void gemm_phase(PG8_LAS unsigned char* lds, const Gemm g, const Sched& S, const Epi& E, const int tid_arg) {
;     ...
;         for (int t = 0; t < nt; t += 2) {
;             const bool last = (t == nt - 2);
;             const char* a1 = cA + (size_t)(t + 1) * kstep;
;             const char* a2 = last ? nA : cA + (size_t)(t + 2) * kstep; const char* b2 = last ? nB : cB + (size_t)(t + 2) * kstep;
;             const char* a3 = a2 + kstep; const char* b3 = b2 + kstep;
;             if (last && has_next) S.a_ready(nxt);
;             if constexpr (SP2) {
;             PG8_LDB(B0, 0, 0); PG8_LDB(B1, 0, 1); PG8_SCHED; PG8_LDA(At, 0, 0); PG8_STAGE(PG8_SA(1, 1), a1 + hstep, voffA);
;             PG8_WAIT_V(8); PG8_WAIT_L(0); PG8_BAR; PG8_MMA(0, 0, At, B0); PG8_MMA(0, 1, At, B1); PG8_BAR; PG8_SCHED;
;             PG8_LDA(At, 0, 1); PG8_STAGE(PG8_SB(0, 0), b2, voffB); PG8_STAGE(PG8_SB(0, 1), b2 + hstep, voffB); PG8_STAGE(PG8_SA(0, 0), a2, voffA);
;             PG8_WAIT_V(8); PG8_WAIT_L(0); PG8_BAR; PG8_MMA(1, 0, At, B0); PG8_MMA(1, 1, At, B1); PG8_BAR; PG8_SCHED;
;             PG8_LDB(B0, 1, 0); PG8_LDB(B1, 1, 1); PG8_SCHED; PG8_LDA(At, 1, 0); PG8_STAGE(PG8_SA(0, 1), a2 + hstep, voffA);
;             PG8_WAIT_V(8); PG8_WAIT_L(0); PG8_BAR; PG8_MMA(0, 0, At, B0); PG8_MMA(0, 1, At, B1); PG8_BAR; PG8_SCHED;
;             PG8_LDA(At, 1, 1); PG8_STAGE(PG8_SB(1, 0), b3, voffB); PG8_STAGE(PG8_SB(1, 1), b3 + hstep, voffB); PG8_STAGE(PG8_SA(1, 0), a3, voffA);
;             PG8_WAIT_V(8); PG8_WAIT_L(0); PG8_BAR; PG8_MMA(1, 0, At, B0); PG8_MMA(1, 1, At, B1); PG8_BAR; PG8_SCHED;
.LBB0_1179:
	ds_read_b128 v[144:147], v166
	ds_read_b128 v[148:151], v167
	ds_read_b128 v[152:155], v168
	ds_read_b128 v[156:159], v169
	ds_read_b128 v[184:187], v170
	ds_read_b128 v[188:191], v171
	ds_read_b128 v[192:195], v172
	ds_read_b128 v[196:199], v173
	s_add_u32 s0, s4, 0xfffc0080
	s_addc_u32 s1, s5, -1
	s_cmp_eq_u32 s68, 12
	s_cselect_b32 s11, s25, s1
	s_cselect_b32 s10, s36, s0
	s_cselect_b32 s1, s23, s67
	s_cselect_b32 s0, s37, s66
	s_mov_b32 m0, s55
	v_lshl_add_u64 v[160:161], s[4:5], 0, v[138:139]
	ds_read_b128 v[200:203], v165
	ds_read_b128 v[204:207], v165 offset:1024
	ds_read_b128 v[208:211], v165 offset:2048
	ds_read_b128 v[212:215], v165 offset:3072
	ds_read_b128 v[216:219], v165 offset:4096
	ds_read_b128 v[220:223], v165 offset:5120
	ds_read_b128 v[224:227], v165 offset:6144
	ds_read_b128 v[228:231], v165 offset:7168
	global_load_lds_dwordx4 v[160:161], off
	v_lshl_add_u64 v[160:161], s[4:5], 0, v[136:137]
	s_mov_b32 m0, s56
	s_nop 0
	global_load_lds_dwordx4 v[160:161], off
	s_waitcnt vmcnt(8)
	s_waitcnt lgkmcnt(0)
	s_setprio 0
	s_barrier
	v_mfma_f32_16x16x32_bf16 v[124:127], v[144:147], v[200:203], v[124:127]
	v_mfma_f32_16x16x32_bf16 v[120:123], v[152:155], v[200:203], v[120:123]
	v_mfma_f32_16x16x32_bf16 v[108:111], v[144:147], v[208:211], v[108:111]
	v_mfma_f32_16x16x32_bf16 v[104:107], v[152:155], v[208:211], v[104:107]
	v_mfma_f32_16x16x32_bf16 v[92:95], v[144:147], v[216:219], v[92:95]
	v_mfma_f32_16x16x32_bf16 v[88:91], v[152:155], v[216:219], v[88:91]
	v_mfma_f32_16x16x32_bf16 v[76:79], v[144:147], v[224:227], v[76:79]
	v_mfma_f32_16x16x32_bf16 v[72:75], v[152:155], v[224:227], v[72:75]
	v_mfma_f32_16x16x32_bf16 v[124:127], v[148:151], v[204:207], v[124:127]
	v_mfma_f32_16x16x32_bf16 v[120:123], v[156:159], v[204:207], v[120:123]
	v_mfma_f32_16x16x32_bf16 v[108:111], v[148:151], v[212:215], v[108:111]
	v_mfma_f32_16x16x32_bf16 v[104:107], v[156:159], v[212:215], v[104:107]
	v_mfma_f32_16x16x32_bf16 v[92:95], v[148:151], v[220:223], v[92:95]
	v_mfma_f32_16x16x32_bf16 v[88:91], v[156:159], v[220:223], v[88:91]
	v_mfma_f32_16x16x32_bf16 v[76:79], v[148:151], v[228:231], v[76:79]
	v_mfma_f32_16x16x32_bf16 v[72:75], v[156:159], v[228:231], v[72:75]
	v_mfma_f32_16x16x32_bf16 v[116:119], v[184:187], v[200:203], v[116:119]
	v_mfma_f32_16x16x32_bf16 v[112:115], v[192:195], v[200:203], v[112:115]
	v_mfma_f32_16x16x32_bf16 v[100:103], v[184:187], v[208:211], v[100:103]
	v_mfma_f32_16x16x32_bf16 v[96:99], v[192:195], v[208:211], v[96:99]
	v_mfma_f32_16x16x32_bf16 v[84:87], v[184:187], v[216:219], v[84:87]
	v_mfma_f32_16x16x32_bf16 v[80:83], v[192:195], v[216:219], v[80:83]
	v_mfma_f32_16x16x32_bf16 v[68:71], v[184:187], v[224:227], v[68:71]
	v_mfma_f32_16x16x32_bf16 v[64:67], v[192:195], v[224:227], v[64:67]
	v_mfma_f32_16x16x32_bf16 v[116:119], v[188:191], v[204:207], v[116:119]
	v_mfma_f32_16x16x32_bf16 v[112:115], v[196:199], v[204:207], v[112:115]
	v_mfma_f32_16x16x32_bf16 v[100:103], v[188:191], v[212:215], v[100:103]
	v_mfma_f32_16x16x32_bf16 v[96:99], v[196:199], v[212:215], v[96:99]
	v_mfma_f32_16x16x32_bf16 v[84:87], v[188:191], v[220:223], v[84:87]
	v_mfma_f32_16x16x32_bf16 v[80:83], v[196:199], v[220:223], v[80:83]
	v_mfma_f32_16x16x32_bf16 v[68:71], v[188:191], v[228:231], v[68:71]
	v_mfma_f32_16x16x32_bf16 v[64:67], v[196:199], v[228:231], v[64:67]
	s_barrier
	s_setprio 1
	s_mov_b32 m0, s31
	v_lshl_add_u64 v[160:161], s[0:1], 0, v[130:131]
	s_add_u32 s70, s0, 0x40000
	ds_read_b128 v[200:203], v165 offset:16384
	ds_read_b128 v[204:207], v165 offset:17408
	ds_read_b128 v[208:211], v165 offset:18432
	ds_read_b128 v[212:215], v165 offset:19456
	ds_read_b128 v[216:219], v165 offset:20480
	ds_read_b128 v[220:223], v165 offset:21504
	ds_read_b128 v[224:227], v165 offset:22528
	ds_read_b128 v[228:231], v165 offset:23552
	global_load_lds_dwordx4 v[160:161], off
	v_lshl_add_u64 v[232:233], s[0:1], 0, v[134:135]
	s_mov_b32 m0, s35
	s_addc_u32 s71, s1, 0
	global_load_lds_dwordx4 v[232:233], off
	v_lshl_add_u64 v[234:235], s[70:71], 0, v[130:131]
	s_mov_b32 m0, s40
	v_lshl_add_u64 v[236:237], s[10:11], 0, v[132:133]
	global_load_lds_dwordx4 v[234:235], off
	v_lshl_add_u64 v[234:235], s[70:71], 0, v[134:135]
	s_mov_b32 m0, s41
	s_nop 0
	global_load_lds_dwordx4 v[234:235], off
	v_lshl_add_u64 v[234:235], s[10:11], 0, v[128:129]
	s_mov_b32 m0, s39
	s_nop 0
	global_load_lds_dwordx4 v[234:235], off
	s_mov_b32 m0, s42
	s_nop 0
	global_load_lds_dwordx4 v[236:237], off
	s_waitcnt vmcnt(8)
	s_waitcnt lgkmcnt(0)
	s_setprio 0
	s_barrier
	v_mfma_f32_16x16x32_bf16 v[60:63], v[144:147], v[200:203], v[60:63]
	v_mfma_f32_16x16x32_bf16 v[56:59], v[152:155], v[200:203], v[56:59]
	v_mfma_f32_16x16x32_bf16 v[44:47], v[144:147], v[208:211], v[44:47]
	v_mfma_f32_16x16x32_bf16 v[40:43], v[152:155], v[208:211], v[40:43]
	v_mfma_f32_16x16x32_bf16 v[28:31], v[144:147], v[216:219], v[28:31]
	v_mfma_f32_16x16x32_bf16 v[24:27], v[152:155], v[216:219], v[24:27]
	v_mfma_f32_16x16x32_bf16 v[12:15], v[144:147], v[224:227], v[12:15]
	v_mfma_f32_16x16x32_bf16 v[8:11], v[152:155], v[224:227], v[8:11]
	v_mfma_f32_16x16x32_bf16 v[60:63], v[148:151], v[204:207], v[60:63]
	v_mfma_f32_16x16x32_bf16 v[56:59], v[156:159], v[204:207], v[56:59]
	v_mfma_f32_16x16x32_bf16 v[44:47], v[148:151], v[212:215], v[44:47]
	v_mfma_f32_16x16x32_bf16 v[40:43], v[156:159], v[212:215], v[40:43]
	v_mfma_f32_16x16x32_bf16 v[28:31], v[148:151], v[220:223], v[28:31]
	v_mfma_f32_16x16x32_bf16 v[24:27], v[156:159], v[220:223], v[24:27]
	v_mfma_f32_16x16x32_bf16 v[12:15], v[148:151], v[228:231], v[12:15]
	v_mfma_f32_16x16x32_bf16 v[8:11], v[156:159], v[228:231], v[8:11]
	v_mfma_f32_16x16x32_bf16 v[52:55], v[184:187], v[200:203], v[52:55]
	v_mfma_f32_16x16x32_bf16 v[48:51], v[192:195], v[200:203], v[48:51]
	v_mfma_f32_16x16x32_bf16 v[36:39], v[184:187], v[208:211], v[36:39]
	v_mfma_f32_16x16x32_bf16 v[32:35], v[192:195], v[208:211], v[32:35]
	v_mfma_f32_16x16x32_bf16 v[20:23], v[184:187], v[216:219], v[20:23]
	v_mfma_f32_16x16x32_bf16 v[16:19], v[192:195], v[216:219], v[16:19]
	v_mfma_f32_16x16x32_bf16 v[4:7], v[184:187], v[224:227], v[4:7]
	v_mfma_f32_16x16x32_bf16 v[0:3], v[192:195], v[224:227], v[0:3]
	v_mfma_f32_16x16x32_bf16 v[52:55], v[188:191], v[204:207], v[52:55]
	v_mfma_f32_16x16x32_bf16 v[48:51], v[196:199], v[204:207], v[48:51]
	v_mfma_f32_16x16x32_bf16 v[36:39], v[188:191], v[212:215], v[36:39]
	v_mfma_f32_16x16x32_bf16 v[32:35], v[196:199], v[212:215], v[32:35]
	v_mfma_f32_16x16x32_bf16 v[20:23], v[188:191], v[220:223], v[20:23]
	v_mfma_f32_16x16x32_bf16 v[16:19], v[196:199], v[220:223], v[16:19]
	v_mfma_f32_16x16x32_bf16 v[4:7], v[188:191], v[228:231], v[4:7]
	v_mfma_f32_16x16x32_bf16 v[0:3], v[196:199], v[228:231], v[0:3]
	s_barrier
; #define PG8_STAGE(bufoff, gbase, voff) do { _Pragma("unroll") for (int _i = 0; _i < 2; ++_i) \
;         __builtin_amdgcn_global_load_lds((const unsigned*)((const char*)(gbase) + (voff)[_i]), (PG8_LAS unsigned*)(lds + (bufoff) + ldsw + _i * 8192), 16, 0, 0); } while (0)
; #define PG8_LDA(dst, b, h) do { _Pragma("unroll") for (int m = 0; m < 4; ++m) _Pragma("unroll") for (int k = 0; k < 2; ++k) dst[m][k] = *(const PG8_LAS bf16x8*)(lds + PG8_SA(b, h) + aoff + m * 2048 + k * 1024); } while (0)
; #define PG8_WAIT_V(n) asm volatile("s_waitcnt vmcnt(" #n ")" ::: "memory")
; #define PG8_WAIT_L(n) asm volatile("s_waitcnt lgkmcnt(" #n ")" ::: "memory")
; #define PG8_BAR __builtin_amdgcn_s_barrier()
; template <class Epi, class Sched, bool ALIGN_EPI = false, bool SP2 = false>
; __device__ __forceinline__ void gemm_phase(PG8_LAS unsigned char* lds, const Gemm g, const Sched& S, const Epi& E, const int tid_arg) {
;     ...
;         for (int t = 0; t < nt; t += 2) {
;             const bool last = (t == nt - 2);
;             const char* a1 = cA + (size_t)(t + 1) * kstep;
;             const char* a2 = last ? nA : cA + (size_t)(t + 2) * kstep; const char* b2 = last ? nB : cB + (size_t)(t + 2) * kstep;
;             const char* a3 = a2 + kstep; const char* b3 = b2 + kstep;
;             if (last && has_next) S.a_ready(nxt);
;             if constexpr (SP2) {
;             PG8_LDB(B0, 0, 0); PG8_LDB(B1, 0, 1); PG8_SCHED; PG8_LDA(At, 0, 0); PG8_STAGE(PG8_SA(1, 1), a1 + hstep, voffA);
;             PG8_WAIT_V(8); PG8_WAIT_L(0); PG8_BAR; PG8_MMA(0, 0, At, B0); PG8_MMA(0, 1, At, B1); PG8_BAR; PG8_SCHED;
;             PG8_LDA(At, 0, 1); PG8_STAGE(PG8_SB(0, 0), b2, voffB); PG8_STAGE(PG8_SB(0, 1), b2 + hstep, voffB); PG8_STAGE(PG8_SA(0, 0), a2, voffA);
;             PG8_WAIT_V(8); PG8_WAIT_L(0); PG8_BAR; PG8_MMA(1, 0, At, B0); PG8_MMA(1, 1, At, B1); PG8_BAR; PG8_SCHED;
;             PG8_LDB(B0, 1, 0); PG8_LDB(B1, 1, 1); PG8_SCHED; PG8_LDA(At, 1, 0); PG8_STAGE(PG8_SA(0, 1), a2 + hstep, voffA);
;             PG8_WAIT_V(8); PG8_WAIT_L(0); PG8_BAR; PG8_MMA(0, 0, At, B0); PG8_MMA(0, 1, At, B1); PG8_BAR; PG8_SCHED;
;             PG8_LDA(At, 1, 1); PG8_STAGE(PG8_SB(1, 0), b3, voffB); PG8_STAGE(PG8_SB(1, 1), b3 + hstep, voffB); PG8_STAGE(PG8_SA(1, 0), a3, voffA);
;             PG8_WAIT_V(8); PG8_WAIT_L(0); PG8_BAR; PG8_MMA(1, 0, At, B0); PG8_MMA(1, 1, At, B1); PG8_BAR; PG8_SCHED;
	s_setprio 1
	ds_read_b128 v[144:147], v174
	ds_read_b128 v[148:151], v175
	ds_read_b128 v[152:155], v176
	ds_read_b128 v[156:159], v177
	ds_read_b128 v[184:187], v178
	ds_read_b128 v[188:191], v179
	ds_read_b128 v[192:195], v180
	ds_read_b128 v[196:199], v181
	s_add_u32 s10, s10, 0x40000
	s_addc_u32 s11, s11, 0
	s_mov_b32 m0, s43
	v_lshl_add_u64 v[238:239], s[10:11], 0, v[128:129]
	ds_read_b128 v[200:203], v165 offset:32768
	ds_read_b128 v[204:207], v165 offset:33792
	ds_read_b128 v[208:211], v165 offset:34816
	ds_read_b128 v[212:215], v165 offset:35840
	ds_read_b128 v[216:219], v165 offset:36864
	ds_read_b128 v[220:223], v165 offset:37888
	ds_read_b128 v[224:227], v165 offset:38912
	ds_read_b128 v[228:231], v165 offset:39936
	global_load_lds_dwordx4 v[238:239], off
	v_lshl_add_u64 v[238:239], s[10:11], 0, v[132:133]
	s_mov_b32 m0, s44
	s_nop 0
	global_load_lds_dwordx4 v[238:239], off
	s_waitcnt vmcnt(8)
	s_waitcnt lgkmcnt(0)
	s_setprio 0
	s_barrier
	v_mfma_f32_16x16x32_bf16 v[124:127], v[144:147], v[200:203], v[124:127]
	v_mfma_f32_16x16x32_bf16 v[120:123], v[152:155], v[200:203], v[120:123]
	v_mfma_f32_16x16x32_bf16 v[108:111], v[144:147], v[208:211], v[108:111]
	v_mfma_f32_16x16x32_bf16 v[104:107], v[152:155], v[208:211], v[104:107]
	v_mfma_f32_16x16x32_bf16 v[92:95], v[144:147], v[216:219], v[92:95]
	v_mfma_f32_16x16x32_bf16 v[88:91], v[152:155], v[216:219], v[88:91]
	v_mfma_f32_16x16x32_bf16 v[76:79], v[144:147], v[224:227], v[76:79]
	v_mfma_f32_16x16x32_bf16 v[72:75], v[152:155], v[224:227], v[72:75]
	v_mfma_f32_16x16x32_bf16 v[124:127], v[148:151], v[204:207], v[124:127]
	v_mfma_f32_16x16x32_bf16 v[120:123], v[156:159], v[204:207], v[120:123]
	v_mfma_f32_16x16x32_bf16 v[108:111], v[148:151], v[212:215], v[108:111]
	v_mfma_f32_16x16x32_bf16 v[104:107], v[156:159], v[212:215], v[104:107]
	v_mfma_f32_16x16x32_bf16 v[92:95], v[148:151], v[220:223], v[92:95]
	v_mfma_f32_16x16x32_bf16 v[88:91], v[156:159], v[220:223], v[88:91]
	v_mfma_f32_16x16x32_bf16 v[76:79], v[148:151], v[228:231], v[76:79]
	v_mfma_f32_16x16x32_bf16 v[72:75], v[156:159], v[228:231], v[72:75]
	v_mfma_f32_16x16x32_bf16 v[116:119], v[184:187], v[200:203], v[116:119]
	v_mfma_f32_16x16x32_bf16 v[112:115], v[192:195], v[200:203], v[112:115]
	v_mfma_f32_16x16x32_bf16 v[100:103], v[184:187], v[208:211], v[100:103]
	v_mfma_f32_16x16x32_bf16 v[96:99], v[192:195], v[208:211], v[96:99]
	v_mfma_f32_16x16x32_bf16 v[84:87], v[184:187], v[216:219], v[84:87]
	v_mfma_f32_16x16x32_bf16 v[80:83], v[192:195], v[216:219], v[80:83]
	v_mfma_f32_16x16x32_bf16 v[68:71], v[184:187], v[224:227], v[68:71]
	v_mfma_f32_16x16x32_bf16 v[64:67], v[192:195], v[224:227], v[64:67]
	v_mfma_f32_16x16x32_bf16 v[116:119], v[188:191], v[204:207], v[116:119]
	v_mfma_f32_16x16x32_bf16 v[112:115], v[196:199], v[204:207], v[112:115]
	v_mfma_f32_16x16x32_bf16 v[100:103], v[188:191], v[212:215], v[100:103]
	v_mfma_f32_16x16x32_bf16 v[96:99], v[196:199], v[212:215], v[96:99]
	v_mfma_f32_16x16x32_bf16 v[84:87], v[188:191], v[220:223], v[84:87]
	v_mfma_f32_16x16x32_bf16 v[80:83], v[196:199], v[220:223], v[80:83]
	v_mfma_f32_16x16x32_bf16 v[68:71], v[188:191], v[228:231], v[68:71]
	v_mfma_f32_16x16x32_bf16 v[64:67], v[196:199], v[228:231], v[64:67]
	s_barrier
	s_setprio 1
	s_mov_b32 m0, s47
	v_lshl_add_u64 v[160:161], v[160:161], 0, s[16:17]
	s_add_u32 s0, s0, 0x40080
	ds_read_b128 v[200:203], v165 offset:49152
	ds_read_b128 v[204:207], v165 offset:50176
	ds_read_b128 v[208:211], v165 offset:51200
	ds_read_b128 v[212:215], v165 offset:52224
	ds_read_b128 v[216:219], v165 offset:53248
	ds_read_b128 v[220:223], v165 offset:54272
	ds_read_b128 v[224:227], v165 offset:55296
	ds_read_b128 v[228:231], v165 offset:56320
	global_load_lds_dwordx4 v[160:161], off
	v_lshl_add_u64 v[160:161], v[232:233], 0, s[16:17]
	s_mov_b32 m0, s48
	s_addc_u32 s1, s1, 0
	global_load_lds_dwordx4 v[160:161], off
	v_lshl_add_u64 v[160:161], s[0:1], 0, v[130:131]
	s_mov_b32 m0, s51
	s_nop 0
	global_load_lds_dwordx4 v[160:161], off
	v_lshl_add_u64 v[160:161], s[0:1], 0, v[134:135]
	s_mov_b32 m0, s52
	s_nop 0
	global_load_lds_dwordx4 v[160:161], off
	v_lshl_add_u64 v[160:161], v[234:235], 0, s[16:17]
	s_mov_b32 m0, s49
	s_nop 0
	global_load_lds_dwordx4 v[160:161], off
	v_lshl_add_u64 v[160:161], v[236:237], 0, s[16:17]
	s_mov_b32 m0, s50
	s_nop 0
	global_load_lds_dwordx4 v[160:161], off
	s_waitcnt vmcnt(8)
	s_waitcnt lgkmcnt(0)
	s_setprio 0
	s_barrier
	v_mfma_f32_16x16x32_bf16 v[60:63], v[144:147], v[200:203], v[60:63]
	v_mfma_f32_16x16x32_bf16 v[56:59], v[152:155], v[200:203], v[56:59]
	v_mfma_f32_16x16x32_bf16 v[44:47], v[144:147], v[208:211], v[44:47]
	v_mfma_f32_16x16x32_bf16 v[40:43], v[152:155], v[208:211], v[40:43]
	v_mfma_f32_16x16x32_bf16 v[28:31], v[144:147], v[216:219], v[28:31]
	v_mfma_f32_16x16x32_bf16 v[24:27], v[152:155], v[216:219], v[24:27]
	v_mfma_f32_16x16x32_bf16 v[12:15], v[144:147], v[224:227], v[12:15]
	v_mfma_f32_16x16x32_bf16 v[8:11], v[152:155], v[224:227], v[8:11]
	v_mfma_f32_16x16x32_bf16 v[60:63], v[148:151], v[204:207], v[60:63]
	v_mfma_f32_16x16x32_bf16 v[56:59], v[156:159], v[204:207], v[56:59]
	v_mfma_f32_16x16x32_bf16 v[44:47], v[148:151], v[212:215], v[44:47]
	v_mfma_f32_16x16x32_bf16 v[40:43], v[156:159], v[212:215], v[40:43]
	v_mfma_f32_16x16x32_bf16 v[28:31], v[148:151], v[220:223], v[28:31]
	v_mfma_f32_16x16x32_bf16 v[24:27], v[156:159], v[220:223], v[24:27]
	v_mfma_f32_16x16x32_bf16 v[12:15], v[148:151], v[228:231], v[12:15]
	v_mfma_f32_16x16x32_bf16 v[8:11], v[156:159], v[228:231], v[8:11]
	v_mfma_f32_16x16x32_bf16 v[52:55], v[184:187], v[200:203], v[52:55]
	v_mfma_f32_16x16x32_bf16 v[48:51], v[192:195], v[200:203], v[48:51]
	v_mfma_f32_16x16x32_bf16 v[36:39], v[184:187], v[208:211], v[36:39]
	v_mfma_f32_16x16x32_bf16 v[32:35], v[192:195], v[208:211], v[32:35]
	v_mfma_f32_16x16x32_bf16 v[20:23], v[184:187], v[216:219], v[20:23]
	v_mfma_f32_16x16x32_bf16 v[16:19], v[192:195], v[216:219], v[16:19]
	v_mfma_f32_16x16x32_bf16 v[4:7], v[184:187], v[224:227], v[4:7]
	v_mfma_f32_16x16x32_bf16 v[0:3], v[192:195], v[224:227], v[0:3]
	v_mfma_f32_16x16x32_bf16 v[52:55], v[188:191], v[204:207], v[52:55]
	v_mfma_f32_16x16x32_bf16 v[48:51], v[196:199], v[204:207], v[48:51]
	v_mfma_f32_16x16x32_bf16 v[36:39], v[188:191], v[212:215], v[36:39]
	v_mfma_f32_16x16x32_bf16 v[32:35], v[196:199], v[212:215], v[32:35]
	v_mfma_f32_16x16x32_bf16 v[20:23], v[188:191], v[220:223], v[20:23]
	v_mfma_f32_16x16x32_bf16 v[16:19], v[196:199], v[220:223], v[16:19]
	v_mfma_f32_16x16x32_bf16 v[4:7], v[188:191], v[228:231], v[4:7]
	v_mfma_f32_16x16x32_bf16 v[0:3], v[196:199], v[228:231], v[0:3]
	s_barrier
	s_setprio 1
	s_add_i32 s68, s68, 2
	s_add_u32 s66, s66, 0x100
	s_addc_u32 s67, s67, 0
	s_add_u32 s4, s4, 0x100
	s_addc_u32 s5, s5, 0
	s_cmp_gt_u32 s68, 13
	s_cbranch_scc0 .LBB0_1179
	s_setprio 0
	s_and_b64 vcc, exec, s[18:19]
	s_cbranch_vccz .LBB0_1182
	s_barrier

; #define PG8_STAGE(bufoff, gbase, voff) do { _Pragma("unroll") for (int _i = 0; _i < 2; ++_i) \
;         __builtin_amdgcn_global_load_lds((const unsigned*)((const char*)(gbase) + (voff)[_i]), (PG8_LAS unsigned*)(lds + (bufoff) + ldsw + _i * 8192), 16, 0, 0); } while (0)
; #define PG8_LDA(dst, b, h) do { _Pragma("unroll") for (int m = 0; m < 4; ++m) _Pragma("unroll") for (int k = 0; k < 2; ++k) dst[m][k] = *(const PG8_LAS bf16x8*)(lds + PG8_SA(b, h) + aoff + m * 2048 + k * 1024); } while (0)
; #define PG8_WAIT_V(n) asm volatile("s_waitcnt vmcnt(" #n ")" ::: "memory")
; #define PG8_WAIT_L(n) asm volatile("s_waitcnt lgkmcnt(" #n ")" ::: "memory")
; #define PG8_BAR __builtin_amdgcn_s_barrier()
; template <class Epi, class Sched, bool ALIGN_EPI = false, bool SP2 = false>
; __device__ __forceinline__ void gemm_phase(PG8_LAS unsigned char* lds, const Gemm g, const Sched& S, const Epi& E, const int tid_arg) {
;     ...
;         for (int t = 0; t < nt; t += 2) {
;             const bool last = (t == nt - 2);
;             const char* a1 = cA + (size_t)(t + 1) * kstep;
;             const char* a2 = last ? nA : cA + (size_t)(t + 2) * kstep; const char* b2 = last ? nB : cB + (size_t)(t + 2) * kstep;
;             const char* a3 = a2 + kstep; const char* b3 = b2 + kstep;
;             if (last && has_next) S.a_ready(nxt);
;             if constexpr (SP2) {
;             PG8_LDB(B0, 0, 0); PG8_LDB(B1, 0, 1); PG8_SCHED; PG8_LDA(At, 0, 0); PG8_STAGE(PG8_SA(1, 1), a1 + hstep, voffA);
;             PG8_WAIT_V(8); PG8_WAIT_L(0); PG8_BAR; PG8_MMA(0, 0, At, B0); PG8_MMA(0, 1, At, B1); PG8_BAR; PG8_SCHED;
;             PG8_LDA(At, 0, 1); PG8_STAGE(PG8_SB(0, 0), b2, voffB); PG8_STAGE(PG8_SB(0, 1), b2 + hstep, voffB); PG8_STAGE(PG8_SA(0, 0), a2, voffA);
;             PG8_WAIT_V(8); PG8_WAIT_L(0); PG8_BAR; PG8_MMA(1, 0, At, B0); PG8_MMA(1, 1, At, B1); PG8_BAR; PG8_SCHED;
;             PG8_LDB(B0, 1, 0); PG8_LDB(B1, 1, 1); PG8_SCHED; PG8_LDA(At, 1, 0); PG8_STAGE(PG8_SA(0, 1), a2 + hstep, voffA);
;             PG8_WAIT_V(8); PG8_WAIT_L(0); PG8_BAR; PG8_MMA(0, 0, At, B0); PG8_MMA(0, 1, At, B1); PG8_BAR; PG8_SCHED;
;             PG8_LDA(At, 1, 1); PG8_STAGE(PG8_SB(1, 0), b3, voffB); PG8_STAGE(PG8_SB(1, 1), b3 + hstep, voffB); PG8_STAGE(PG8_SA(1, 0), a3, voffA);
;             PG8_WAIT_V(8); PG8_WAIT_L(0); PG8_BAR; PG8_MMA(1, 0, At, B0); PG8_MMA(1, 1, At, B1); PG8_BAR; PG8_SCHED;
.LBB0_1459:
	ds_read_b128 v[144:147], v151
	ds_read_b128 v[168:171], v152
	ds_read_b128 v[172:175], v153
	ds_read_b128 v[176:179], v154
	ds_read_b128 v[180:183], v155
	ds_read_b128 v[184:187], v156
	ds_read_b128 v[188:191], v157
	ds_read_b128 v[192:195], v158
	s_add_u32 s0, s28, 0xfffc0080
	s_addc_u32 s1, s29, -1
	s_cmp_eq_u32 s59, 12
	s_cselect_b32 s31, s21, s1
	s_cselect_b32 s30, s27, s0
	s_cselect_b32 s1, s19, s58
	s_cselect_b32 s0, s56, s57
	s_mov_b32 m0, s53
	v_lshl_add_u64 v[228:229], s[28:29], 0, v[138:139]
	ds_read_b128 v[196:199], v150
	ds_read_b128 v[200:203], v150 offset:1024
	ds_read_b128 v[204:207], v150 offset:2048
	ds_read_b128 v[208:211], v150 offset:3072
	ds_read_b128 v[212:215], v150 offset:4096
	ds_read_b128 v[216:219], v150 offset:5120
	ds_read_b128 v[220:223], v150 offset:6144
	ds_read_b128 v[224:227], v150 offset:7168
	global_load_lds_dwordx4 v[228:229], off
	v_lshl_add_u64 v[228:229], s[28:29], 0, v[136:137]
	s_mov_b32 m0, s54
	s_nop 0
	global_load_lds_dwordx4 v[228:229], off
	s_waitcnt vmcnt(8)
	s_waitcnt lgkmcnt(0)
	s_setprio 0
	s_barrier
	v_mfma_f32_16x16x32_bf16 v[124:127], v[144:147], v[196:199], v[124:127]
	v_mfma_f32_16x16x32_bf16 v[120:123], v[172:175], v[196:199], v[120:123]
	v_mfma_f32_16x16x32_bf16 v[108:111], v[144:147], v[204:207], v[108:111]
	v_mfma_f32_16x16x32_bf16 v[104:107], v[172:175], v[204:207], v[104:107]
	v_mfma_f32_16x16x32_bf16 v[92:95], v[144:147], v[212:215], v[92:95]
	v_mfma_f32_16x16x32_bf16 v[88:91], v[172:175], v[212:215], v[88:91]
	v_mfma_f32_16x16x32_bf16 v[76:79], v[144:147], v[220:223], v[76:79]
	v_mfma_f32_16x16x32_bf16 v[72:75], v[172:175], v[220:223], v[72:75]
	v_mfma_f32_16x16x32_bf16 v[124:127], v[168:171], v[200:203], v[124:127]
	v_mfma_f32_16x16x32_bf16 v[120:123], v[176:179], v[200:203], v[120:123]
	v_mfma_f32_16x16x32_bf16 v[108:111], v[168:171], v[208:211], v[108:111]
	v_mfma_f32_16x16x32_bf16 v[104:107], v[176:179], v[208:211], v[104:107]
	v_mfma_f32_16x16x32_bf16 v[92:95], v[168:171], v[216:219], v[92:95]
	v_mfma_f32_16x16x32_bf16 v[88:91], v[176:179], v[216:219], v[88:91]
	v_mfma_f32_16x16x32_bf16 v[76:79], v[168:171], v[224:227], v[76:79]
	v_mfma_f32_16x16x32_bf16 v[72:75], v[176:179], v[224:227], v[72:75]
	v_mfma_f32_16x16x32_bf16 v[116:119], v[180:183], v[196:199], v[116:119]
	v_mfma_f32_16x16x32_bf16 v[112:115], v[188:191], v[196:199], v[112:115]
	v_mfma_f32_16x16x32_bf16 v[100:103], v[180:183], v[204:207], v[100:103]
	v_mfma_f32_16x16x32_bf16 v[96:99], v[188:191], v[204:207], v[96:99]
	v_mfma_f32_16x16x32_bf16 v[84:87], v[180:183], v[212:215], v[84:87]
	v_mfma_f32_16x16x32_bf16 v[80:83], v[188:191], v[212:215], v[80:83]
	v_mfma_f32_16x16x32_bf16 v[68:71], v[180:183], v[220:223], v[68:71]
	v_mfma_f32_16x16x32_bf16 v[64:67], v[188:191], v[220:223], v[64:67]
	v_mfma_f32_16x16x32_bf16 v[116:119], v[184:187], v[200:203], v[116:119]
	v_mfma_f32_16x16x32_bf16 v[112:115], v[192:195], v[200:203], v[112:115]
	v_mfma_f32_16x16x32_bf16 v[100:103], v[184:187], v[208:211], v[100:103]
	v_mfma_f32_16x16x32_bf16 v[96:99], v[192:195], v[208:211], v[96:99]
	v_mfma_f32_16x16x32_bf16 v[84:87], v[184:187], v[216:219], v[84:87]
	v_mfma_f32_16x16x32_bf16 v[80:83], v[192:195], v[216:219], v[80:83]
	v_mfma_f32_16x16x32_bf16 v[68:71], v[184:187], v[224:227], v[68:71]
	v_mfma_f32_16x16x32_bf16 v[64:67], v[192:195], v[224:227], v[64:67]
	s_barrier
	s_setprio 1
	s_mov_b32 m0, s5
	v_lshl_add_u64 v[228:229], s[0:1], 0, v[130:131]
	s_add_u32 s60, s0, 0x40000
	ds_read_b128 v[196:199], v150 offset:16384
	ds_read_b128 v[200:203], v150 offset:17408
	ds_read_b128 v[204:207], v150 offset:18432
	ds_read_b128 v[208:211], v150 offset:19456
	ds_read_b128 v[212:215], v150 offset:20480
	ds_read_b128 v[216:219], v150 offset:21504
	ds_read_b128 v[220:223], v150 offset:22528
	ds_read_b128 v[224:227], v150 offset:23552
	global_load_lds_dwordx4 v[228:229], off
	v_lshl_add_u64 v[230:231], s[0:1], 0, v[134:135]
	s_mov_b32 m0, s36
	s_addc_u32 s61, s1, 0
	global_load_lds_dwordx4 v[230:231], off
	v_lshl_add_u64 v[232:233], s[60:61], 0, v[130:131]
	s_mov_b32 m0, s37
	v_lshl_add_u64 v[234:235], s[30:31], 0, v[132:133]
	global_load_lds_dwordx4 v[232:233], off
	v_lshl_add_u64 v[232:233], s[60:61], 0, v[134:135]
	s_mov_b32 m0, s38
	s_nop 0
	global_load_lds_dwordx4 v[232:233], off
	v_lshl_add_u64 v[232:233], s[30:31], 0, v[128:129]
	s_mov_b32 m0, s35
	s_nop 0
	global_load_lds_dwordx4 v[232:233], off
	s_mov_b32 m0, s39
	s_nop 0
	global_load_lds_dwordx4 v[234:235], off
	s_waitcnt vmcnt(8)
	s_waitcnt lgkmcnt(0)
	s_setprio 0
	s_barrier
	v_mfma_f32_16x16x32_bf16 v[60:63], v[144:147], v[196:199], v[60:63]
	v_mfma_f32_16x16x32_bf16 v[56:59], v[172:175], v[196:199], v[56:59]
	v_mfma_f32_16x16x32_bf16 v[44:47], v[144:147], v[204:207], v[44:47]
	v_mfma_f32_16x16x32_bf16 v[40:43], v[172:175], v[204:207], v[40:43]
	v_mfma_f32_16x16x32_bf16 v[28:31], v[144:147], v[212:215], v[28:31]
	v_mfma_f32_16x16x32_bf16 v[24:27], v[172:175], v[212:215], v[24:27]
	v_mfma_f32_16x16x32_bf16 v[12:15], v[144:147], v[220:223], v[12:15]
	v_mfma_f32_16x16x32_bf16 v[8:11], v[172:175], v[220:223], v[8:11]
	v_mfma_f32_16x16x32_bf16 v[60:63], v[168:171], v[200:203], v[60:63]
	v_mfma_f32_16x16x32_bf16 v[56:59], v[176:179], v[200:203], v[56:59]
	v_mfma_f32_16x16x32_bf16 v[44:47], v[168:171], v[208:211], v[44:47]
	v_mfma_f32_16x16x32_bf16 v[40:43], v[176:179], v[208:211], v[40:43]
	v_mfma_f32_16x16x32_bf16 v[28:31], v[168:171], v[216:219], v[28:31]
	v_mfma_f32_16x16x32_bf16 v[24:27], v[176:179], v[216:219], v[24:27]
	v_mfma_f32_16x16x32_bf16 v[12:15], v[168:171], v[224:227], v[12:15]
	v_mfma_f32_16x16x32_bf16 v[8:11], v[176:179], v[224:227], v[8:11]
	v_mfma_f32_16x16x32_bf16 v[52:55], v[180:183], v[196:199], v[52:55]
	v_mfma_f32_16x16x32_bf16 v[48:51], v[188:191], v[196:199], v[48:51]
	v_mfma_f32_16x16x32_bf16 v[36:39], v[180:183], v[204:207], v[36:39]
	v_mfma_f32_16x16x32_bf16 v[32:35], v[188:191], v[204:207], v[32:35]
	v_mfma_f32_16x16x32_bf16 v[20:23], v[180:183], v[212:215], v[20:23]
	v_mfma_f32_16x16x32_bf16 v[16:19], v[188:191], v[212:215], v[16:19]
	v_mfma_f32_16x16x32_bf16 v[4:7], v[180:183], v[220:223], v[4:7]
	v_mfma_f32_16x16x32_bf16 v[0:3], v[188:191], v[220:223], v[0:3]
	v_mfma_f32_16x16x32_bf16 v[52:55], v[184:187], v[200:203], v[52:55]
	v_mfma_f32_16x16x32_bf16 v[48:51], v[192:195], v[200:203], v[48:51]
	v_mfma_f32_16x16x32_bf16 v[36:39], v[184:187], v[208:211], v[36:39]
	v_mfma_f32_16x16x32_bf16 v[32:35], v[192:195], v[208:211], v[32:35]
	v_mfma_f32_16x16x32_bf16 v[20:23], v[184:187], v[216:219], v[20:23]
	v_mfma_f32_16x16x32_bf16 v[16:19], v[192:195], v[216:219], v[16:19]
	v_mfma_f32_16x16x32_bf16 v[4:7], v[184:187], v[224:227], v[4:7]
	v_mfma_f32_16x16x32_bf16 v[0:3], v[192:195], v[224:227], v[0:3]
	s_barrier
; #define PG8_STAGE(bufoff, gbase, voff) do { _Pragma("unroll") for (int _i = 0; _i < 2; ++_i) \
;         __builtin_amdgcn_global_load_lds((const unsigned*)((const char*)(gbase) + (voff)[_i]), (PG8_LAS unsigned*)(lds + (bufoff) + ldsw + _i * 8192), 16, 0, 0); } while (0)
; #define PG8_LDA(dst, b, h) do { _Pragma("unroll") for (int m = 0; m < 4; ++m) _Pragma("unroll") for (int k = 0; k < 2; ++k) dst[m][k] = *(const PG8_LAS bf16x8*)(lds + PG8_SA(b, h) + aoff + m * 2048 + k * 1024); } while (0)
; #define PG8_WAIT_V(n) asm volatile("s_waitcnt vmcnt(" #n ")" ::: "memory")
; #define PG8_WAIT_L(n) asm volatile("s_waitcnt lgkmcnt(" #n ")" ::: "memory")
; #define PG8_BAR __builtin_amdgcn_s_barrier()
; template <class Epi, class Sched, bool ALIGN_EPI = false, bool SP2 = false>
; __device__ __forceinline__ void gemm_phase(PG8_LAS unsigned char* lds, const Gemm g, const Sched& S, const Epi& E, const int tid_arg) {
;     ...
;         for (int t = 0; t < nt; t += 2) {
;             const bool last = (t == nt - 2);
;             const char* a1 = cA + (size_t)(t + 1) * kstep;
;             const char* a2 = last ? nA : cA + (size_t)(t + 2) * kstep; const char* b2 = last ? nB : cB + (size_t)(t + 2) * kstep;
;             const char* a3 = a2 + kstep; const char* b3 = b2 + kstep;
;             if (last && has_next) S.a_ready(nxt);
;             if constexpr (SP2) {
;             PG8_LDB(B0, 0, 0); PG8_LDB(B1, 0, 1); PG8_SCHED; PG8_LDA(At, 0, 0); PG8_STAGE(PG8_SA(1, 1), a1 + hstep, voffA);
;             PG8_WAIT_V(8); PG8_WAIT_L(0); PG8_BAR; PG8_MMA(0, 0, At, B0); PG8_MMA(0, 1, At, B1); PG8_BAR; PG8_SCHED;
;             PG8_LDA(At, 0, 1); PG8_STAGE(PG8_SB(0, 0), b2, voffB); PG8_STAGE(PG8_SB(0, 1), b2 + hstep, voffB); PG8_STAGE(PG8_SA(0, 0), a2, voffA);
;             PG8_WAIT_V(8); PG8_WAIT_L(0); PG8_BAR; PG8_MMA(1, 0, At, B0); PG8_MMA(1, 1, At, B1); PG8_BAR; PG8_SCHED;
;             PG8_LDB(B0, 1, 0); PG8_LDB(B1, 1, 1); PG8_SCHED; PG8_LDA(At, 1, 0); PG8_STAGE(PG8_SA(0, 1), a2 + hstep, voffA);
;             PG8_WAIT_V(8); PG8_WAIT_L(0); PG8_BAR; PG8_MMA(0, 0, At, B0); PG8_MMA(0, 1, At, B1); PG8_BAR; PG8_SCHED;
;             PG8_LDA(At, 1, 1); PG8_STAGE(PG8_SB(1, 0), b3, voffB); PG8_STAGE(PG8_SB(1, 1), b3 + hstep, voffB); PG8_STAGE(PG8_SA(1, 0), a3, voffA);
;             PG8_WAIT_V(8); PG8_WAIT_L(0); PG8_BAR; PG8_MMA(1, 0, At, B0); PG8_MMA(1, 1, At, B1); PG8_BAR; PG8_SCHED;
	s_setprio 1
	ds_read_b128 v[144:147], v159
	ds_read_b128 v[168:171], v160
	ds_read_b128 v[172:175], v161
	ds_read_b128 v[176:179], v162
	ds_read_b128 v[180:183], v163
	ds_read_b128 v[184:187], v164
	ds_read_b128 v[188:191], v165
	ds_read_b128 v[192:195], v166
	s_add_u32 s30, s30, 0x40000
	s_addc_u32 s31, s31, 0
	s_mov_b32 m0, s40
	v_lshl_add_u64 v[236:237], s[30:31], 0, v[128:129]
	ds_read_b128 v[196:199], v150 offset:32768
	ds_read_b128 v[200:203], v150 offset:33792
	ds_read_b128 v[204:207], v150 offset:34816
	ds_read_b128 v[208:211], v150 offset:35840
	ds_read_b128 v[212:215], v150 offset:36864
	ds_read_b128 v[216:219], v150 offset:37888
	ds_read_b128 v[220:223], v150 offset:38912
	ds_read_b128 v[224:227], v150 offset:39936
	global_load_lds_dwordx4 v[236:237], off
	v_lshl_add_u64 v[236:237], s[30:31], 0, v[132:133]
	s_mov_b32 m0, s41
	s_nop 0
	global_load_lds_dwordx4 v[236:237], off
	s_waitcnt vmcnt(8)
	s_waitcnt lgkmcnt(0)
	s_setprio 0
	s_barrier
	v_mfma_f32_16x16x32_bf16 v[124:127], v[144:147], v[196:199], v[124:127]
	v_mfma_f32_16x16x32_bf16 v[120:123], v[172:175], v[196:199], v[120:123]
	v_mfma_f32_16x16x32_bf16 v[108:111], v[144:147], v[204:207], v[108:111]
	v_mfma_f32_16x16x32_bf16 v[104:107], v[172:175], v[204:207], v[104:107]
	v_mfma_f32_16x16x32_bf16 v[92:95], v[144:147], v[212:215], v[92:95]
	v_mfma_f32_16x16x32_bf16 v[88:91], v[172:175], v[212:215], v[88:91]
	v_mfma_f32_16x16x32_bf16 v[76:79], v[144:147], v[220:223], v[76:79]
	v_mfma_f32_16x16x32_bf16 v[72:75], v[172:175], v[220:223], v[72:75]
	v_mfma_f32_16x16x32_bf16 v[124:127], v[168:171], v[200:203], v[124:127]
	v_mfma_f32_16x16x32_bf16 v[120:123], v[176:179], v[200:203], v[120:123]
	v_mfma_f32_16x16x32_bf16 v[108:111], v[168:171], v[208:211], v[108:111]
	v_mfma_f32_16x16x32_bf16 v[104:107], v[176:179], v[208:211], v[104:107]
	v_mfma_f32_16x16x32_bf16 v[92:95], v[168:171], v[216:219], v[92:95]
	v_mfma_f32_16x16x32_bf16 v[88:91], v[176:179], v[216:219], v[88:91]
	v_mfma_f32_16x16x32_bf16 v[76:79], v[168:171], v[224:227], v[76:79]
	v_mfma_f32_16x16x32_bf16 v[72:75], v[176:179], v[224:227], v[72:75]
	v_mfma_f32_16x16x32_bf16 v[116:119], v[180:183], v[196:199], v[116:119]
	v_mfma_f32_16x16x32_bf16 v[112:115], v[188:191], v[196:199], v[112:115]
	v_mfma_f32_16x16x32_bf16 v[100:103], v[180:183], v[204:207], v[100:103]
	v_mfma_f32_16x16x32_bf16 v[96:99], v[188:191], v[204:207], v[96:99]
	v_mfma_f32_16x16x32_bf16 v[84:87], v[180:183], v[212:215], v[84:87]
	v_mfma_f32_16x16x32_bf16 v[80:83], v[188:191], v[212:215], v[80:83]
	v_mfma_f32_16x16x32_bf16 v[68:71], v[180:183], v[220:223], v[68:71]
	v_mfma_f32_16x16x32_bf16 v[64:67], v[188:191], v[220:223], v[64:67]
	v_mfma_f32_16x16x32_bf16 v[116:119], v[184:187], v[200:203], v[116:119]
	v_mfma_f32_16x16x32_bf16 v[112:115], v[192:195], v[200:203], v[112:115]
	v_mfma_f32_16x16x32_bf16 v[100:103], v[184:187], v[208:211], v[100:103]
	v_mfma_f32_16x16x32_bf16 v[96:99], v[192:195], v[208:211], v[96:99]
	v_mfma_f32_16x16x32_bf16 v[84:87], v[184:187], v[216:219], v[84:87]
	v_mfma_f32_16x16x32_bf16 v[80:83], v[192:195], v[216:219], v[80:83]
	v_mfma_f32_16x16x32_bf16 v[68:71], v[184:187], v[224:227], v[68:71]
	v_mfma_f32_16x16x32_bf16 v[64:67], v[192:195], v[224:227], v[64:67]
	s_barrier
	s_setprio 1
	s_mov_b32 m0, s45
	v_lshl_add_u64 v[228:229], v[228:229], 0, s[14:15]
	s_add_u32 s0, s0, 0x40080
	ds_read_b128 v[196:199], v150 offset:49152
	ds_read_b128 v[200:203], v150 offset:50176
	ds_read_b128 v[204:207], v150 offset:51200
	ds_read_b128 v[208:211], v150 offset:52224
	ds_read_b128 v[212:215], v150 offset:53248
	ds_read_b128 v[216:219], v150 offset:54272
	ds_read_b128 v[220:223], v150 offset:55296
	ds_read_b128 v[224:227], v150 offset:56320
	global_load_lds_dwordx4 v[228:229], off
	v_lshl_add_u64 v[228:229], v[230:231], 0, s[14:15]
	s_mov_b32 m0, s46
	s_addc_u32 s1, s1, 0
	global_load_lds_dwordx4 v[228:229], off
	v_lshl_add_u64 v[228:229], s[0:1], 0, v[130:131]
	s_mov_b32 m0, s49
	s_nop 0
	global_load_lds_dwordx4 v[228:229], off
	v_lshl_add_u64 v[228:229], s[0:1], 0, v[134:135]
	s_mov_b32 m0, s50
	s_nop 0
	global_load_lds_dwordx4 v[228:229], off
	v_lshl_add_u64 v[228:229], v[232:233], 0, s[14:15]
	s_mov_b32 m0, s47
	s_nop 0
	global_load_lds_dwordx4 v[228:229], off
	v_lshl_add_u64 v[228:229], v[234:235], 0, s[14:15]
	s_mov_b32 m0, s48
	s_nop 0
	global_load_lds_dwordx4 v[228:229], off
	s_waitcnt vmcnt(8)
	s_waitcnt lgkmcnt(0)
	s_setprio 0
	s_barrier
	v_mfma_f32_16x16x32_bf16 v[60:63], v[144:147], v[196:199], v[60:63]
	v_mfma_f32_16x16x32_bf16 v[56:59], v[172:175], v[196:199], v[56:59]
	v_mfma_f32_16x16x32_bf16 v[44:47], v[144:147], v[204:207], v[44:47]
	v_mfma_f32_16x16x32_bf16 v[40:43], v[172:175], v[204:207], v[40:43]
	v_mfma_f32_16x16x32_bf16 v[28:31], v[144:147], v[212:215], v[28:31]
	v_mfma_f32_16x16x32_bf16 v[24:27], v[172:175], v[212:215], v[24:27]
	v_mfma_f32_16x16x32_bf16 v[12:15], v[144:147], v[220:223], v[12:15]
	v_mfma_f32_16x16x32_bf16 v[8:11], v[172:175], v[220:223], v[8:11]
	v_mfma_f32_16x16x32_bf16 v[60:63], v[168:171], v[200:203], v[60:63]
	v_mfma_f32_16x16x32_bf16 v[56:59], v[176:179], v[200:203], v[56:59]
	v_mfma_f32_16x16x32_bf16 v[44:47], v[168:171], v[208:211], v[44:47]
	v_mfma_f32_16x16x32_bf16 v[40:43], v[176:179], v[208:211], v[40:43]
	v_mfma_f32_16x16x32_bf16 v[28:31], v[168:171], v[216:219], v[28:31]
	v_mfma_f32_16x16x32_bf16 v[24:27], v[176:179], v[216:219], v[24:27]
	v_mfma_f32_16x16x32_bf16 v[12:15], v[168:171], v[224:227], v[12:15]
	v_mfma_f32_16x16x32_bf16 v[8:11], v[176:179], v[224:227], v[8:11]
	v_mfma_f32_16x16x32_bf16 v[52:55], v[180:183], v[196:199], v[52:55]
	v_mfma_f32_16x16x32_bf16 v[48:51], v[188:191], v[196:199], v[48:51]
	v_mfma_f32_16x16x32_bf16 v[36:39], v[180:183], v[204:207], v[36:39]
	v_mfma_f32_16x16x32_bf16 v[32:35], v[188:191], v[204:207], v[32:35]
	v_mfma_f32_16x16x32_bf16 v[20:23], v[180:183], v[212:215], v[20:23]
	v_mfma_f32_16x16x32_bf16 v[16:19], v[188:191], v[212:215], v[16:19]
	v_mfma_f32_16x16x32_bf16 v[4:7], v[180:183], v[220:223], v[4:7]
	v_mfma_f32_16x16x32_bf16 v[0:3], v[188:191], v[220:223], v[0:3]
	v_mfma_f32_16x16x32_bf16 v[52:55], v[184:187], v[200:203], v[52:55]
	v_mfma_f32_16x16x32_bf16 v[48:51], v[192:195], v[200:203], v[48:51]
	v_mfma_f32_16x16x32_bf16 v[36:39], v[184:187], v[208:211], v[36:39]
	v_mfma_f32_16x16x32_bf16 v[32:35], v[192:195], v[208:211], v[32:35]
	v_mfma_f32_16x16x32_bf16 v[20:23], v[184:187], v[216:219], v[20:23]
	v_mfma_f32_16x16x32_bf16 v[16:19], v[192:195], v[216:219], v[16:19]
	v_mfma_f32_16x16x32_bf16 v[4:7], v[184:187], v[224:227], v[4:7]
	v_mfma_f32_16x16x32_bf16 v[0:3], v[192:195], v[224:227], v[0:3]
	s_barrier
	s_setprio 1
	s_add_i32 s59, s59, 2
	s_add_u32 s57, s57, 0x100
	s_addc_u32 s58, s58, 0
	s_add_u32 s28, s28, 0x100
	s_addc_u32 s29, s29, 0
	s_cmp_gt_u32 s59, 13
	s_cbranch_scc0 .LBB0_1459
	s_setprio 0
	s_and_b64 vcc, exec, s[16:17]
	s_cbranch_vccz .LBB0_1462
	s_barrier

; #define PG8_STAGE(bufoff, gbase, voff) do { _Pragma("unroll") for (int _i = 0; _i < 2; ++_i) \
;         __builtin_amdgcn_global_load_lds((const unsigned*)((const char*)(gbase) + (voff)[_i]), (PG8_LAS unsigned*)(lds + (bufoff) + ldsw + _i * 8192), 16, 0, 0); } while (0)
; #define PG8_LDA(dst, b, h) do { _Pragma("unroll") for (int m = 0; m < 4; ++m) _Pragma("unroll") for (int k = 0; k < 2; ++k) dst[m][k] = *(const PG8_LAS bf16x8*)(lds + PG8_SA(b, h) + aoff + m * 2048 + k * 1024); } while (0)
; #define PG8_WAIT_V(n) asm volatile("s_waitcnt vmcnt(" #n ")" ::: "memory")
; #define PG8_WAIT_L(n) asm volatile("s_waitcnt lgkmcnt(" #n ")" ::: "memory")
; #define PG8_BAR __builtin_amdgcn_s_barrier()
; template <class Epi, class Sched, bool ALIGN_EPI = false, bool SP2 = false>
; __device__ __forceinline__ void gemm_phase(PG8_LAS unsigned char* lds, const Gemm g, const Sched& S, const Epi& E, const int tid_arg) {
;     ...
;         for (int t = 0; t < nt; t += 2) {
;             const bool last = (t == nt - 2);
;             const char* a1 = cA + (size_t)(t + 1) * kstep;
;             const char* a2 = last ? nA : cA + (size_t)(t + 2) * kstep; const char* b2 = last ? nB : cB + (size_t)(t + 2) * kstep;
;             const char* a3 = a2 + kstep; const char* b3 = b2 + kstep;
;             if (last && has_next) S.a_ready(nxt);
;             if constexpr (SP2) {
;             PG8_LDB(B0, 0, 0); PG8_LDB(B1, 0, 1); PG8_SCHED; PG8_LDA(At, 0, 0); PG8_STAGE(PG8_SA(1, 1), a1 + hstep, voffA);
;             PG8_WAIT_V(8); PG8_WAIT_L(0); PG8_BAR; PG8_MMA(0, 0, At, B0); PG8_MMA(0, 1, At, B1); PG8_BAR; PG8_SCHED;
;             PG8_LDA(At, 0, 1); PG8_STAGE(PG8_SB(0, 0), b2, voffB); PG8_STAGE(PG8_SB(0, 1), b2 + hstep, voffB); PG8_STAGE(PG8_SA(0, 0), a2, voffA);
;             PG8_WAIT_V(8); PG8_WAIT_L(0); PG8_BAR; PG8_MMA(1, 0, At, B0); PG8_MMA(1, 1, At, B1); PG8_BAR; PG8_SCHED;
;             PG8_LDB(B0, 1, 0); PG8_LDB(B1, 1, 1); PG8_SCHED; PG8_LDA(At, 1, 0); PG8_STAGE(PG8_SA(0, 1), a2 + hstep, voffA);
;             PG8_WAIT_V(8); PG8_WAIT_L(0); PG8_BAR; PG8_MMA(0, 0, At, B0); PG8_MMA(0, 1, At, B1); PG8_BAR; PG8_SCHED;
;             PG8_LDA(At, 1, 1); PG8_STAGE(PG8_SB(1, 0), b3, voffB); PG8_STAGE(PG8_SB(1, 1), b3 + hstep, voffB); PG8_STAGE(PG8_SA(1, 0), a3, voffA);
;             PG8_WAIT_V(8); PG8_WAIT_L(0); PG8_BAR; PG8_MMA(1, 0, At, B0); PG8_MMA(1, 1, At, B1); PG8_BAR; PG8_SCHED;
.LBB0_1547:
	ds_read_b128 v[72:75], v207
	ds_read_b128 v[100:103], v208
	ds_read_b128 v[136:139], v209
	ds_read_b128 v[140:143], v210
	ds_read_b128 v[144:147], v211
	ds_read_b128 v[148:151], v212
	ds_read_b128 v[152:155], v213
	ds_read_b128 v[156:159], v214
	s_add_u32 s6, s4, 0x100
	s_addc_u32 s7, s5, 0
	s_cmp_eq_u32 s78, 12
	s_cselect_b32 s11, s13, s7
	s_cselect_b32 s10, s31, s6
	s_cselect_b32 s1, s29, s75
	s_cselect_b32 s0, s42, s43
	s_mov_b32 m0, s71
	v_lshl_add_u64 v[184:185], s[4:5], 0, v[196:197]
	ds_read_b128 v[160:163], v206
	ds_read_b128 v[164:167], v206 offset:1024
	ds_read_b128 v[168:171], v206 offset:2048
	ds_read_b128 v[172:175], v206 offset:3072
	ds_read_b128 v[176:179], v206 offset:4096
	ds_read_b128 v[180:183], v206 offset:5120
	ds_read_b128 v[226:229], v206 offset:6144
	ds_read_b128 v[230:233], v206 offset:7168
	global_load_lds_dwordx4 v[184:185], off
	v_lshl_add_u64 v[184:185], s[4:5], 0, v[194:195]
	s_mov_b32 m0, s72
	s_nop 0
	global_load_lds_dwordx4 v[184:185], off
	s_waitcnt vmcnt(8)
	s_waitcnt lgkmcnt(0)
	s_setprio 0
	s_barrier
	v_mfma_f32_16x16x32_bf16 v[132:135], v[72:75], v[160:163], v[132:135]
	v_mfma_f32_16x16x32_bf16 v[60:63], v[136:139], v[160:163], v[60:63]
	v_mfma_f32_16x16x32_bf16 v[124:127], v[72:75], v[168:171], v[124:127]
	v_mfma_f32_16x16x32_bf16 v[52:55], v[136:139], v[168:171], v[52:55]
	v_mfma_f32_16x16x32_bf16 v[116:119], v[72:75], v[176:179], v[116:119]
	v_mfma_f32_16x16x32_bf16 v[44:47], v[136:139], v[176:179], v[44:47]
	v_mfma_f32_16x16x32_bf16 v[108:111], v[72:75], v[226:229], v[108:111]
	v_mfma_f32_16x16x32_bf16 v[36:39], v[136:139], v[226:229], v[36:39]
	v_mfma_f32_16x16x32_bf16 v[132:135], v[100:103], v[164:167], v[132:135]
	v_mfma_f32_16x16x32_bf16 v[60:63], v[140:143], v[164:167], v[60:63]
	v_mfma_f32_16x16x32_bf16 v[124:127], v[100:103], v[172:175], v[124:127]
	v_mfma_f32_16x16x32_bf16 v[52:55], v[140:143], v[172:175], v[52:55]
	v_mfma_f32_16x16x32_bf16 v[116:119], v[100:103], v[180:183], v[116:119]
	v_mfma_f32_16x16x32_bf16 v[44:47], v[140:143], v[180:183], v[44:47]
	v_mfma_f32_16x16x32_bf16 v[108:111], v[100:103], v[230:233], v[108:111]
	v_mfma_f32_16x16x32_bf16 v[36:39], v[140:143], v[230:233], v[36:39]
	v_mfma_f32_16x16x32_bf16 v[128:131], v[144:147], v[160:163], v[128:131]
	v_mfma_f32_16x16x32_bf16 v[56:59], v[152:155], v[160:163], v[56:59]
	v_mfma_f32_16x16x32_bf16 v[120:123], v[144:147], v[168:171], v[120:123]
	v_mfma_f32_16x16x32_bf16 v[48:51], v[152:155], v[168:171], v[48:51]
	v_mfma_f32_16x16x32_bf16 v[112:115], v[144:147], v[176:179], v[112:115]
	v_mfma_f32_16x16x32_bf16 v[40:43], v[152:155], v[176:179], v[40:43]
	v_mfma_f32_16x16x32_bf16 v[104:107], v[144:147], v[226:229], v[104:107]
	v_mfma_f32_16x16x32_bf16 v[32:35], v[152:155], v[226:229], v[32:35]
	v_mfma_f32_16x16x32_bf16 v[128:131], v[148:151], v[164:167], v[128:131]
	v_mfma_f32_16x16x32_bf16 v[56:59], v[156:159], v[164:167], v[56:59]
	v_mfma_f32_16x16x32_bf16 v[120:123], v[148:151], v[172:175], v[120:123]
	v_mfma_f32_16x16x32_bf16 v[48:51], v[156:159], v[172:175], v[48:51]
	v_mfma_f32_16x16x32_bf16 v[112:115], v[148:151], v[180:183], v[112:115]
	v_mfma_f32_16x16x32_bf16 v[40:43], v[156:159], v[180:183], v[40:43]
	v_mfma_f32_16x16x32_bf16 v[104:107], v[148:151], v[230:233], v[104:107]
	v_mfma_f32_16x16x32_bf16 v[32:35], v[156:159], v[230:233], v[32:35]
	s_barrier
	s_setprio 1
	s_mov_b32 m0, s39
	v_lshl_add_u64 v[184:185], s[0:1], 0, v[188:189]
	s_add_u32 s4, s0, 0x40000
	ds_read_b128 v[160:163], v206 offset:16384
	ds_read_b128 v[164:167], v206 offset:17408
	ds_read_b128 v[168:171], v206 offset:18432
	ds_read_b128 v[172:175], v206 offset:19456
	ds_read_b128 v[176:179], v206 offset:20480
	ds_read_b128 v[180:183], v206 offset:21504
	ds_read_b128 v[226:229], v206 offset:22528
	ds_read_b128 v[230:233], v206 offset:23552
	global_load_lds_dwordx4 v[184:185], off
	v_lshl_add_u64 v[202:203], s[0:1], 0, v[192:193]
	s_mov_b32 m0, s41
	s_addc_u32 s5, s1, 0
	global_load_lds_dwordx4 v[202:203], off
	v_lshl_add_u64 v[234:235], s[4:5], 0, v[188:189]
	s_mov_b32 m0, s47
	v_lshl_add_u64 v[236:237], s[10:11], 0, v[190:191]
	global_load_lds_dwordx4 v[234:235], off
	v_lshl_add_u64 v[234:235], s[4:5], 0, v[192:193]
	s_mov_b32 m0, s48
	s_nop 0
	global_load_lds_dwordx4 v[234:235], off
	v_lshl_add_u64 v[234:235], s[10:11], 0, v[186:187]
	s_mov_b32 m0, s46
	s_nop 0
	global_load_lds_dwordx4 v[234:235], off
	s_mov_b32 m0, s49
	s_nop 0
	global_load_lds_dwordx4 v[236:237], off
	s_waitcnt vmcnt(8)
	s_waitcnt lgkmcnt(0)
	s_setprio 0
	s_barrier
	v_mfma_f32_16x16x32_bf16 v[96:99], v[72:75], v[160:163], v[96:99]
	v_mfma_f32_16x16x32_bf16 v[28:31], v[136:139], v[160:163], v[28:31]
	v_mfma_f32_16x16x32_bf16 v[88:91], v[72:75], v[168:171], v[88:91]
	v_mfma_f32_16x16x32_bf16 v[20:23], v[136:139], v[168:171], v[20:23]
	v_mfma_f32_16x16x32_bf16 v[80:83], v[72:75], v[176:179], v[80:83]
	v_mfma_f32_16x16x32_bf16 v[12:15], v[136:139], v[176:179], v[12:15]
	v_mfma_f32_16x16x32_bf16 v[68:71], v[72:75], v[226:229], v[68:71]
	v_mfma_f32_16x16x32_bf16 v[4:7], v[136:139], v[226:229], v[4:7]
	v_mfma_f32_16x16x32_bf16 v[96:99], v[100:103], v[164:167], v[96:99]
	v_mfma_f32_16x16x32_bf16 v[28:31], v[140:143], v[164:167], v[28:31]
	v_mfma_f32_16x16x32_bf16 v[88:91], v[100:103], v[172:175], v[88:91]
	v_mfma_f32_16x16x32_bf16 v[20:23], v[140:143], v[172:175], v[20:23]
	v_mfma_f32_16x16x32_bf16 v[80:83], v[100:103], v[180:183], v[80:83]
	v_mfma_f32_16x16x32_bf16 v[12:15], v[140:143], v[180:183], v[12:15]
	v_mfma_f32_16x16x32_bf16 v[68:71], v[100:103], v[230:233], v[68:71]
	v_mfma_f32_16x16x32_bf16 v[4:7], v[140:143], v[230:233], v[4:7]
	v_mfma_f32_16x16x32_bf16 v[24:27], v[152:155], v[160:163], v[24:27]
	v_mfma_f32_16x16x32_bf16 v[84:87], v[144:147], v[168:171], v[84:87]
	v_mfma_f32_16x16x32_bf16 v[16:19], v[152:155], v[168:171], v[16:19]
	v_mfma_f32_16x16x32_bf16 v[76:79], v[144:147], v[176:179], v[76:79]
	v_mfma_f32_16x16x32_bf16 v[8:11], v[152:155], v[176:179], v[8:11]
	v_mfma_f32_16x16x32_bf16 v[64:67], v[144:147], v[226:229], v[64:67]
	v_mfma_f32_16x16x32_bf16 v[0:3], v[152:155], v[226:229], v[0:3]
	v_mfma_f32_16x16x32_bf16 v[72:75], v[144:147], v[160:163], v[92:95]
	v_mfma_f32_16x16x32_bf16 v[24:27], v[156:159], v[164:167], v[24:27]
	v_mfma_f32_16x16x32_bf16 v[84:87], v[148:151], v[172:175], v[84:87]
	v_mfma_f32_16x16x32_bf16 v[16:19], v[156:159], v[172:175], v[16:19]
	v_mfma_f32_16x16x32_bf16 v[76:79], v[148:151], v[180:183], v[76:79]
	v_mfma_f32_16x16x32_bf16 v[8:11], v[156:159], v[180:183], v[8:11]
	v_mfma_f32_16x16x32_bf16 v[64:67], v[148:151], v[230:233], v[64:67]
	v_mfma_f32_16x16x32_bf16 v[0:3], v[156:159], v[230:233], v[0:3]
	v_mfma_f32_16x16x32_bf16 v[72:75], v[148:151], v[164:167], v[72:75]
	s_barrier
; #define PG8_STAGE(bufoff, gbase, voff) do { _Pragma("unroll") for (int _i = 0; _i < 2; ++_i) \
;         __builtin_amdgcn_global_load_lds((const unsigned*)((const char*)(gbase) + (voff)[_i]), (PG8_LAS unsigned*)(lds + (bufoff) + ldsw + _i * 8192), 16, 0, 0); } while (0)
; #define PG8_LDA(dst, b, h) do { _Pragma("unroll") for (int m = 0; m < 4; ++m) _Pragma("unroll") for (int k = 0; k < 2; ++k) dst[m][k] = *(const PG8_LAS bf16x8*)(lds + PG8_SA(b, h) + aoff + m * 2048 + k * 1024); } while (0)
; #define PG8_WAIT_V(n) asm volatile("s_waitcnt vmcnt(" #n ")" ::: "memory")
; #define PG8_WAIT_L(n) asm volatile("s_waitcnt lgkmcnt(" #n ")" ::: "memory")
; #define PG8_BAR __builtin_amdgcn_s_barrier()
; template <class Epi, class Sched, bool ALIGN_EPI = false, bool SP2 = false>
; __device__ __forceinline__ void gemm_phase(PG8_LAS unsigned char* lds, const Gemm g, const Sched& S, const Epi& E, const int tid_arg) {
;     ...
;         for (int t = 0; t < nt; t += 2) {
;             const bool last = (t == nt - 2);
;             const char* a1 = cA + (size_t)(t + 1) * kstep;
;             const char* a2 = last ? nA : cA + (size_t)(t + 2) * kstep; const char* b2 = last ? nB : cB + (size_t)(t + 2) * kstep;
;             const char* a3 = a2 + kstep; const char* b3 = b2 + kstep;
;             if (last && has_next) S.a_ready(nxt);
;             if constexpr (SP2) {
;             PG8_LDB(B0, 0, 0); PG8_LDB(B1, 0, 1); PG8_SCHED; PG8_LDA(At, 0, 0); PG8_STAGE(PG8_SA(1, 1), a1 + hstep, voffA);
;             PG8_WAIT_V(8); PG8_WAIT_L(0); PG8_BAR; PG8_MMA(0, 0, At, B0); PG8_MMA(0, 1, At, B1); PG8_BAR; PG8_SCHED;
;             PG8_LDA(At, 0, 1); PG8_STAGE(PG8_SB(0, 0), b2, voffB); PG8_STAGE(PG8_SB(0, 1), b2 + hstep, voffB); PG8_STAGE(PG8_SA(0, 0), a2, voffA);
;             PG8_WAIT_V(8); PG8_WAIT_L(0); PG8_BAR; PG8_MMA(1, 0, At, B0); PG8_MMA(1, 1, At, B1); PG8_BAR; PG8_SCHED;
;             PG8_LDB(B0, 1, 0); PG8_LDB(B1, 1, 1); PG8_SCHED; PG8_LDA(At, 1, 0); PG8_STAGE(PG8_SA(0, 1), a2 + hstep, voffA);
;             PG8_WAIT_V(8); PG8_WAIT_L(0); PG8_BAR; PG8_MMA(0, 0, At, B0); PG8_MMA(0, 1, At, B1); PG8_BAR; PG8_SCHED;
;             PG8_LDA(At, 1, 1); PG8_STAGE(PG8_SB(1, 0), b3, voffB); PG8_STAGE(PG8_SB(1, 1), b3 + hstep, voffB); PG8_STAGE(PG8_SA(1, 0), a3, voffA);
;             PG8_WAIT_V(8); PG8_WAIT_L(0); PG8_BAR; PG8_MMA(1, 0, At, B0); PG8_MMA(1, 1, At, B1); PG8_BAR; PG8_SCHED;
	s_setprio 1
	ds_read_b128 v[92:95], v215
	ds_read_b128 v[100:103], v216
	ds_read_b128 v[136:139], v217
	ds_read_b128 v[140:143], v218
	ds_read_b128 v[144:147], v219
	ds_read_b128 v[148:151], v220
	ds_read_b128 v[152:155], v221
	ds_read_b128 v[156:159], v222
	s_add_u32 s4, s10, 0x40000
	s_addc_u32 s5, s11, 0
	s_mov_b32 m0, s50
	v_lshl_add_u64 v[238:239], s[4:5], 0, v[186:187]
	ds_read_b128 v[160:163], v206 offset:32768
	ds_read_b128 v[164:167], v206 offset:33792
	ds_read_b128 v[168:171], v206 offset:34816
	ds_read_b128 v[172:175], v206 offset:35840
	ds_read_b128 v[176:179], v206 offset:36864
	ds_read_b128 v[180:183], v206 offset:37888
	ds_read_b128 v[226:229], v206 offset:38912
	ds_read_b128 v[230:233], v206 offset:39936
	global_load_lds_dwordx4 v[238:239], off
	v_lshl_add_u64 v[238:239], s[4:5], 0, v[190:191]
	s_mov_b32 m0, s51
	s_nop 0
	global_load_lds_dwordx4 v[238:239], off
	s_waitcnt vmcnt(8)
	s_waitcnt lgkmcnt(0)
	s_setprio 0
	s_barrier
	v_mfma_f32_16x16x32_bf16 v[132:135], v[92:95], v[160:163], v[132:135]
	v_mfma_f32_16x16x32_bf16 v[60:63], v[136:139], v[160:163], v[60:63]
	v_mfma_f32_16x16x32_bf16 v[124:127], v[92:95], v[168:171], v[124:127]
	v_mfma_f32_16x16x32_bf16 v[52:55], v[136:139], v[168:171], v[52:55]
	v_mfma_f32_16x16x32_bf16 v[116:119], v[92:95], v[176:179], v[116:119]
	v_mfma_f32_16x16x32_bf16 v[44:47], v[136:139], v[176:179], v[44:47]
	v_mfma_f32_16x16x32_bf16 v[108:111], v[92:95], v[226:229], v[108:111]
	v_mfma_f32_16x16x32_bf16 v[36:39], v[136:139], v[226:229], v[36:39]
	v_mfma_f32_16x16x32_bf16 v[132:135], v[100:103], v[164:167], v[132:135]
	v_mfma_f32_16x16x32_bf16 v[60:63], v[140:143], v[164:167], v[60:63]
	v_mfma_f32_16x16x32_bf16 v[124:127], v[100:103], v[172:175], v[124:127]
	v_mfma_f32_16x16x32_bf16 v[52:55], v[140:143], v[172:175], v[52:55]
	v_mfma_f32_16x16x32_bf16 v[116:119], v[100:103], v[180:183], v[116:119]
	v_mfma_f32_16x16x32_bf16 v[44:47], v[140:143], v[180:183], v[44:47]
	v_mfma_f32_16x16x32_bf16 v[108:111], v[100:103], v[230:233], v[108:111]
	v_mfma_f32_16x16x32_bf16 v[36:39], v[140:143], v[230:233], v[36:39]
	v_mfma_f32_16x16x32_bf16 v[128:131], v[144:147], v[160:163], v[128:131]
	v_mfma_f32_16x16x32_bf16 v[56:59], v[152:155], v[160:163], v[56:59]
	v_mfma_f32_16x16x32_bf16 v[120:123], v[144:147], v[168:171], v[120:123]
	v_mfma_f32_16x16x32_bf16 v[48:51], v[152:155], v[168:171], v[48:51]
	v_mfma_f32_16x16x32_bf16 v[112:115], v[144:147], v[176:179], v[112:115]
	v_mfma_f32_16x16x32_bf16 v[40:43], v[152:155], v[176:179], v[40:43]
	v_mfma_f32_16x16x32_bf16 v[104:107], v[144:147], v[226:229], v[104:107]
	v_mfma_f32_16x16x32_bf16 v[32:35], v[152:155], v[226:229], v[32:35]
	v_mfma_f32_16x16x32_bf16 v[128:131], v[148:151], v[164:167], v[128:131]
	v_mfma_f32_16x16x32_bf16 v[56:59], v[156:159], v[164:167], v[56:59]
	v_mfma_f32_16x16x32_bf16 v[120:123], v[148:151], v[172:175], v[120:123]
	v_mfma_f32_16x16x32_bf16 v[48:51], v[156:159], v[172:175], v[48:51]
	v_mfma_f32_16x16x32_bf16 v[112:115], v[148:151], v[180:183], v[112:115]
	v_mfma_f32_16x16x32_bf16 v[40:43], v[156:159], v[180:183], v[40:43]
	v_mfma_f32_16x16x32_bf16 v[104:107], v[148:151], v[230:233], v[104:107]
	v_mfma_f32_16x16x32_bf16 v[32:35], v[156:159], v[230:233], v[32:35]
	s_barrier
	s_setprio 1
	s_mov_b32 m0, s60
	v_lshl_add_u64 v[184:185], v[184:185], 0, s[20:21]
	s_add_u32 s0, s0, 0x40080
	ds_read_b128 v[160:163], v206 offset:49152
	ds_read_b128 v[164:167], v206 offset:50176
	ds_read_b128 v[168:171], v206 offset:51200
	ds_read_b128 v[172:175], v206 offset:52224
	ds_read_b128 v[176:179], v206 offset:53248
	ds_read_b128 v[180:183], v206 offset:54272
	ds_read_b128 v[226:229], v206 offset:55296
	ds_read_b128 v[230:233], v206 offset:56320
	global_load_lds_dwordx4 v[184:185], off
	v_lshl_add_u64 v[184:185], v[202:203], 0, s[20:21]
	s_mov_b32 m0, s61
	s_addc_u32 s1, s1, 0
	global_load_lds_dwordx4 v[184:185], off
	v_lshl_add_u64 v[184:185], s[0:1], 0, v[188:189]
	s_mov_b32 m0, s64
	s_nop 0
	global_load_lds_dwordx4 v[184:185], off
	v_lshl_add_u64 v[184:185], s[0:1], 0, v[192:193]
	s_mov_b32 m0, s65
	s_nop 0
	global_load_lds_dwordx4 v[184:185], off
	v_lshl_add_u64 v[184:185], v[234:235], 0, s[20:21]
	s_mov_b32 m0, s62
	s_nop 0
	global_load_lds_dwordx4 v[184:185], off
	v_lshl_add_u64 v[184:185], v[236:237], 0, s[20:21]
	s_mov_b32 m0, s63
	s_nop 0
	global_load_lds_dwordx4 v[184:185], off
	s_waitcnt vmcnt(8)
	s_waitcnt lgkmcnt(0)
	s_setprio 0
	s_barrier
	v_mfma_f32_16x16x32_bf16 v[96:99], v[92:95], v[160:163], v[96:99]
	v_mfma_f32_16x16x32_bf16 v[28:31], v[136:139], v[160:163], v[28:31]
	v_mfma_f32_16x16x32_bf16 v[88:91], v[92:95], v[168:171], v[88:91]
	v_mfma_f32_16x16x32_bf16 v[20:23], v[136:139], v[168:171], v[20:23]
	v_mfma_f32_16x16x32_bf16 v[80:83], v[92:95], v[176:179], v[80:83]
	v_mfma_f32_16x16x32_bf16 v[12:15], v[136:139], v[176:179], v[12:15]
	v_mfma_f32_16x16x32_bf16 v[68:71], v[92:95], v[226:229], v[68:71]
	v_mfma_f32_16x16x32_bf16 v[4:7], v[136:139], v[226:229], v[4:7]
	v_mfma_f32_16x16x32_bf16 v[96:99], v[100:103], v[164:167], v[96:99]
	v_mfma_f32_16x16x32_bf16 v[28:31], v[140:143], v[164:167], v[28:31]
	v_mfma_f32_16x16x32_bf16 v[88:91], v[100:103], v[172:175], v[88:91]
	v_mfma_f32_16x16x32_bf16 v[20:23], v[140:143], v[172:175], v[20:23]
	v_mfma_f32_16x16x32_bf16 v[80:83], v[100:103], v[180:183], v[80:83]
	v_mfma_f32_16x16x32_bf16 v[12:15], v[140:143], v[180:183], v[12:15]
	v_mfma_f32_16x16x32_bf16 v[68:71], v[100:103], v[230:233], v[68:71]
	v_mfma_f32_16x16x32_bf16 v[4:7], v[140:143], v[230:233], v[4:7]
	v_mfma_f32_16x16x32_bf16 v[72:75], v[144:147], v[160:163], v[72:75]
	v_mfma_f32_16x16x32_bf16 v[92:95], v[148:151], v[164:167], v[72:75]
	v_mfma_f32_16x16x32_bf16 v[72:75], v[144:147], v[168:171], v[84:87]
	v_mfma_f32_16x16x32_bf16 v[24:27], v[152:155], v[160:163], v[24:27]
	v_mfma_f32_16x16x32_bf16 v[84:87], v[148:151], v[172:175], v[72:75]
	v_mfma_f32_16x16x32_bf16 v[16:19], v[152:155], v[168:171], v[16:19]
	v_mfma_f32_16x16x32_bf16 v[72:75], v[144:147], v[176:179], v[76:79]
	v_mfma_f32_16x16x32_bf16 v[8:11], v[152:155], v[176:179], v[8:11]
	v_mfma_f32_16x16x32_bf16 v[64:67], v[144:147], v[226:229], v[64:67]
	v_mfma_f32_16x16x32_bf16 v[0:3], v[152:155], v[226:229], v[0:3]
	v_mfma_f32_16x16x32_bf16 v[24:27], v[156:159], v[164:167], v[24:27]
	v_mfma_f32_16x16x32_bf16 v[16:19], v[156:159], v[172:175], v[16:19]
	v_mfma_f32_16x16x32_bf16 v[76:79], v[148:151], v[180:183], v[72:75]
	v_mfma_f32_16x16x32_bf16 v[8:11], v[156:159], v[180:183], v[8:11]
	v_mfma_f32_16x16x32_bf16 v[64:67], v[148:151], v[230:233], v[64:67]
	v_mfma_f32_16x16x32_bf16 v[0:3], v[156:159], v[230:233], v[0:3]
	s_barrier
	s_setprio 1
	s_add_i32 s78, s78, 2
	s_add_u32 s43, s43, 0x100
	s_addc_u32 s75, s75, 0
	s_cmp_gt_u32 s78, 13
	s_mov_b64 s[4:5], s[6:7]
	s_cbranch_scc0 .LBB0_1547
	s_setprio 0
	s_and_b64 vcc, exec, s[22:23]
	s_cbranch_vccz .LBB0_1550
	s_barrier

; #define PG8_STAGE(bufoff, gbase, voff) do { _Pragma("unroll") for (int _i = 0; _i < 2; ++_i) \
;         __builtin_amdgcn_global_load_lds((const unsigned*)((const char*)(gbase) + (voff)[_i]), (PG8_LAS unsigned*)(lds + (bufoff) + ldsw + _i * 8192), 16, 0, 0); } while (0)
; #define PG8_LDA(dst, b, h) do { _Pragma("unroll") for (int m = 0; m < 4; ++m) _Pragma("unroll") for (int k = 0; k < 2; ++k) dst[m][k] = *(const PG8_LAS bf16x8*)(lds + PG8_SA(b, h) + aoff + m * 2048 + k * 1024); } while (0)
; #define PG8_WAIT_V(n) asm volatile("s_waitcnt vmcnt(" #n ")" ::: "memory")
; #define PG8_WAIT_L(n) asm volatile("s_waitcnt lgkmcnt(" #n ")" ::: "memory")
; #define PG8_BAR __builtin_amdgcn_s_barrier()
; template <class Epi, class Sched, bool ALIGN_EPI = false, bool SP2 = false>
; __device__ __forceinline__ void gemm_phase(PG8_LAS unsigned char* lds, const Gemm g, const Sched& S, const Epi& E, const int tid_arg) {
;     ...
;         for (int t = 0; t < nt; t += 2) {
;             const bool last = (t == nt - 2);
;             const char* a1 = cA + (size_t)(t + 1) * kstep;
;             const char* a2 = last ? nA : cA + (size_t)(t + 2) * kstep; const char* b2 = last ? nB : cB + (size_t)(t + 2) * kstep;
;             const char* a3 = a2 + kstep; const char* b3 = b2 + kstep;
;             if (last && has_next) S.a_ready(nxt);
;             if constexpr (SP2) {
;             PG8_LDB(B0, 0, 0); PG8_LDB(B1, 0, 1); PG8_SCHED; PG8_LDA(At, 0, 0); PG8_STAGE(PG8_SA(1, 1), a1 + hstep, voffA);
;             PG8_WAIT_V(8); PG8_WAIT_L(0); PG8_BAR; PG8_MMA(0, 0, At, B0); PG8_MMA(0, 1, At, B1); PG8_BAR; PG8_SCHED;
;             PG8_LDA(At, 0, 1); PG8_STAGE(PG8_SB(0, 0), b2, voffB); PG8_STAGE(PG8_SB(0, 1), b2 + hstep, voffB); PG8_STAGE(PG8_SA(0, 0), a2, voffA);
;             PG8_WAIT_V(8); PG8_WAIT_L(0); PG8_BAR; PG8_MMA(1, 0, At, B0); PG8_MMA(1, 1, At, B1); PG8_BAR; PG8_SCHED;
;             PG8_LDB(B0, 1, 0); PG8_LDB(B1, 1, 1); PG8_SCHED; PG8_LDA(At, 1, 0); PG8_STAGE(PG8_SA(0, 1), a2 + hstep, voffA);
;             PG8_WAIT_V(8); PG8_WAIT_L(0); PG8_BAR; PG8_MMA(0, 0, At, B0); PG8_MMA(0, 1, At, B1); PG8_BAR; PG8_SCHED;
;             PG8_LDA(At, 1, 1); PG8_STAGE(PG8_SB(1, 0), b3, voffB); PG8_STAGE(PG8_SB(1, 1), b3 + hstep, voffB); PG8_STAGE(PG8_SA(1, 0), a3, voffA);
;             PG8_WAIT_V(8); PG8_WAIT_L(0); PG8_BAR; PG8_MMA(1, 0, At, B0); PG8_MMA(1, 1, At, B1); PG8_BAR; PG8_SCHED;
.LBB0_1733:
	ds_read_b128 v[144:147], v151
	ds_read_b128 v[168:171], v152
	ds_read_b128 v[172:175], v153
	ds_read_b128 v[176:179], v154
	ds_read_b128 v[180:183], v155
	ds_read_b128 v[184:187], v156
	ds_read_b128 v[188:191], v157
	ds_read_b128 v[192:195], v158
	s_add_u32 s22, s4, 0x100
	s_addc_u32 s23, s5, 0
	s_cmp_eq_u32 s57, 40
	s_cselect_b32 s25, s9, s23
	s_cselect_b32 s24, s8, s22
	s_cselect_b32 s1, s21, s56
	s_cselect_b32 s0, s20, s55
	s_mov_b32 m0, s48
	v_lshl_add_u64 v[228:229], s[4:5], 0, v[138:139]
	ds_read_b128 v[196:199], v150
	ds_read_b128 v[200:203], v150 offset:1024
	ds_read_b128 v[204:207], v150 offset:2048
	ds_read_b128 v[208:211], v150 offset:3072
	ds_read_b128 v[212:215], v150 offset:4096
	ds_read_b128 v[216:219], v150 offset:5120
	ds_read_b128 v[220:223], v150 offset:6144
	ds_read_b128 v[224:227], v150 offset:7168
	global_load_lds_dwordx4 v[228:229], off
	v_lshl_add_u64 v[228:229], s[4:5], 0, v[136:137]
	s_mov_b32 m0, s49
	s_nop 0
	global_load_lds_dwordx4 v[228:229], off
	s_waitcnt vmcnt(8)
	s_waitcnt lgkmcnt(0)
	s_setprio 0
	s_barrier
	v_mfma_f32_16x16x32_bf16 v[124:127], v[144:147], v[196:199], v[124:127]
	v_mfma_f32_16x16x32_bf16 v[120:123], v[172:175], v[196:199], v[120:123]
	v_mfma_f32_16x16x32_bf16 v[108:111], v[144:147], v[204:207], v[108:111]
	v_mfma_f32_16x16x32_bf16 v[104:107], v[172:175], v[204:207], v[104:107]
	v_mfma_f32_16x16x32_bf16 v[92:95], v[144:147], v[212:215], v[92:95]
	v_mfma_f32_16x16x32_bf16 v[88:91], v[172:175], v[212:215], v[88:91]
	v_mfma_f32_16x16x32_bf16 v[76:79], v[144:147], v[220:223], v[76:79]
	v_mfma_f32_16x16x32_bf16 v[72:75], v[172:175], v[220:223], v[72:75]
	v_mfma_f32_16x16x32_bf16 v[124:127], v[168:171], v[200:203], v[124:127]
	v_mfma_f32_16x16x32_bf16 v[120:123], v[176:179], v[200:203], v[120:123]
	v_mfma_f32_16x16x32_bf16 v[108:111], v[168:171], v[208:211], v[108:111]
	v_mfma_f32_16x16x32_bf16 v[104:107], v[176:179], v[208:211], v[104:107]
	v_mfma_f32_16x16x32_bf16 v[92:95], v[168:171], v[216:219], v[92:95]
	v_mfma_f32_16x16x32_bf16 v[88:91], v[176:179], v[216:219], v[88:91]
	v_mfma_f32_16x16x32_bf16 v[76:79], v[168:171], v[224:227], v[76:79]
	v_mfma_f32_16x16x32_bf16 v[72:75], v[176:179], v[224:227], v[72:75]
	v_mfma_f32_16x16x32_bf16 v[116:119], v[180:183], v[196:199], v[116:119]
	v_mfma_f32_16x16x32_bf16 v[112:115], v[188:191], v[196:199], v[112:115]
	v_mfma_f32_16x16x32_bf16 v[100:103], v[180:183], v[204:207], v[100:103]
	v_mfma_f32_16x16x32_bf16 v[96:99], v[188:191], v[204:207], v[96:99]
	v_mfma_f32_16x16x32_bf16 v[84:87], v[180:183], v[212:215], v[84:87]
	v_mfma_f32_16x16x32_bf16 v[80:83], v[188:191], v[212:215], v[80:83]
	v_mfma_f32_16x16x32_bf16 v[68:71], v[180:183], v[220:223], v[68:71]
	v_mfma_f32_16x16x32_bf16 v[64:67], v[188:191], v[220:223], v[64:67]
	v_mfma_f32_16x16x32_bf16 v[116:119], v[184:187], v[200:203], v[116:119]
	v_mfma_f32_16x16x32_bf16 v[112:115], v[192:195], v[200:203], v[112:115]
	v_mfma_f32_16x16x32_bf16 v[100:103], v[184:187], v[208:211], v[100:103]
	v_mfma_f32_16x16x32_bf16 v[96:99], v[192:195], v[208:211], v[96:99]
	v_mfma_f32_16x16x32_bf16 v[84:87], v[184:187], v[216:219], v[84:87]
	v_mfma_f32_16x16x32_bf16 v[80:83], v[192:195], v[216:219], v[80:83]
	v_mfma_f32_16x16x32_bf16 v[68:71], v[184:187], v[224:227], v[68:71]
	v_mfma_f32_16x16x32_bf16 v[64:67], v[192:195], v[224:227], v[64:67]
	s_barrier
	s_setprio 1
	s_mov_b32 m0, s29
	v_lshl_add_u64 v[228:229], s[0:1], 0, v[130:131]
	s_add_u32 s4, s0, 0xb0000
	ds_read_b128 v[196:199], v150 offset:16384
	ds_read_b128 v[200:203], v150 offset:17408
	ds_read_b128 v[204:207], v150 offset:18432
	ds_read_b128 v[208:211], v150 offset:19456
	ds_read_b128 v[212:215], v150 offset:20480
	ds_read_b128 v[216:219], v150 offset:21504
	ds_read_b128 v[220:223], v150 offset:22528
	ds_read_b128 v[224:227], v150 offset:23552
	global_load_lds_dwordx4 v[228:229], off
	v_lshl_add_u64 v[230:231], s[0:1], 0, v[134:135]
	s_mov_b32 m0, s30
	s_addc_u32 s5, s1, 0
	global_load_lds_dwordx4 v[230:231], off
	v_lshl_add_u64 v[232:233], s[4:5], 0, v[130:131]
	s_mov_b32 m0, s31
	v_lshl_add_u64 v[234:235], s[24:25], 0, v[132:133]
	global_load_lds_dwordx4 v[232:233], off
	v_lshl_add_u64 v[232:233], s[4:5], 0, v[134:135]
	s_mov_b32 m0, s33
	s_nop 0
	global_load_lds_dwordx4 v[232:233], off
	v_lshl_add_u64 v[232:233], s[24:25], 0, v[128:129]
	s_mov_b32 m0, s28
	s_nop 0
	global_load_lds_dwordx4 v[232:233], off
	s_mov_b32 m0, s34
	s_nop 0
	global_load_lds_dwordx4 v[234:235], off
	s_waitcnt vmcnt(8)
	s_waitcnt lgkmcnt(0)
	s_setprio 0
	s_barrier
	v_mfma_f32_16x16x32_bf16 v[60:63], v[144:147], v[196:199], v[60:63]
	v_mfma_f32_16x16x32_bf16 v[56:59], v[172:175], v[196:199], v[56:59]
	v_mfma_f32_16x16x32_bf16 v[44:47], v[144:147], v[204:207], v[44:47]
	v_mfma_f32_16x16x32_bf16 v[40:43], v[172:175], v[204:207], v[40:43]
	v_mfma_f32_16x16x32_bf16 v[28:31], v[144:147], v[212:215], v[28:31]
	v_mfma_f32_16x16x32_bf16 v[24:27], v[172:175], v[212:215], v[24:27]
	v_mfma_f32_16x16x32_bf16 v[12:15], v[144:147], v[220:223], v[12:15]
	v_mfma_f32_16x16x32_bf16 v[8:11], v[172:175], v[220:223], v[8:11]
	v_mfma_f32_16x16x32_bf16 v[60:63], v[168:171], v[200:203], v[60:63]
	v_mfma_f32_16x16x32_bf16 v[56:59], v[176:179], v[200:203], v[56:59]
	v_mfma_f32_16x16x32_bf16 v[44:47], v[168:171], v[208:211], v[44:47]
	v_mfma_f32_16x16x32_bf16 v[40:43], v[176:179], v[208:211], v[40:43]
	v_mfma_f32_16x16x32_bf16 v[28:31], v[168:171], v[216:219], v[28:31]
	v_mfma_f32_16x16x32_bf16 v[24:27], v[176:179], v[216:219], v[24:27]
	v_mfma_f32_16x16x32_bf16 v[12:15], v[168:171], v[224:227], v[12:15]
	v_mfma_f32_16x16x32_bf16 v[8:11], v[176:179], v[224:227], v[8:11]
	v_mfma_f32_16x16x32_bf16 v[52:55], v[180:183], v[196:199], v[52:55]
	v_mfma_f32_16x16x32_bf16 v[48:51], v[188:191], v[196:199], v[48:51]
	v_mfma_f32_16x16x32_bf16 v[36:39], v[180:183], v[204:207], v[36:39]
	v_mfma_f32_16x16x32_bf16 v[32:35], v[188:191], v[204:207], v[32:35]
	v_mfma_f32_16x16x32_bf16 v[20:23], v[180:183], v[212:215], v[20:23]
	v_mfma_f32_16x16x32_bf16 v[16:19], v[188:191], v[212:215], v[16:19]
	v_mfma_f32_16x16x32_bf16 v[4:7], v[180:183], v[220:223], v[4:7]
	v_mfma_f32_16x16x32_bf16 v[0:3], v[188:191], v[220:223], v[0:3]
	v_mfma_f32_16x16x32_bf16 v[52:55], v[184:187], v[200:203], v[52:55]
	v_mfma_f32_16x16x32_bf16 v[48:51], v[192:195], v[200:203], v[48:51]
	v_mfma_f32_16x16x32_bf16 v[36:39], v[184:187], v[208:211], v[36:39]
	v_mfma_f32_16x16x32_bf16 v[32:35], v[192:195], v[208:211], v[32:35]
	v_mfma_f32_16x16x32_bf16 v[20:23], v[184:187], v[216:219], v[20:23]
	v_mfma_f32_16x16x32_bf16 v[16:19], v[192:195], v[216:219], v[16:19]
	v_mfma_f32_16x16x32_bf16 v[4:7], v[184:187], v[224:227], v[4:7]
	v_mfma_f32_16x16x32_bf16 v[0:3], v[192:195], v[224:227], v[0:3]
	s_barrier
; #define PG8_STAGE(bufoff, gbase, voff) do { _Pragma("unroll") for (int _i = 0; _i < 2; ++_i) \
;         __builtin_amdgcn_global_load_lds((const unsigned*)((const char*)(gbase) + (voff)[_i]), (PG8_LAS unsigned*)(lds + (bufoff) + ldsw + _i * 8192), 16, 0, 0); } while (0)
; #define PG8_LDA(dst, b, h) do { _Pragma("unroll") for (int m = 0; m < 4; ++m) _Pragma("unroll") for (int k = 0; k < 2; ++k) dst[m][k] = *(const PG8_LAS bf16x8*)(lds + PG8_SA(b, h) + aoff + m * 2048 + k * 1024); } while (0)
; #define PG8_WAIT_V(n) asm volatile("s_waitcnt vmcnt(" #n ")" ::: "memory")
; #define PG8_WAIT_L(n) asm volatile("s_waitcnt lgkmcnt(" #n ")" ::: "memory")
; #define PG8_BAR __builtin_amdgcn_s_barrier()
; template <class Epi, class Sched, bool ALIGN_EPI = false, bool SP2 = false>
; __device__ __forceinline__ void gemm_phase(PG8_LAS unsigned char* lds, const Gemm g, const Sched& S, const Epi& E, const int tid_arg) {
;     ...
;         for (int t = 0; t < nt; t += 2) {
;             const bool last = (t == nt - 2);
;             const char* a1 = cA + (size_t)(t + 1) * kstep;
;             const char* a2 = last ? nA : cA + (size_t)(t + 2) * kstep; const char* b2 = last ? nB : cB + (size_t)(t + 2) * kstep;
;             const char* a3 = a2 + kstep; const char* b3 = b2 + kstep;
;             if (last && has_next) S.a_ready(nxt);
;             if constexpr (SP2) {
;             PG8_LDB(B0, 0, 0); PG8_LDB(B1, 0, 1); PG8_SCHED; PG8_LDA(At, 0, 0); PG8_STAGE(PG8_SA(1, 1), a1 + hstep, voffA);
;             PG8_WAIT_V(8); PG8_WAIT_L(0); PG8_BAR; PG8_MMA(0, 0, At, B0); PG8_MMA(0, 1, At, B1); PG8_BAR; PG8_SCHED;
;             PG8_LDA(At, 0, 1); PG8_STAGE(PG8_SB(0, 0), b2, voffB); PG8_STAGE(PG8_SB(0, 1), b2 + hstep, voffB); PG8_STAGE(PG8_SA(0, 0), a2, voffA);
;             PG8_WAIT_V(8); PG8_WAIT_L(0); PG8_BAR; PG8_MMA(1, 0, At, B0); PG8_MMA(1, 1, At, B1); PG8_BAR; PG8_SCHED;
;             PG8_LDB(B0, 1, 0); PG8_LDB(B1, 1, 1); PG8_SCHED; PG8_LDA(At, 1, 0); PG8_STAGE(PG8_SA(0, 1), a2 + hstep, voffA);
;             PG8_WAIT_V(8); PG8_WAIT_L(0); PG8_BAR; PG8_MMA(0, 0, At, B0); PG8_MMA(0, 1, At, B1); PG8_BAR; PG8_SCHED;
;             PG8_LDA(At, 1, 1); PG8_STAGE(PG8_SB(1, 0), b3, voffB); PG8_STAGE(PG8_SB(1, 1), b3 + hstep, voffB); PG8_STAGE(PG8_SA(1, 0), a3, voffA);
;             PG8_WAIT_V(8); PG8_WAIT_L(0); PG8_BAR; PG8_MMA(1, 0, At, B0); PG8_MMA(1, 1, At, B1); PG8_BAR; PG8_SCHED;
	s_setprio 1
	ds_read_b128 v[144:147], v159
	ds_read_b128 v[168:171], v160
	ds_read_b128 v[172:175], v161
	ds_read_b128 v[176:179], v162
	ds_read_b128 v[180:183], v163
	ds_read_b128 v[184:187], v164
	ds_read_b128 v[188:191], v165
	ds_read_b128 v[192:195], v166
	s_add_u32 s4, s24, 0xb0000
	s_addc_u32 s5, s25, 0
	s_mov_b32 m0, s35
	v_lshl_add_u64 v[236:237], s[4:5], 0, v[128:129]
	ds_read_b128 v[196:199], v150 offset:32768
	ds_read_b128 v[200:203], v150 offset:33792
	ds_read_b128 v[204:207], v150 offset:34816
	ds_read_b128 v[208:211], v150 offset:35840
	ds_read_b128 v[212:215], v150 offset:36864
	ds_read_b128 v[216:219], v150 offset:37888
	ds_read_b128 v[220:223], v150 offset:38912
	ds_read_b128 v[224:227], v150 offset:39936
	global_load_lds_dwordx4 v[236:237], off
	v_lshl_add_u64 v[236:237], s[4:5], 0, v[132:133]
	s_mov_b32 m0, s36
	s_nop 0
	global_load_lds_dwordx4 v[236:237], off
	s_waitcnt vmcnt(8)
	s_waitcnt lgkmcnt(0)
	s_setprio 0
	s_barrier
	v_mfma_f32_16x16x32_bf16 v[124:127], v[144:147], v[196:199], v[124:127]
	v_mfma_f32_16x16x32_bf16 v[120:123], v[172:175], v[196:199], v[120:123]
	v_mfma_f32_16x16x32_bf16 v[108:111], v[144:147], v[204:207], v[108:111]
	v_mfma_f32_16x16x32_bf16 v[104:107], v[172:175], v[204:207], v[104:107]
	v_mfma_f32_16x16x32_bf16 v[92:95], v[144:147], v[212:215], v[92:95]
	v_mfma_f32_16x16x32_bf16 v[88:91], v[172:175], v[212:215], v[88:91]
	v_mfma_f32_16x16x32_bf16 v[76:79], v[144:147], v[220:223], v[76:79]
	v_mfma_f32_16x16x32_bf16 v[72:75], v[172:175], v[220:223], v[72:75]
	v_mfma_f32_16x16x32_bf16 v[124:127], v[168:171], v[200:203], v[124:127]
	v_mfma_f32_16x16x32_bf16 v[120:123], v[176:179], v[200:203], v[120:123]
	v_mfma_f32_16x16x32_bf16 v[108:111], v[168:171], v[208:211], v[108:111]
	v_mfma_f32_16x16x32_bf16 v[104:107], v[176:179], v[208:211], v[104:107]
	v_mfma_f32_16x16x32_bf16 v[92:95], v[168:171], v[216:219], v[92:95]
	v_mfma_f32_16x16x32_bf16 v[88:91], v[176:179], v[216:219], v[88:91]
	v_mfma_f32_16x16x32_bf16 v[76:79], v[168:171], v[224:227], v[76:79]
	v_mfma_f32_16x16x32_bf16 v[72:75], v[176:179], v[224:227], v[72:75]
	v_mfma_f32_16x16x32_bf16 v[116:119], v[180:183], v[196:199], v[116:119]
	v_mfma_f32_16x16x32_bf16 v[112:115], v[188:191], v[196:199], v[112:115]
	v_mfma_f32_16x16x32_bf16 v[100:103], v[180:183], v[204:207], v[100:103]
	v_mfma_f32_16x16x32_bf16 v[96:99], v[188:191], v[204:207], v[96:99]
	v_mfma_f32_16x16x32_bf16 v[84:87], v[180:183], v[212:215], v[84:87]
	v_mfma_f32_16x16x32_bf16 v[80:83], v[188:191], v[212:215], v[80:83]
	v_mfma_f32_16x16x32_bf16 v[68:71], v[180:183], v[220:223], v[68:71]
	v_mfma_f32_16x16x32_bf16 v[64:67], v[188:191], v[220:223], v[64:67]
	v_mfma_f32_16x16x32_bf16 v[116:119], v[184:187], v[200:203], v[116:119]
	v_mfma_f32_16x16x32_bf16 v[112:115], v[192:195], v[200:203], v[112:115]
	v_mfma_f32_16x16x32_bf16 v[100:103], v[184:187], v[208:211], v[100:103]
	v_mfma_f32_16x16x32_bf16 v[96:99], v[192:195], v[208:211], v[96:99]
	v_mfma_f32_16x16x32_bf16 v[84:87], v[184:187], v[216:219], v[84:87]
	v_mfma_f32_16x16x32_bf16 v[80:83], v[192:195], v[216:219], v[80:83]
	v_mfma_f32_16x16x32_bf16 v[68:71], v[184:187], v[224:227], v[68:71]
	v_mfma_f32_16x16x32_bf16 v[64:67], v[192:195], v[224:227], v[64:67]
	s_barrier
	s_setprio 1
	s_mov_b32 m0, s40
	v_lshl_add_u64 v[228:229], v[228:229], 0, s[16:17]
	s_add_u32 s0, s0, 0xb0080
	ds_read_b128 v[196:199], v150 offset:49152
	ds_read_b128 v[200:203], v150 offset:50176
	ds_read_b128 v[204:207], v150 offset:51200
	ds_read_b128 v[208:211], v150 offset:52224
	ds_read_b128 v[212:215], v150 offset:53248
	ds_read_b128 v[216:219], v150 offset:54272
	ds_read_b128 v[220:223], v150 offset:55296
	ds_read_b128 v[224:227], v150 offset:56320
	global_load_lds_dwordx4 v[228:229], off
	v_lshl_add_u64 v[228:229], v[230:231], 0, s[16:17]
	s_mov_b32 m0, s41
	s_addc_u32 s1, s1, 0
	global_load_lds_dwordx4 v[228:229], off
	v_lshl_add_u64 v[228:229], s[0:1], 0, v[130:131]
	s_mov_b32 m0, s44
	s_nop 0
	global_load_lds_dwordx4 v[228:229], off
	v_lshl_add_u64 v[228:229], s[0:1], 0, v[134:135]
	s_mov_b32 m0, s45
	s_nop 0
	global_load_lds_dwordx4 v[228:229], off
	v_lshl_add_u64 v[228:229], v[232:233], 0, s[16:17]
	s_mov_b32 m0, s42
	s_nop 0
	global_load_lds_dwordx4 v[228:229], off
	v_lshl_add_u64 v[228:229], v[234:235], 0, s[16:17]
	s_mov_b32 m0, s43
	s_nop 0
	global_load_lds_dwordx4 v[228:229], off
	s_waitcnt vmcnt(8)
	s_waitcnt lgkmcnt(0)
	s_setprio 0
	s_barrier
	v_mfma_f32_16x16x32_bf16 v[60:63], v[144:147], v[196:199], v[60:63]
	v_mfma_f32_16x16x32_bf16 v[56:59], v[172:175], v[196:199], v[56:59]
	v_mfma_f32_16x16x32_bf16 v[44:47], v[144:147], v[204:207], v[44:47]
	v_mfma_f32_16x16x32_bf16 v[40:43], v[172:175], v[204:207], v[40:43]
	v_mfma_f32_16x16x32_bf16 v[28:31], v[144:147], v[212:215], v[28:31]
	v_mfma_f32_16x16x32_bf16 v[24:27], v[172:175], v[212:215], v[24:27]
	v_mfma_f32_16x16x32_bf16 v[12:15], v[144:147], v[220:223], v[12:15]
	v_mfma_f32_16x16x32_bf16 v[8:11], v[172:175], v[220:223], v[8:11]
	v_mfma_f32_16x16x32_bf16 v[60:63], v[168:171], v[200:203], v[60:63]
	v_mfma_f32_16x16x32_bf16 v[56:59], v[176:179], v[200:203], v[56:59]
	v_mfma_f32_16x16x32_bf16 v[44:47], v[168:171], v[208:211], v[44:47]
	v_mfma_f32_16x16x32_bf16 v[40:43], v[176:179], v[208:211], v[40:43]
	v_mfma_f32_16x16x32_bf16 v[28:31], v[168:171], v[216:219], v[28:31]
	v_mfma_f32_16x16x32_bf16 v[24:27], v[176:179], v[216:219], v[24:27]
	v_mfma_f32_16x16x32_bf16 v[12:15], v[168:171], v[224:227], v[12:15]
	v_mfma_f32_16x16x32_bf16 v[8:11], v[176:179], v[224:227], v[8:11]
	v_mfma_f32_16x16x32_bf16 v[52:55], v[180:183], v[196:199], v[52:55]
	v_mfma_f32_16x16x32_bf16 v[48:51], v[188:191], v[196:199], v[48:51]
	v_mfma_f32_16x16x32_bf16 v[36:39], v[180:183], v[204:207], v[36:39]
	v_mfma_f32_16x16x32_bf16 v[32:35], v[188:191], v[204:207], v[32:35]
	v_mfma_f32_16x16x32_bf16 v[20:23], v[180:183], v[212:215], v[20:23]
	v_mfma_f32_16x16x32_bf16 v[16:19], v[188:191], v[212:215], v[16:19]
	v_mfma_f32_16x16x32_bf16 v[4:7], v[180:183], v[220:223], v[4:7]
	v_mfma_f32_16x16x32_bf16 v[0:3], v[188:191], v[220:223], v[0:3]
	v_mfma_f32_16x16x32_bf16 v[52:55], v[184:187], v[200:203], v[52:55]
	v_mfma_f32_16x16x32_bf16 v[48:51], v[192:195], v[200:203], v[48:51]
	v_mfma_f32_16x16x32_bf16 v[36:39], v[184:187], v[208:211], v[36:39]
	v_mfma_f32_16x16x32_bf16 v[32:35], v[192:195], v[208:211], v[32:35]
	v_mfma_f32_16x16x32_bf16 v[20:23], v[184:187], v[216:219], v[20:23]
	v_mfma_f32_16x16x32_bf16 v[16:19], v[192:195], v[216:219], v[16:19]
	v_mfma_f32_16x16x32_bf16 v[4:7], v[184:187], v[224:227], v[4:7]
	v_mfma_f32_16x16x32_bf16 v[0:3], v[192:195], v[224:227], v[0:3]
	s_barrier
	s_setprio 1
	s_add_i32 s57, s57, 2
	s_add_u32 s55, s55, 0x100
	s_addc_u32 s56, s56, 0
	s_cmp_gt_u32 s57, 41
	s_mov_b64 s[4:5], s[22:23]
	s_cbranch_scc0 .LBB0_1733
	s_setprio 0
	s_and_b64 vcc, exec, s[18:19]
	s_cbranch_vccz .LBB0_1736
	s_barrier

; #define PG8_STAGE(bufoff, gbase, voff) do { _Pragma("unroll") for (int _i = 0; _i < 2; ++_i) \
;         __builtin_amdgcn_global_load_lds((const unsigned*)((const char*)(gbase) + (voff)[_i]), (PG8_LAS unsigned*)(lds + (bufoff) + ldsw + _i * 8192), 16, 0, 0); } while (0)
; #define PG8_LDA(dst, b, h) do { _Pragma("unroll") for (int m = 0; m < 4; ++m) _Pragma("unroll") for (int k = 0; k < 2; ++k) dst[m][k] = *(const PG8_LAS bf16x8*)(lds + PG8_SA(b, h) + aoff + m * 2048 + k * 1024); } while (0)
; #define PG8_WAIT_V(n) asm volatile("s_waitcnt vmcnt(" #n ")" ::: "memory")
; #define PG8_WAIT_L(n) asm volatile("s_waitcnt lgkmcnt(" #n ")" ::: "memory")
; #define PG8_BAR __builtin_amdgcn_s_barrier()
; template <class Epi, class Sched, bool ALIGN_EPI = false, bool SP2 = false>
; __device__ __forceinline__ void gemm_phase(PG8_LAS unsigned char* lds, const Gemm g, const Sched& S, const Epi& E, const int tid_arg) {
;     ...
;         for (int t = 0; t < nt; t += 2) {
;             const bool last = (t == nt - 2);
;             const char* a1 = cA + (size_t)(t + 1) * kstep;
;             const char* a2 = last ? nA : cA + (size_t)(t + 2) * kstep; const char* b2 = last ? nB : cB + (size_t)(t + 2) * kstep;
;             const char* a3 = a2 + kstep; const char* b3 = b2 + kstep;
;             if (last && has_next) S.a_ready(nxt);
;             if constexpr (SP2) {
;             PG8_LDB(B0, 0, 0); PG8_LDB(B1, 0, 1); PG8_SCHED; PG8_LDA(At, 0, 0); PG8_STAGE(PG8_SA(1, 1), a1 + hstep, voffA);
;             PG8_WAIT_V(8); PG8_WAIT_L(0); PG8_BAR; PG8_MMA(0, 0, At, B0); PG8_MMA(0, 1, At, B1); PG8_BAR; PG8_SCHED;
;             PG8_LDA(At, 0, 1); PG8_STAGE(PG8_SB(0, 0), b2, voffB); PG8_STAGE(PG8_SB(0, 1), b2 + hstep, voffB); PG8_STAGE(PG8_SA(0, 0), a2, voffA);
;             PG8_WAIT_V(8); PG8_WAIT_L(0); PG8_BAR; PG8_MMA(1, 0, At, B0); PG8_MMA(1, 1, At, B1); PG8_BAR; PG8_SCHED;
;             PG8_LDB(B0, 1, 0); PG8_LDB(B1, 1, 1); PG8_SCHED; PG8_LDA(At, 1, 0); PG8_STAGE(PG8_SA(0, 1), a2 + hstep, voffA);
;             PG8_WAIT_V(8); PG8_WAIT_L(0); PG8_BAR; PG8_MMA(0, 0, At, B0); PG8_MMA(0, 1, At, B1); PG8_BAR; PG8_SCHED;
;             PG8_LDA(At, 1, 1); PG8_STAGE(PG8_SB(1, 0), b3, voffB); PG8_STAGE(PG8_SB(1, 1), b3 + hstep, voffB); PG8_STAGE(PG8_SA(1, 0), a3, voffA);
;             PG8_WAIT_V(8); PG8_WAIT_L(0); PG8_BAR; PG8_MMA(1, 0, At, B0); PG8_MMA(1, 1, At, B1); PG8_BAR; PG8_SCHED;
.LBB0_1827:
	ds_read_b128 v[170:173], v151
	ds_read_b128 v[174:177], v153
	ds_read_b128 v[178:181], v155
	ds_read_b128 v[182:185], v156
	ds_read_b128 v[186:189], v157
	ds_read_b128 v[190:193], v158
	ds_read_b128 v[194:197], v159
	ds_read_b128 v[198:201], v160
	s_add_u32 s0, s44, 0xfffc0080
	s_addc_u32 s1, s45, -1
	s_cmp_eq_u32 s81, 12
	s_cselect_b32 s47, s39, s1
	s_cselect_b32 s46, s75, s0
	s_cselect_b32 s1, s37, s80
	s_cselect_b32 s0, s78, s79
	s_mov_b32 m0, s67
	v_lshl_add_u64 v[234:235], s[44:45], 0, v[138:139]
	ds_read_b128 v[202:205], v149
	ds_read_b128 v[206:209], v149 offset:1024
	ds_read_b128 v[210:213], v149 offset:2048
	ds_read_b128 v[214:217], v149 offset:3072
	ds_read_b128 v[218:221], v149 offset:4096
	ds_read_b128 v[222:225], v149 offset:5120
	ds_read_b128 v[226:229], v149 offset:6144
	ds_read_b128 v[230:233], v149 offset:7168
	global_load_lds_dwordx4 v[234:235], off
	v_lshl_add_u64 v[234:235], s[44:45], 0, v[136:137]
	s_mov_b32 m0, s68
	s_nop 0
	global_load_lds_dwordx4 v[234:235], off
	s_waitcnt vmcnt(8)
	s_waitcnt lgkmcnt(0)
	s_setprio 0
	s_barrier
	v_mfma_f32_16x16x32_bf16 v[124:127], v[170:173], v[202:205], v[124:127]
	v_mfma_f32_16x16x32_bf16 v[120:123], v[178:181], v[202:205], v[120:123]
	v_mfma_f32_16x16x32_bf16 v[108:111], v[170:173], v[210:213], v[108:111]
	v_mfma_f32_16x16x32_bf16 v[104:107], v[178:181], v[210:213], v[104:107]
	v_mfma_f32_16x16x32_bf16 v[92:95], v[170:173], v[218:221], v[92:95]
	v_mfma_f32_16x16x32_bf16 v[88:91], v[178:181], v[218:221], v[88:91]
	v_mfma_f32_16x16x32_bf16 v[76:79], v[170:173], v[226:229], v[76:79]
	v_mfma_f32_16x16x32_bf16 v[72:75], v[178:181], v[226:229], v[72:75]
	v_mfma_f32_16x16x32_bf16 v[124:127], v[174:177], v[206:209], v[124:127]
	v_mfma_f32_16x16x32_bf16 v[120:123], v[182:185], v[206:209], v[120:123]
	v_mfma_f32_16x16x32_bf16 v[108:111], v[174:177], v[214:217], v[108:111]
	v_mfma_f32_16x16x32_bf16 v[104:107], v[182:185], v[214:217], v[104:107]
	v_mfma_f32_16x16x32_bf16 v[92:95], v[174:177], v[222:225], v[92:95]
	v_mfma_f32_16x16x32_bf16 v[88:91], v[182:185], v[222:225], v[88:91]
	v_mfma_f32_16x16x32_bf16 v[76:79], v[174:177], v[230:233], v[76:79]
	v_mfma_f32_16x16x32_bf16 v[72:75], v[182:185], v[230:233], v[72:75]
	v_mfma_f32_16x16x32_bf16 v[116:119], v[186:189], v[202:205], v[116:119]
	v_mfma_f32_16x16x32_bf16 v[112:115], v[194:197], v[202:205], v[112:115]
	v_mfma_f32_16x16x32_bf16 v[100:103], v[186:189], v[210:213], v[100:103]
	v_mfma_f32_16x16x32_bf16 v[96:99], v[194:197], v[210:213], v[96:99]
	v_mfma_f32_16x16x32_bf16 v[84:87], v[186:189], v[218:221], v[84:87]
	v_mfma_f32_16x16x32_bf16 v[80:83], v[194:197], v[218:221], v[80:83]
	v_mfma_f32_16x16x32_bf16 v[68:71], v[186:189], v[226:229], v[68:71]
	v_mfma_f32_16x16x32_bf16 v[64:67], v[194:197], v[226:229], v[64:67]
	v_mfma_f32_16x16x32_bf16 v[116:119], v[190:193], v[206:209], v[116:119]
	v_mfma_f32_16x16x32_bf16 v[112:115], v[198:201], v[206:209], v[112:115]
	v_mfma_f32_16x16x32_bf16 v[100:103], v[190:193], v[214:217], v[100:103]
	v_mfma_f32_16x16x32_bf16 v[96:99], v[198:201], v[214:217], v[96:99]
	v_mfma_f32_16x16x32_bf16 v[84:87], v[190:193], v[222:225], v[84:87]
	v_mfma_f32_16x16x32_bf16 v[80:83], v[198:201], v[222:225], v[80:83]
	v_mfma_f32_16x16x32_bf16 v[68:71], v[190:193], v[230:233], v[68:71]
	v_mfma_f32_16x16x32_bf16 v[64:67], v[198:201], v[230:233], v[64:67]
	s_barrier
	s_setprio 1
	s_mov_b32 m0, s5
	v_lshl_add_u64 v[234:235], s[0:1], 0, v[130:131]
	s_add_u32 s82, s0, 0x40000
	ds_read_b128 v[202:205], v149 offset:16384
	ds_read_b128 v[206:209], v149 offset:17408
	ds_read_b128 v[210:213], v149 offset:18432
	ds_read_b128 v[214:217], v149 offset:19456
	ds_read_b128 v[218:221], v149 offset:20480
	ds_read_b128 v[222:225], v149 offset:21504
	ds_read_b128 v[226:229], v149 offset:22528
	ds_read_b128 v[230:233], v149 offset:23552
	global_load_lds_dwordx4 v[234:235], off
	v_lshl_add_u64 v[236:237], s[0:1], 0, v[134:135]
	s_mov_b32 m0, s51
	s_addc_u32 s83, s1, 0
	global_load_lds_dwordx4 v[236:237], off
	v_lshl_add_u64 v[238:239], s[82:83], 0, v[130:131]
	s_mov_b32 m0, s52
	v_lshl_add_u64 v[240:241], s[46:47], 0, v[132:133]
	global_load_lds_dwordx4 v[238:239], off
	v_lshl_add_u64 v[238:239], s[82:83], 0, v[134:135]
	s_mov_b32 m0, s53
	s_nop 0
	global_load_lds_dwordx4 v[238:239], off
	v_lshl_add_u64 v[238:239], s[46:47], 0, v[128:129]
	s_mov_b32 m0, s50
	s_nop 0
	global_load_lds_dwordx4 v[238:239], off
	s_mov_b32 m0, s54
	s_nop 0
	global_load_lds_dwordx4 v[240:241], off
	s_waitcnt vmcnt(8)
	s_waitcnt lgkmcnt(0)
	s_setprio 0
	s_barrier
	v_mfma_f32_16x16x32_bf16 v[60:63], v[170:173], v[202:205], v[60:63]
	v_mfma_f32_16x16x32_bf16 v[56:59], v[178:181], v[202:205], v[56:59]
	v_mfma_f32_16x16x32_bf16 v[44:47], v[170:173], v[210:213], v[44:47]
	v_mfma_f32_16x16x32_bf16 v[40:43], v[178:181], v[210:213], v[40:43]
	v_mfma_f32_16x16x32_bf16 v[28:31], v[170:173], v[218:221], v[28:31]
	v_mfma_f32_16x16x32_bf16 v[24:27], v[178:181], v[218:221], v[24:27]
	v_mfma_f32_16x16x32_bf16 v[12:15], v[170:173], v[226:229], v[12:15]
	v_mfma_f32_16x16x32_bf16 v[8:11], v[178:181], v[226:229], v[8:11]
	v_mfma_f32_16x16x32_bf16 v[60:63], v[174:177], v[206:209], v[60:63]
	v_mfma_f32_16x16x32_bf16 v[56:59], v[182:185], v[206:209], v[56:59]
	v_mfma_f32_16x16x32_bf16 v[44:47], v[174:177], v[214:217], v[44:47]
	v_mfma_f32_16x16x32_bf16 v[40:43], v[182:185], v[214:217], v[40:43]
	v_mfma_f32_16x16x32_bf16 v[28:31], v[174:177], v[222:225], v[28:31]
	v_mfma_f32_16x16x32_bf16 v[24:27], v[182:185], v[222:225], v[24:27]
	v_mfma_f32_16x16x32_bf16 v[12:15], v[174:177], v[230:233], v[12:15]
	v_mfma_f32_16x16x32_bf16 v[8:11], v[182:185], v[230:233], v[8:11]
	v_mfma_f32_16x16x32_bf16 v[52:55], v[186:189], v[202:205], v[52:55]
	v_mfma_f32_16x16x32_bf16 v[48:51], v[194:197], v[202:205], v[48:51]
	v_mfma_f32_16x16x32_bf16 v[36:39], v[186:189], v[210:213], v[36:39]
	v_mfma_f32_16x16x32_bf16 v[32:35], v[194:197], v[210:213], v[32:35]
	v_mfma_f32_16x16x32_bf16 v[20:23], v[186:189], v[218:221], v[20:23]
	v_mfma_f32_16x16x32_bf16 v[16:19], v[194:197], v[218:221], v[16:19]
	v_mfma_f32_16x16x32_bf16 v[4:7], v[186:189], v[226:229], v[4:7]
	v_mfma_f32_16x16x32_bf16 v[0:3], v[194:197], v[226:229], v[0:3]
	v_mfma_f32_16x16x32_bf16 v[52:55], v[190:193], v[206:209], v[52:55]
	v_mfma_f32_16x16x32_bf16 v[48:51], v[198:201], v[206:209], v[48:51]
	v_mfma_f32_16x16x32_bf16 v[36:39], v[190:193], v[214:217], v[36:39]
	v_mfma_f32_16x16x32_bf16 v[32:35], v[198:201], v[214:217], v[32:35]
	v_mfma_f32_16x16x32_bf16 v[20:23], v[190:193], v[222:225], v[20:23]
	v_mfma_f32_16x16x32_bf16 v[16:19], v[198:201], v[222:225], v[16:19]
	v_mfma_f32_16x16x32_bf16 v[4:7], v[190:193], v[230:233], v[4:7]
	v_mfma_f32_16x16x32_bf16 v[0:3], v[198:201], v[230:233], v[0:3]
	s_barrier
; #define PG8_STAGE(bufoff, gbase, voff) do { _Pragma("unroll") for (int _i = 0; _i < 2; ++_i) \
;         __builtin_amdgcn_global_load_lds((const unsigned*)((const char*)(gbase) + (voff)[_i]), (PG8_LAS unsigned*)(lds + (bufoff) + ldsw + _i * 8192), 16, 0, 0); } while (0)
; #define PG8_LDA(dst, b, h) do { _Pragma("unroll") for (int m = 0; m < 4; ++m) _Pragma("unroll") for (int k = 0; k < 2; ++k) dst[m][k] = *(const PG8_LAS bf16x8*)(lds + PG8_SA(b, h) + aoff + m * 2048 + k * 1024); } while (0)
; #define PG8_WAIT_V(n) asm volatile("s_waitcnt vmcnt(" #n ")" ::: "memory")
; #define PG8_WAIT_L(n) asm volatile("s_waitcnt lgkmcnt(" #n ")" ::: "memory")
; #define PG8_BAR __builtin_amdgcn_s_barrier()
; template <class Epi, class Sched, bool ALIGN_EPI = false, bool SP2 = false>
; __device__ __forceinline__ void gemm_phase(PG8_LAS unsigned char* lds, const Gemm g, const Sched& S, const Epi& E, const int tid_arg) {
;     ...
;         for (int t = 0; t < nt; t += 2) {
;             const bool last = (t == nt - 2);
;             const char* a1 = cA + (size_t)(t + 1) * kstep;
;             const char* a2 = last ? nA : cA + (size_t)(t + 2) * kstep; const char* b2 = last ? nB : cB + (size_t)(t + 2) * kstep;
;             const char* a3 = a2 + kstep; const char* b3 = b2 + kstep;
;             if (last && has_next) S.a_ready(nxt);
;             if constexpr (SP2) {
;             PG8_LDB(B0, 0, 0); PG8_LDB(B1, 0, 1); PG8_SCHED; PG8_LDA(At, 0, 0); PG8_STAGE(PG8_SA(1, 1), a1 + hstep, voffA);
;             PG8_WAIT_V(8); PG8_WAIT_L(0); PG8_BAR; PG8_MMA(0, 0, At, B0); PG8_MMA(0, 1, At, B1); PG8_BAR; PG8_SCHED;
;             PG8_LDA(At, 0, 1); PG8_STAGE(PG8_SB(0, 0), b2, voffB); PG8_STAGE(PG8_SB(0, 1), b2 + hstep, voffB); PG8_STAGE(PG8_SA(0, 0), a2, voffA);
;             PG8_WAIT_V(8); PG8_WAIT_L(0); PG8_BAR; PG8_MMA(1, 0, At, B0); PG8_MMA(1, 1, At, B1); PG8_BAR; PG8_SCHED;
;             PG8_LDB(B0, 1, 0); PG8_LDB(B1, 1, 1); PG8_SCHED; PG8_LDA(At, 1, 0); PG8_STAGE(PG8_SA(0, 1), a2 + hstep, voffA);
;             PG8_WAIT_V(8); PG8_WAIT_L(0); PG8_BAR; PG8_MMA(0, 0, At, B0); PG8_MMA(0, 1, At, B1); PG8_BAR; PG8_SCHED;
;             PG8_LDA(At, 1, 1); PG8_STAGE(PG8_SB(1, 0), b3, voffB); PG8_STAGE(PG8_SB(1, 1), b3 + hstep, voffB); PG8_STAGE(PG8_SA(1, 0), a3, voffA);
;             PG8_WAIT_V(8); PG8_WAIT_L(0); PG8_BAR; PG8_MMA(1, 0, At, B0); PG8_MMA(1, 1, At, B1); PG8_BAR; PG8_SCHED;
	s_setprio 1
	ds_read_b128 v[170:173], v161
	ds_read_b128 v[174:177], v162
	ds_read_b128 v[178:181], v163
	ds_read_b128 v[182:185], v164
	ds_read_b128 v[186:189], v165
	ds_read_b128 v[190:193], v166
	ds_read_b128 v[194:197], v167
	ds_read_b128 v[198:201], v168
	s_add_u32 s46, s46, 0x40000
	s_addc_u32 s47, s47, 0
	s_mov_b32 m0, s55
	v_lshl_add_u64 v[242:243], s[46:47], 0, v[128:129]
	ds_read_b128 v[202:205], v149 offset:32768
	ds_read_b128 v[206:209], v149 offset:33792
	ds_read_b128 v[210:213], v149 offset:34816
	ds_read_b128 v[214:217], v149 offset:35840
	ds_read_b128 v[218:221], v149 offset:36864
	ds_read_b128 v[222:225], v149 offset:37888
	ds_read_b128 v[226:229], v149 offset:38912
	ds_read_b128 v[230:233], v149 offset:39936
	global_load_lds_dwordx4 v[242:243], off
	v_lshl_add_u64 v[242:243], s[46:47], 0, v[132:133]
	s_mov_b32 m0, s56
	s_nop 0
	global_load_lds_dwordx4 v[242:243], off
	s_waitcnt vmcnt(8)
	s_waitcnt lgkmcnt(0)
	s_setprio 0
	s_barrier
	v_mfma_f32_16x16x32_bf16 v[124:127], v[170:173], v[202:205], v[124:127]
	v_mfma_f32_16x16x32_bf16 v[120:123], v[178:181], v[202:205], v[120:123]
	v_mfma_f32_16x16x32_bf16 v[108:111], v[170:173], v[210:213], v[108:111]
	v_mfma_f32_16x16x32_bf16 v[104:107], v[178:181], v[210:213], v[104:107]
	v_mfma_f32_16x16x32_bf16 v[92:95], v[170:173], v[218:221], v[92:95]
	v_mfma_f32_16x16x32_bf16 v[88:91], v[178:181], v[218:221], v[88:91]
	v_mfma_f32_16x16x32_bf16 v[76:79], v[170:173], v[226:229], v[76:79]
	v_mfma_f32_16x16x32_bf16 v[72:75], v[178:181], v[226:229], v[72:75]
	v_mfma_f32_16x16x32_bf16 v[124:127], v[174:177], v[206:209], v[124:127]
	v_mfma_f32_16x16x32_bf16 v[120:123], v[182:185], v[206:209], v[120:123]
	v_mfma_f32_16x16x32_bf16 v[108:111], v[174:177], v[214:217], v[108:111]
	v_mfma_f32_16x16x32_bf16 v[104:107], v[182:185], v[214:217], v[104:107]
	v_mfma_f32_16x16x32_bf16 v[92:95], v[174:177], v[222:225], v[92:95]
	v_mfma_f32_16x16x32_bf16 v[88:91], v[182:185], v[222:225], v[88:91]
	v_mfma_f32_16x16x32_bf16 v[76:79], v[174:177], v[230:233], v[76:79]
	v_mfma_f32_16x16x32_bf16 v[72:75], v[182:185], v[230:233], v[72:75]
	v_mfma_f32_16x16x32_bf16 v[116:119], v[186:189], v[202:205], v[116:119]
	v_mfma_f32_16x16x32_bf16 v[112:115], v[194:197], v[202:205], v[112:115]
	v_mfma_f32_16x16x32_bf16 v[100:103], v[186:189], v[210:213], v[100:103]
	v_mfma_f32_16x16x32_bf16 v[96:99], v[194:197], v[210:213], v[96:99]
	v_mfma_f32_16x16x32_bf16 v[84:87], v[186:189], v[218:221], v[84:87]
	v_mfma_f32_16x16x32_bf16 v[80:83], v[194:197], v[218:221], v[80:83]
	v_mfma_f32_16x16x32_bf16 v[68:71], v[186:189], v[226:229], v[68:71]
	v_mfma_f32_16x16x32_bf16 v[64:67], v[194:197], v[226:229], v[64:67]
	v_mfma_f32_16x16x32_bf16 v[116:119], v[190:193], v[206:209], v[116:119]
	v_mfma_f32_16x16x32_bf16 v[112:115], v[198:201], v[206:209], v[112:115]
	v_mfma_f32_16x16x32_bf16 v[100:103], v[190:193], v[214:217], v[100:103]
	v_mfma_f32_16x16x32_bf16 v[96:99], v[198:201], v[214:217], v[96:99]
	v_mfma_f32_16x16x32_bf16 v[84:87], v[190:193], v[222:225], v[84:87]
	v_mfma_f32_16x16x32_bf16 v[80:83], v[198:201], v[222:225], v[80:83]
	v_mfma_f32_16x16x32_bf16 v[68:71], v[190:193], v[230:233], v[68:71]
	v_mfma_f32_16x16x32_bf16 v[64:67], v[198:201], v[230:233], v[64:67]
	s_barrier
	s_setprio 1
	s_mov_b32 m0, s59
	v_lshl_add_u64 v[234:235], v[234:235], 0, s[16:17]
	s_add_u32 s0, s0, 0x40080
	ds_read_b128 v[202:205], v149 offset:49152
	ds_read_b128 v[206:209], v149 offset:50176
	ds_read_b128 v[210:213], v149 offset:51200
	ds_read_b128 v[214:217], v149 offset:52224
	ds_read_b128 v[218:221], v149 offset:53248
	ds_read_b128 v[222:225], v149 offset:54272
	ds_read_b128 v[226:229], v149 offset:55296
	ds_read_b128 v[230:233], v149 offset:56320
	global_load_lds_dwordx4 v[234:235], off
	v_lshl_add_u64 v[234:235], v[236:237], 0, s[16:17]
	s_mov_b32 m0, s60
	s_addc_u32 s1, s1, 0
	global_load_lds_dwordx4 v[234:235], off
	v_lshl_add_u64 v[234:235], s[0:1], 0, v[130:131]
	s_mov_b32 m0, s63
	s_nop 0
	global_load_lds_dwordx4 v[234:235], off
	v_lshl_add_u64 v[234:235], s[0:1], 0, v[134:135]
	s_mov_b32 m0, s64
	s_nop 0
	global_load_lds_dwordx4 v[234:235], off
	v_lshl_add_u64 v[234:235], v[238:239], 0, s[16:17]
	s_mov_b32 m0, s61
	s_nop 0
	global_load_lds_dwordx4 v[234:235], off
	v_lshl_add_u64 v[234:235], v[240:241], 0, s[16:17]
	s_mov_b32 m0, s62
	s_nop 0
	global_load_lds_dwordx4 v[234:235], off
	s_waitcnt vmcnt(8)
	s_waitcnt lgkmcnt(0)
	s_setprio 0
	s_barrier
	v_mfma_f32_16x16x32_bf16 v[60:63], v[170:173], v[202:205], v[60:63]
	v_mfma_f32_16x16x32_bf16 v[56:59], v[178:181], v[202:205], v[56:59]
	v_mfma_f32_16x16x32_bf16 v[44:47], v[170:173], v[210:213], v[44:47]
	v_mfma_f32_16x16x32_bf16 v[40:43], v[178:181], v[210:213], v[40:43]
	v_mfma_f32_16x16x32_bf16 v[28:31], v[170:173], v[218:221], v[28:31]
	v_mfma_f32_16x16x32_bf16 v[24:27], v[178:181], v[218:221], v[24:27]
	v_mfma_f32_16x16x32_bf16 v[12:15], v[170:173], v[226:229], v[12:15]
	v_mfma_f32_16x16x32_bf16 v[8:11], v[178:181], v[226:229], v[8:11]
	v_mfma_f32_16x16x32_bf16 v[60:63], v[174:177], v[206:209], v[60:63]
	v_mfma_f32_16x16x32_bf16 v[56:59], v[182:185], v[206:209], v[56:59]
	v_mfma_f32_16x16x32_bf16 v[44:47], v[174:177], v[214:217], v[44:47]
	v_mfma_f32_16x16x32_bf16 v[40:43], v[182:185], v[214:217], v[40:43]
	v_mfma_f32_16x16x32_bf16 v[28:31], v[174:177], v[222:225], v[28:31]
	v_mfma_f32_16x16x32_bf16 v[24:27], v[182:185], v[222:225], v[24:27]
	v_mfma_f32_16x16x32_bf16 v[12:15], v[174:177], v[230:233], v[12:15]
	v_mfma_f32_16x16x32_bf16 v[8:11], v[182:185], v[230:233], v[8:11]
	v_mfma_f32_16x16x32_bf16 v[52:55], v[186:189], v[202:205], v[52:55]
	v_mfma_f32_16x16x32_bf16 v[48:51], v[194:197], v[202:205], v[48:51]
	v_mfma_f32_16x16x32_bf16 v[36:39], v[186:189], v[210:213], v[36:39]
	v_mfma_f32_16x16x32_bf16 v[32:35], v[194:197], v[210:213], v[32:35]
	v_mfma_f32_16x16x32_bf16 v[20:23], v[186:189], v[218:221], v[20:23]
	v_mfma_f32_16x16x32_bf16 v[16:19], v[194:197], v[218:221], v[16:19]
	v_mfma_f32_16x16x32_bf16 v[4:7], v[186:189], v[226:229], v[4:7]
	v_mfma_f32_16x16x32_bf16 v[0:3], v[194:197], v[226:229], v[0:3]
	v_mfma_f32_16x16x32_bf16 v[52:55], v[190:193], v[206:209], v[52:55]
	v_mfma_f32_16x16x32_bf16 v[48:51], v[198:201], v[206:209], v[48:51]
	v_mfma_f32_16x16x32_bf16 v[36:39], v[190:193], v[214:217], v[36:39]
	v_mfma_f32_16x16x32_bf16 v[32:35], v[198:201], v[214:217], v[32:35]
	v_mfma_f32_16x16x32_bf16 v[20:23], v[190:193], v[222:225], v[20:23]
	v_mfma_f32_16x16x32_bf16 v[16:19], v[198:201], v[222:225], v[16:19]
	v_mfma_f32_16x16x32_bf16 v[4:7], v[190:193], v[230:233], v[4:7]
	v_mfma_f32_16x16x32_bf16 v[0:3], v[198:201], v[230:233], v[0:3]
	s_barrier
	s_setprio 1
	s_add_i32 s81, s81, 2
	s_add_u32 s79, s79, 0x100
	s_addc_u32 s80, s80, 0
	s_add_u32 s44, s44, 0x100
	s_addc_u32 s45, s45, 0
	s_cmp_gt_u32 s81, 13
	s_cbranch_scc0 .LBB0_1827
	s_setprio 0
	s_and_b64 vcc, exec, s[18:19]
	s_cbranch_vccz .LBB0_1830
	s_barrier

; #define PG8_STAGE(bufoff, gbase, voff) do { _Pragma("unroll") for (int _i = 0; _i < 2; ++_i) \
;         __builtin_amdgcn_global_load_lds((const unsigned*)((const char*)(gbase) + (voff)[_i]), (PG8_LAS unsigned*)(lds + (bufoff) + ldsw + _i * 8192), 16, 0, 0); } while (0)
; #define PG8_LDA(dst, b, h) do { _Pragma("unroll") for (int m = 0; m < 4; ++m) _Pragma("unroll") for (int k = 0; k < 2; ++k) dst[m][k] = *(const PG8_LAS bf16x8*)(lds + PG8_SA(b, h) + aoff + m * 2048 + k * 1024); } while (0)
; #define PG8_WAIT_V(n) asm volatile("s_waitcnt vmcnt(" #n ")" ::: "memory")
; #define PG8_WAIT_L(n) asm volatile("s_waitcnt lgkmcnt(" #n ")" ::: "memory")
; #define PG8_BAR __builtin_amdgcn_s_barrier()
; template <class Epi, class Sched, bool ALIGN_EPI = false, bool SP2 = false>
; __device__ __forceinline__ void gemm_phase(PG8_LAS unsigned char* lds, const Gemm g, const Sched& S, const Epi& E, const int tid_arg) {
;     ...
;         for (int t = 0; t < nt; t += 2) {
;             const bool last = (t == nt - 2);
;             const char* a1 = cA + (size_t)(t + 1) * kstep;
;             const char* a2 = last ? nA : cA + (size_t)(t + 2) * kstep; const char* b2 = last ? nB : cB + (size_t)(t + 2) * kstep;
;             const char* a3 = a2 + kstep; const char* b3 = b2 + kstep;
;             if (last && has_next) S.a_ready(nxt);
;             if constexpr (SP2) {
;             PG8_LDB(B0, 0, 0); PG8_LDB(B1, 0, 1); PG8_SCHED; PG8_LDA(At, 0, 0); PG8_STAGE(PG8_SA(1, 1), a1 + hstep, voffA);
;             PG8_WAIT_V(8); PG8_WAIT_L(0); PG8_BAR; PG8_MMA(0, 0, At, B0); PG8_MMA(0, 1, At, B1); PG8_BAR; PG8_SCHED;
;             PG8_LDA(At, 0, 1); PG8_STAGE(PG8_SB(0, 0), b2, voffB); PG8_STAGE(PG8_SB(0, 1), b2 + hstep, voffB); PG8_STAGE(PG8_SA(0, 0), a2, voffA);
;             PG8_WAIT_V(8); PG8_WAIT_L(0); PG8_BAR; PG8_MMA(1, 0, At, B0); PG8_MMA(1, 1, At, B1); PG8_BAR; PG8_SCHED;
;             PG8_LDB(B0, 1, 0); PG8_LDB(B1, 1, 1); PG8_SCHED; PG8_LDA(At, 1, 0); PG8_STAGE(PG8_SA(0, 1), a2 + hstep, voffA);
;             PG8_WAIT_V(8); PG8_WAIT_L(0); PG8_BAR; PG8_MMA(0, 0, At, B0); PG8_MMA(0, 1, At, B1); PG8_BAR; PG8_SCHED;
;             PG8_LDA(At, 1, 1); PG8_STAGE(PG8_SB(1, 0), b3, voffB); PG8_STAGE(PG8_SB(1, 1), b3 + hstep, voffB); PG8_STAGE(PG8_SA(1, 0), a3, voffA);
;             PG8_WAIT_V(8); PG8_WAIT_L(0); PG8_BAR; PG8_MMA(1, 0, At, B0); PG8_MMA(1, 1, At, B1); PG8_BAR; PG8_SCHED;
.LBB0_1911:
	ds_read_b128 v[144:147], v157
	ds_read_b128 v[148:151], v158
	ds_read_b128 v[174:177], v159
	ds_read_b128 v[178:181], v160
	ds_read_b128 v[182:185], v161
	ds_read_b128 v[186:189], v162
	ds_read_b128 v[190:193], v163
	ds_read_b128 v[194:197], v164
	s_add_i32 s36, s34, 2
	s_add_u32 s37, s6, 0x80
	s_addc_u32 s35, s7, 0
	s_cmp_eq_u32 s57, s34
	s_cselect_b32 s34, s28, s37
	s_cselect_b32 s35, s29, s35
	s_cselect_b32 s67, s31, s64
	s_cselect_b32 s66, s30, s63
	s_mov_b32 m0, s58
	v_lshl_add_u64 v[152:153], s[6:7], 0, v[138:139]
	ds_read_b128 v[198:201], v156
	ds_read_b128 v[202:205], v156 offset:1024
	ds_read_b128 v[206:209], v156 offset:2048
	ds_read_b128 v[210:213], v156 offset:3072
	ds_read_b128 v[214:217], v156 offset:4096
	ds_read_b128 v[218:221], v156 offset:5120
	ds_read_b128 v[222:225], v156 offset:6144
	ds_read_b128 v[226:229], v156 offset:7168
	global_load_lds_dwordx4 v[152:153], off
	v_lshl_add_u64 v[152:153], s[6:7], 0, v[136:137]
	s_mov_b32 m0, s59
	s_nop 0
	global_load_lds_dwordx4 v[152:153], off
	s_waitcnt vmcnt(8)
	s_waitcnt lgkmcnt(0)
	s_setprio 0
	s_barrier
	v_mfma_f32_16x16x32_bf16 v[124:127], v[144:147], v[198:201], v[124:127]
	v_mfma_f32_16x16x32_bf16 v[120:123], v[174:177], v[198:201], v[120:123]
	v_mfma_f32_16x16x32_bf16 v[108:111], v[144:147], v[206:209], v[108:111]
	v_mfma_f32_16x16x32_bf16 v[104:107], v[174:177], v[206:209], v[104:107]
	v_mfma_f32_16x16x32_bf16 v[92:95], v[144:147], v[214:217], v[92:95]
	v_mfma_f32_16x16x32_bf16 v[88:91], v[174:177], v[214:217], v[88:91]
	v_mfma_f32_16x16x32_bf16 v[76:79], v[144:147], v[222:225], v[76:79]
	v_mfma_f32_16x16x32_bf16 v[72:75], v[174:177], v[222:225], v[72:75]
	v_mfma_f32_16x16x32_bf16 v[124:127], v[148:151], v[202:205], v[124:127]
	v_mfma_f32_16x16x32_bf16 v[120:123], v[178:181], v[202:205], v[120:123]
	v_mfma_f32_16x16x32_bf16 v[108:111], v[148:151], v[210:213], v[108:111]
	v_mfma_f32_16x16x32_bf16 v[104:107], v[178:181], v[210:213], v[104:107]
	v_mfma_f32_16x16x32_bf16 v[92:95], v[148:151], v[218:221], v[92:95]
	v_mfma_f32_16x16x32_bf16 v[88:91], v[178:181], v[218:221], v[88:91]
	v_mfma_f32_16x16x32_bf16 v[76:79], v[148:151], v[226:229], v[76:79]
	v_mfma_f32_16x16x32_bf16 v[72:75], v[178:181], v[226:229], v[72:75]
	v_mfma_f32_16x16x32_bf16 v[116:119], v[182:185], v[198:201], v[116:119]
	v_mfma_f32_16x16x32_bf16 v[112:115], v[190:193], v[198:201], v[112:115]
	v_mfma_f32_16x16x32_bf16 v[100:103], v[182:185], v[206:209], v[100:103]
	v_mfma_f32_16x16x32_bf16 v[96:99], v[190:193], v[206:209], v[96:99]
	v_mfma_f32_16x16x32_bf16 v[84:87], v[182:185], v[214:217], v[84:87]
	v_mfma_f32_16x16x32_bf16 v[80:83], v[190:193], v[214:217], v[80:83]
	v_mfma_f32_16x16x32_bf16 v[68:71], v[182:185], v[222:225], v[68:71]
	v_mfma_f32_16x16x32_bf16 v[64:67], v[190:193], v[222:225], v[64:67]
	v_mfma_f32_16x16x32_bf16 v[116:119], v[186:189], v[202:205], v[116:119]
	v_mfma_f32_16x16x32_bf16 v[112:115], v[194:197], v[202:205], v[112:115]
	v_mfma_f32_16x16x32_bf16 v[100:103], v[186:189], v[210:213], v[100:103]
	v_mfma_f32_16x16x32_bf16 v[96:99], v[194:197], v[210:213], v[96:99]
	v_mfma_f32_16x16x32_bf16 v[84:87], v[186:189], v[218:221], v[84:87]
	v_mfma_f32_16x16x32_bf16 v[80:83], v[194:197], v[218:221], v[80:83]
	v_mfma_f32_16x16x32_bf16 v[68:71], v[186:189], v[226:229], v[68:71]
	v_mfma_f32_16x16x32_bf16 v[64:67], v[194:197], v[226:229], v[64:67]
	s_barrier
	s_setprio 1
	s_mov_b32 m0, s42
	v_lshl_add_u64 v[152:153], s[66:67], 0, v[130:131]
	v_lshl_add_u64 v[230:231], s[66:67], 0, v[134:135]
	s_add_u32 s66, s66, s12
	ds_read_b128 v[198:201], v156 offset:16384
	ds_read_b128 v[202:205], v156 offset:17408
	ds_read_b128 v[206:209], v156 offset:18432
	ds_read_b128 v[210:213], v156 offset:19456
	ds_read_b128 v[214:217], v156 offset:20480
	ds_read_b128 v[218:221], v156 offset:21504
	ds_read_b128 v[222:225], v156 offset:22528
	ds_read_b128 v[226:229], v156 offset:23552
	global_load_lds_dwordx4 v[152:153], off
	s_mov_b32 m0, s43
	s_addc_u32 s67, s67, s13
	global_load_lds_dwordx4 v[230:231], off
	v_lshl_add_u64 v[232:233], s[66:67], 0, v[130:131]
	s_mov_b32 m0, s44
	v_lshl_add_u64 v[234:235], s[66:67], 0, v[134:135]
	global_load_lds_dwordx4 v[232:233], off
	s_mov_b32 m0, s45
	v_lshl_add_u64 v[236:237], s[34:35], 0, v[128:129]
	global_load_lds_dwordx4 v[234:235], off
	s_mov_b32 m0, s41
	v_lshl_add_u64 v[238:239], s[34:35], 0, v[132:133]
	global_load_lds_dwordx4 v[236:237], off
	s_mov_b32 m0, s46
	s_nop 0
	global_load_lds_dwordx4 v[238:239], off
	s_waitcnt vmcnt(8)
	s_waitcnt lgkmcnt(0)
	s_setprio 0
	s_barrier
	v_mfma_f32_16x16x32_bf16 v[60:63], v[144:147], v[198:201], v[60:63]
	v_mfma_f32_16x16x32_bf16 v[56:59], v[174:177], v[198:201], v[56:59]
	v_mfma_f32_16x16x32_bf16 v[44:47], v[144:147], v[206:209], v[44:47]
	v_mfma_f32_16x16x32_bf16 v[40:43], v[174:177], v[206:209], v[40:43]
	v_mfma_f32_16x16x32_bf16 v[28:31], v[144:147], v[214:217], v[28:31]
	v_mfma_f32_16x16x32_bf16 v[24:27], v[174:177], v[214:217], v[24:27]
	v_mfma_f32_16x16x32_bf16 v[12:15], v[144:147], v[222:225], v[12:15]
	v_mfma_f32_16x16x32_bf16 v[8:11], v[174:177], v[222:225], v[8:11]
	v_mfma_f32_16x16x32_bf16 v[60:63], v[148:151], v[202:205], v[60:63]
	v_mfma_f32_16x16x32_bf16 v[56:59], v[178:181], v[202:205], v[56:59]
	v_mfma_f32_16x16x32_bf16 v[44:47], v[148:151], v[210:213], v[44:47]
	v_mfma_f32_16x16x32_bf16 v[40:43], v[178:181], v[210:213], v[40:43]
	v_mfma_f32_16x16x32_bf16 v[28:31], v[148:151], v[218:221], v[28:31]
	v_mfma_f32_16x16x32_bf16 v[24:27], v[178:181], v[218:221], v[24:27]
	v_mfma_f32_16x16x32_bf16 v[12:15], v[148:151], v[226:229], v[12:15]
	v_mfma_f32_16x16x32_bf16 v[8:11], v[178:181], v[226:229], v[8:11]
	v_mfma_f32_16x16x32_bf16 v[52:55], v[182:185], v[198:201], v[52:55]
	v_mfma_f32_16x16x32_bf16 v[48:51], v[190:193], v[198:201], v[48:51]
	v_mfma_f32_16x16x32_bf16 v[36:39], v[182:185], v[206:209], v[36:39]
	v_mfma_f32_16x16x32_bf16 v[32:35], v[190:193], v[206:209], v[32:35]
	v_mfma_f32_16x16x32_bf16 v[20:23], v[182:185], v[214:217], v[20:23]
	v_mfma_f32_16x16x32_bf16 v[16:19], v[190:193], v[214:217], v[16:19]
	v_mfma_f32_16x16x32_bf16 v[4:7], v[182:185], v[222:225], v[4:7]
	v_mfma_f32_16x16x32_bf16 v[0:3], v[190:193], v[222:225], v[0:3]
	v_mfma_f32_16x16x32_bf16 v[52:55], v[186:189], v[202:205], v[52:55]
	v_mfma_f32_16x16x32_bf16 v[48:51], v[194:197], v[202:205], v[48:51]
	v_mfma_f32_16x16x32_bf16 v[36:39], v[186:189], v[210:213], v[36:39]
	v_mfma_f32_16x16x32_bf16 v[32:35], v[194:197], v[210:213], v[32:35]
	v_mfma_f32_16x16x32_bf16 v[20:23], v[186:189], v[218:221], v[20:23]
	v_mfma_f32_16x16x32_bf16 v[16:19], v[194:197], v[218:221], v[16:19]
	v_mfma_f32_16x16x32_bf16 v[4:7], v[186:189], v[226:229], v[4:7]
	v_mfma_f32_16x16x32_bf16 v[0:3], v[194:197], v[226:229], v[0:3]
	s_barrier
; #define PG8_STAGE(bufoff, gbase, voff) do { _Pragma("unroll") for (int _i = 0; _i < 2; ++_i) \
;         __builtin_amdgcn_global_load_lds((const unsigned*)((const char*)(gbase) + (voff)[_i]), (PG8_LAS unsigned*)(lds + (bufoff) + ldsw + _i * 8192), 16, 0, 0); } while (0)
; #define PG8_LDA(dst, b, h) do { _Pragma("unroll") for (int m = 0; m < 4; ++m) _Pragma("unroll") for (int k = 0; k < 2; ++k) dst[m][k] = *(const PG8_LAS bf16x8*)(lds + PG8_SA(b, h) + aoff + m * 2048 + k * 1024); } while (0)
; #define PG8_WAIT_V(n) asm volatile("s_waitcnt vmcnt(" #n ")" ::: "memory")
; #define PG8_WAIT_L(n) asm volatile("s_waitcnt lgkmcnt(" #n ")" ::: "memory")
; #define PG8_BAR __builtin_amdgcn_s_barrier()
; template <class Epi, class Sched, bool ALIGN_EPI = false, bool SP2 = false>
; __device__ __forceinline__ void gemm_phase(PG8_LAS unsigned char* lds, const Gemm g, const Sched& S, const Epi& E, const int tid_arg) {
;     ...
;         for (int t = 0; t < nt; t += 2) {
;             const bool last = (t == nt - 2);
;             const char* a1 = cA + (size_t)(t + 1) * kstep;
;             const char* a2 = last ? nA : cA + (size_t)(t + 2) * kstep; const char* b2 = last ? nB : cB + (size_t)(t + 2) * kstep;
;             const char* a3 = a2 + kstep; const char* b3 = b2 + kstep;
;             if (last && has_next) S.a_ready(nxt);
;             if constexpr (SP2) {
;             PG8_LDB(B0, 0, 0); PG8_LDB(B1, 0, 1); PG8_SCHED; PG8_LDA(At, 0, 0); PG8_STAGE(PG8_SA(1, 1), a1 + hstep, voffA);
;             PG8_WAIT_V(8); PG8_WAIT_L(0); PG8_BAR; PG8_MMA(0, 0, At, B0); PG8_MMA(0, 1, At, B1); PG8_BAR; PG8_SCHED;
;             PG8_LDA(At, 0, 1); PG8_STAGE(PG8_SB(0, 0), b2, voffB); PG8_STAGE(PG8_SB(0, 1), b2 + hstep, voffB); PG8_STAGE(PG8_SA(0, 0), a2, voffA);
;             PG8_WAIT_V(8); PG8_WAIT_L(0); PG8_BAR; PG8_MMA(1, 0, At, B0); PG8_MMA(1, 1, At, B1); PG8_BAR; PG8_SCHED;
;             PG8_LDB(B0, 1, 0); PG8_LDB(B1, 1, 1); PG8_SCHED; PG8_LDA(At, 1, 0); PG8_STAGE(PG8_SA(0, 1), a2 + hstep, voffA);
;             PG8_WAIT_V(8); PG8_WAIT_L(0); PG8_BAR; PG8_MMA(0, 0, At, B0); PG8_MMA(0, 1, At, B1); PG8_BAR; PG8_SCHED;
;             PG8_LDA(At, 1, 1); PG8_STAGE(PG8_SB(1, 0), b3, voffB); PG8_STAGE(PG8_SB(1, 1), b3 + hstep, voffB); PG8_STAGE(PG8_SA(1, 0), a3, voffA);
;             PG8_WAIT_V(8); PG8_WAIT_L(0); PG8_BAR; PG8_MMA(1, 0, At, B0); PG8_MMA(1, 1, At, B1); PG8_BAR; PG8_SCHED;
	s_setprio 1
	ds_read_b128 v[144:147], v165
	ds_read_b128 v[148:151], v166
	ds_read_b128 v[174:177], v167
	ds_read_b128 v[178:181], v168
	ds_read_b128 v[182:185], v169
	ds_read_b128 v[186:189], v170
	ds_read_b128 v[190:193], v171
	ds_read_b128 v[194:197], v172
	s_add_u32 s34, s34, s12
	s_addc_u32 s35, s35, s13
	s_mov_b32 m0, s47
	v_lshl_add_u64 v[240:241], s[34:35], 0, v[128:129]
	ds_read_b128 v[198:201], v156 offset:32768
	ds_read_b128 v[202:205], v156 offset:33792
	ds_read_b128 v[206:209], v156 offset:34816
	ds_read_b128 v[210:213], v156 offset:35840
	ds_read_b128 v[214:217], v156 offset:36864
	ds_read_b128 v[218:221], v156 offset:37888
	ds_read_b128 v[222:225], v156 offset:38912
	ds_read_b128 v[226:229], v156 offset:39936
	global_load_lds_dwordx4 v[240:241], off
	v_lshl_add_u64 v[240:241], s[34:35], 0, v[132:133]
	s_mov_b32 m0, s48
	s_nop 0
	global_load_lds_dwordx4 v[240:241], off
	s_waitcnt vmcnt(8)
	s_waitcnt lgkmcnt(0)
	s_setprio 0
	s_barrier
	v_mfma_f32_16x16x32_bf16 v[124:127], v[144:147], v[198:201], v[124:127]
	v_mfma_f32_16x16x32_bf16 v[120:123], v[174:177], v[198:201], v[120:123]
	v_mfma_f32_16x16x32_bf16 v[108:111], v[144:147], v[206:209], v[108:111]
	v_mfma_f32_16x16x32_bf16 v[104:107], v[174:177], v[206:209], v[104:107]
	v_mfma_f32_16x16x32_bf16 v[92:95], v[144:147], v[214:217], v[92:95]
	v_mfma_f32_16x16x32_bf16 v[88:91], v[174:177], v[214:217], v[88:91]
	v_mfma_f32_16x16x32_bf16 v[76:79], v[144:147], v[222:225], v[76:79]
	v_mfma_f32_16x16x32_bf16 v[72:75], v[174:177], v[222:225], v[72:75]
	v_mfma_f32_16x16x32_bf16 v[124:127], v[148:151], v[202:205], v[124:127]
	v_mfma_f32_16x16x32_bf16 v[120:123], v[178:181], v[202:205], v[120:123]
	v_mfma_f32_16x16x32_bf16 v[108:111], v[148:151], v[210:213], v[108:111]
	v_mfma_f32_16x16x32_bf16 v[104:107], v[178:181], v[210:213], v[104:107]
	v_mfma_f32_16x16x32_bf16 v[92:95], v[148:151], v[218:221], v[92:95]
	v_mfma_f32_16x16x32_bf16 v[88:91], v[178:181], v[218:221], v[88:91]
	v_mfma_f32_16x16x32_bf16 v[76:79], v[148:151], v[226:229], v[76:79]
	v_mfma_f32_16x16x32_bf16 v[72:75], v[178:181], v[226:229], v[72:75]
	v_mfma_f32_16x16x32_bf16 v[116:119], v[182:185], v[198:201], v[116:119]
	v_mfma_f32_16x16x32_bf16 v[112:115], v[190:193], v[198:201], v[112:115]
	v_mfma_f32_16x16x32_bf16 v[100:103], v[182:185], v[206:209], v[100:103]
	v_mfma_f32_16x16x32_bf16 v[96:99], v[190:193], v[206:209], v[96:99]
	v_mfma_f32_16x16x32_bf16 v[84:87], v[182:185], v[214:217], v[84:87]
	v_mfma_f32_16x16x32_bf16 v[80:83], v[190:193], v[214:217], v[80:83]
	v_mfma_f32_16x16x32_bf16 v[68:71], v[182:185], v[222:225], v[68:71]
	v_mfma_f32_16x16x32_bf16 v[64:67], v[190:193], v[222:225], v[64:67]
	v_mfma_f32_16x16x32_bf16 v[116:119], v[186:189], v[202:205], v[116:119]
	v_mfma_f32_16x16x32_bf16 v[112:115], v[194:197], v[202:205], v[112:115]
	v_mfma_f32_16x16x32_bf16 v[100:103], v[186:189], v[210:213], v[100:103]
	v_mfma_f32_16x16x32_bf16 v[96:99], v[194:197], v[210:213], v[96:99]
	v_mfma_f32_16x16x32_bf16 v[84:87], v[186:189], v[218:221], v[84:87]
	v_mfma_f32_16x16x32_bf16 v[80:83], v[194:197], v[218:221], v[80:83]
	v_mfma_f32_16x16x32_bf16 v[68:71], v[186:189], v[226:229], v[68:71]
	v_mfma_f32_16x16x32_bf16 v[64:67], v[194:197], v[226:229], v[64:67]
	s_barrier
	s_setprio 1
	s_mov_b32 m0, s49
	v_lshl_add_u64 v[152:153], v[152:153], 0, s[20:21]
	ds_read_b128 v[198:201], v156 offset:49152
	ds_read_b128 v[202:205], v156 offset:50176
	ds_read_b128 v[206:209], v156 offset:51200
	ds_read_b128 v[210:213], v156 offset:52224
	ds_read_b128 v[214:217], v156 offset:53248
	ds_read_b128 v[218:221], v156 offset:54272
	ds_read_b128 v[222:225], v156 offset:55296
	ds_read_b128 v[226:229], v156 offset:56320
	global_load_lds_dwordx4 v[152:153], off
	v_lshl_add_u64 v[152:153], v[230:231], 0, s[20:21]
	s_mov_b32 m0, s50
	s_nop 0
	global_load_lds_dwordx4 v[152:153], off
	v_lshl_add_u64 v[152:153], v[232:233], 0, s[20:21]
	s_mov_b32 m0, s53
	s_nop 0
	global_load_lds_dwordx4 v[152:153], off
	v_lshl_add_u64 v[152:153], v[234:235], 0, s[20:21]
	s_mov_b32 m0, s54
	s_nop 0
	global_load_lds_dwordx4 v[152:153], off
	v_lshl_add_u64 v[152:153], v[236:237], 0, s[20:21]
	s_mov_b32 m0, s51
	s_nop 0
	global_load_lds_dwordx4 v[152:153], off
	v_lshl_add_u64 v[152:153], v[238:239], 0, s[20:21]
	s_mov_b32 m0, s52
	s_nop 0
	global_load_lds_dwordx4 v[152:153], off
	s_waitcnt vmcnt(8)
	s_waitcnt lgkmcnt(0)
	s_setprio 0
	s_barrier
	v_mfma_f32_16x16x32_bf16 v[60:63], v[144:147], v[198:201], v[60:63]
	v_mfma_f32_16x16x32_bf16 v[56:59], v[174:177], v[198:201], v[56:59]
	v_mfma_f32_16x16x32_bf16 v[44:47], v[144:147], v[206:209], v[44:47]
	v_mfma_f32_16x16x32_bf16 v[40:43], v[174:177], v[206:209], v[40:43]
	v_mfma_f32_16x16x32_bf16 v[28:31], v[144:147], v[214:217], v[28:31]
	v_mfma_f32_16x16x32_bf16 v[24:27], v[174:177], v[214:217], v[24:27]
	v_mfma_f32_16x16x32_bf16 v[12:15], v[144:147], v[222:225], v[12:15]
	v_mfma_f32_16x16x32_bf16 v[8:11], v[174:177], v[222:225], v[8:11]
	v_mfma_f32_16x16x32_bf16 v[60:63], v[148:151], v[202:205], v[60:63]
	v_mfma_f32_16x16x32_bf16 v[56:59], v[178:181], v[202:205], v[56:59]
	v_mfma_f32_16x16x32_bf16 v[44:47], v[148:151], v[210:213], v[44:47]
	v_mfma_f32_16x16x32_bf16 v[40:43], v[178:181], v[210:213], v[40:43]
	v_mfma_f32_16x16x32_bf16 v[28:31], v[148:151], v[218:221], v[28:31]
	v_mfma_f32_16x16x32_bf16 v[24:27], v[178:181], v[218:221], v[24:27]
	v_mfma_f32_16x16x32_bf16 v[12:15], v[148:151], v[226:229], v[12:15]
	v_mfma_f32_16x16x32_bf16 v[8:11], v[178:181], v[226:229], v[8:11]
	v_mfma_f32_16x16x32_bf16 v[52:55], v[182:185], v[198:201], v[52:55]
	v_mfma_f32_16x16x32_bf16 v[48:51], v[190:193], v[198:201], v[48:51]
	v_mfma_f32_16x16x32_bf16 v[36:39], v[182:185], v[206:209], v[36:39]
	v_mfma_f32_16x16x32_bf16 v[32:35], v[190:193], v[206:209], v[32:35]
	v_mfma_f32_16x16x32_bf16 v[20:23], v[182:185], v[214:217], v[20:23]
	v_mfma_f32_16x16x32_bf16 v[16:19], v[190:193], v[214:217], v[16:19]
	v_mfma_f32_16x16x32_bf16 v[4:7], v[182:185], v[222:225], v[4:7]
	v_mfma_f32_16x16x32_bf16 v[0:3], v[190:193], v[222:225], v[0:3]
	v_mfma_f32_16x16x32_bf16 v[52:55], v[186:189], v[202:205], v[52:55]
	v_mfma_f32_16x16x32_bf16 v[48:51], v[194:197], v[202:205], v[48:51]
	v_mfma_f32_16x16x32_bf16 v[36:39], v[186:189], v[210:213], v[36:39]
	v_mfma_f32_16x16x32_bf16 v[32:35], v[194:197], v[210:213], v[32:35]
	v_mfma_f32_16x16x32_bf16 v[20:23], v[186:189], v[218:221], v[20:23]
	v_mfma_f32_16x16x32_bf16 v[16:19], v[194:197], v[218:221], v[16:19]
	v_mfma_f32_16x16x32_bf16 v[4:7], v[186:189], v[226:229], v[4:7]
	v_mfma_f32_16x16x32_bf16 v[0:3], v[194:197], v[226:229], v[0:3]
	s_barrier
	s_setprio 1
	s_add_u32 s63, s63, 0x100
	s_addc_u32 s64, s64, 0
	s_add_u32 s6, s6, 0x100
	s_addc_u32 s7, s7, 0
	s_cmp_ge_i32 s36, s55
	s_mov_b32 s34, s36
	s_cbranch_scc0 .LBB0_1911
.LBB0_1912:
	s_setprio 0
	s_and_b64 vcc, exec, s[24:25]
	s_cbranch_vccz .LBB0_1914
	s_barrier
